# MLA loop variant D: one workgroup barrier per two key tiles (5-slot K / 4-slot V LDS rings, continuous LDS fragment stream), 20x unrolled
# speedup vs baseline: 1.0219x; 1.0021x over previous
; #define LOADK(t) do { const int kp_ = TILE_KPOS(t); kreg = *(const u32x4*)((const char*)P.K + (size_t)(koff + (unsigned)(kp_ * KPITCH * 2))); if (VAR == 0 && tid < 256) pereg = *(const u32x4*)((const char*)P.KPE + (size_t)(peoff + (unsigned)(kp_ * 64))); } while (0)
; #define LOADV(t) do { const int kp_ = TILE_KPOS(t); vreg = *(const u32x4*)((const char*)P.VT + (size_t)(voff + (unsigned)(kp_ * 2))); } while (0)
; #define STOREK(buf) do { LAS unsigned char* kb_ = lds + (buf) * ABUF; *(LAS u32x4*)(kb_ + (tid >> 3) * KP + (tid & 7) * 16) = kreg; \
;         if (VAR == 0 && tid < 256) *(LAS u32x4*)(kb_ + (tid >> 2) * KP + 128 + (tid & 3) * 16) = pereg; } while (0)
; #define STOREV(buf) do { *(LAS u32x4*)(lds + (buf) * ABUF + KT_BYTES + (tid >> 3) * VP + (tid & 7) * 16) = vreg; } while (0)
; template <int VAR>
; __device__ __forceinline__ void attn_phase(LAS unsigned char* lds, const AttnP P, int vcu, int G, int wave_s) {
;     ...
;         LOADK(0); LOADV(0); STOREK(0); STOREV(0);
;         if (nt > 1) { LOADK(1); STOREK(1); }
;         __syncthreads();
;         f32x16 pc0, pc1; const f32x16 zero16 = {};
;         QK_TILE(pc0, pc1, 0, zero16);
;         float mref = rowmax32(pc0, pc1), lrun = 0.f;
;         if (VAR == 1) { const float sk = P.sink[hq] * LOG2E; mref = __builtin_fmaxf(mref, sk); lrun = (hi == 0) ? __builtin_amdgcn_exp2f(sk - mref) : 0.f; }
;         f32x16 negm = {};
;         if (USE_NEGM) {
; #pragma unroll
;             for (int r = 0; r < 16; ++r) { pc0[r] -= mref; pc1[r] -= mref; negm[r] = -mref; }
;         }
;         float rmc = 0.f;
;         bool need_c = true;
;         __syncthreads();
;         for (int t = 0; t < nt; ++t) {
;             const bool hn = (t + 1 < nt);
;             if (hn) { const int t2 = (t + 2 < nt) ? t + 2 : nt - 1; LOADK(t2); LOADV(t + 1); }
.LBB0_1173:
	s_or_b64 exec, exec, s[0:1]
	s_waitcnt vmcnt(0)
	ds_write_b128 v172, v[2:5] offset:22528
	s_and_saveexec_b64 s[0:1], s[2:3]
	ds_write_b128 v176, v[138:141] offset:22656
	s_or_b64 exec, exec, s[0:1]
	s_waitcnt lgkmcnt(0)
	s_barrier
	s_movk_i32 s0, 0x4200
	v_mul_lo_u32 v168, v1, s0
	v_add_u32_e32 v168, v168, v171
	v_add_u32_e32 v168, 0xffffff80, v168
	s_add_i32 s19, s10, 2
	s_cmp_ge_i32 s19, s9
	s_cselect_b32 s1, s9, 0
	s_sub_i32 s19, s19, s1
	s_cmp_ge_i32 s19, s9
	s_cselect_b32 s1, s9, 0
	s_sub_i32 s19, s19, s1
	s_add_i32 s13, s10, 1
	s_cmp_ge_i32 s13, s9
	s_cselect_b32 s1, s9, 0
	s_sub_i32 s13, s13, s1
	s_cmp_ge_i32 s13, s9
	s_cselect_b32 s1, s9, 0
	s_sub_i32 s13, s13, s1
	s_and_saveexec_b64 s[0:1], s[2:3]
	s_cbranch_execz .Lmla_early0
	v_lshl_add_u32 v222, s19, 12, v179
	global_load_dwordx4 v[138:141], v222, s[62:63]
.Lmla_early0:
	s_or_b64 exec, exec, s[0:1]
	v_lshl_add_u32 v222, s19, 17, v178
	global_load_dwordx4 v[146:149], v222, s[52:53]
	v_lshl_add_u32 v222, s13, 7, v168
	global_load_dwordx4 v[142:145], v222, s[56:57]
	s_add_i32 s19, s10, 3
	s_cmp_ge_i32 s19, s9
	s_cselect_b32 s1, s9, 0
	s_sub_i32 s19, s19, s1
	s_cmp_ge_i32 s19, s9
	s_cselect_b32 s1, s9, 0
	s_sub_i32 s19, s19, s1
	s_and_saveexec_b64 s[0:1], s[2:3]
	s_cbranch_execz .Lmla_early1
	v_lshl_add_u32 v222, s19, 12, v179
	global_load_dwordx4 v[160:163], v222, s[62:63]
.Lmla_early1:
	s_or_b64 exec, exec, s[0:1]
	v_lshl_add_u32 v222, s19, 17, v178
	global_load_dwordx4 v[150:153], v222, s[52:53]
	ds_read_b128 v[2:5], v174
	ds_read_b128 v[6:9], v174 offset:32
	s_waitcnt lgkmcnt(1)
	v_mfma_f32_32x32x16_bf16 v[34:49], v[2:5], v[114:117], 0
	ds_read_b128 v[2:5], v174 offset:6656
	ds_read_b128 v[10:13], v174 offset:6688
	v_readlane_b32 s36, v255, 18
	s_mov_b32 s0, s36
	v_readlane_b32 s37, v255, 19
	v_readlane_b32 s38, v255, 20
	v_readlane_b32 s39, v255, 21
	v_readlane_b32 s40, v255, 22
	s_waitcnt lgkmcnt(2)
	v_mfma_f32_32x32x16_bf16 v[34:49], v[6:9], v[118:121], v[34:49]
	v_readlane_b32 s41, v255, 23
	v_readlane_b32 s42, v255, 24
	v_readlane_b32 s43, v255, 25
	v_readlane_b32 s44, v255, 26
	v_readlane_b32 s45, v255, 27
	v_readlane_b32 s46, v255, 28
	v_readlane_b32 s47, v255, 29
	s_waitcnt lgkmcnt(1)
	v_mfma_f32_32x32x16_bf16 v[18:33], v[2:5], v[114:117], 0
	ds_read_b128 v[2:5], v174 offset:64
	ds_read_b128 v[6:9], v174 offset:96
	v_readlane_b32 s48, v255, 30
	v_readlane_b32 s49, v255, 31
	v_readlane_b32 s50, v255, 32
	v_readlane_b32 s51, v255, 33
	v_writelane_b32 v255, s0, 18
	s_mov_b32 s37, s36
	s_waitcnt lgkmcnt(1)
	v_mfma_f32_32x32x16_bf16 v[34:49], v[2:5], v[122:125], v[34:49]
	v_writelane_b32 v255, s1, 19
	v_writelane_b32 v255, s2, 20
	v_writelane_b32 v255, s3, 21
	v_writelane_b32 v255, s4, 22
	v_writelane_b32 v255, s5, 23
	v_writelane_b32 v255, s6, 24
	v_writelane_b32 v255, s7, 25
	v_mfma_f32_32x32x16_bf16 v[18:33], v[10:13], v[118:121], v[18:33]
	ds_read_b128 v[2:5], v174 offset:6720
	ds_read_b128 v[10:13], v174 offset:6752
	v_writelane_b32 v255, s8, 26
	v_writelane_b32 v255, s9, 27
	v_writelane_b32 v255, s10, 28
	v_writelane_b32 v255, s11, 29
	v_writelane_b32 v255, s12, 30
	v_writelane_b32 v255, s13, 31
	s_waitcnt lgkmcnt(2)
	v_mfma_f32_32x32x16_bf16 v[34:49], v[6:9], v[126:129], v[34:49]
	v_writelane_b32 v255, s14, 32
	s_mov_b32 s38, s36
	s_mov_b32 s39, s36
	s_mov_b32 s40, s36
	s_mov_b32 s41, s36
	s_mov_b32 s42, s36
	s_mov_b32 s43, s36
	s_waitcnt lgkmcnt(1)
	v_mfma_f32_32x32x16_bf16 v[18:33], v[2:5], v[122:125], v[18:33]
	ds_read_b128 v[2:5], v174 offset:128
	ds_read_b128 v[6:9], v174 offset:160
	ds_read_b128 v[50:53], v174 offset:6816
	s_mov_b32 s44, s36
	s_mov_b32 s45, s36
	s_mov_b32 s46, s36
	s_mov_b32 s47, s36
	s_mov_b32 s48, s36
	s_waitcnt lgkmcnt(2)
	v_mfma_f32_32x32x16_bf16 v[34:49], v[2:5], v[130:133], v[34:49]
	ds_read_b128 v[2:5], v174 offset:6784
	s_mov_b32 s49, s36
	s_mov_b32 s50, s36
	s_mov_b32 s51, s36
	v_writelane_b32 v255, s15, 33
	s_movk_i32 s0, 0x4200
	v_mul_lo_u32 v1, v1, s0
	v_mfma_f32_32x32x16_bf16 v[18:33], v[10:13], v[126:129], v[18:33]
	v_or_b32_e32 v1, v171, v1
	s_add_i32 s12, s9, -1
	v_lshl_add_u32 v181, s10, 7, v1
	v_mov_b32_e32 v1, 0
	s_mov_b32 s11, 1
	v_mov_b32_e32 v82, 0
	s_waitcnt lgkmcnt(0)
	v_mfma_f32_32x32x16_bf16 v[18:33], v[2:5], v[130:133], v[18:33]
	s_barrier
; #define LOADK(t) do { const int kp_ = TILE_KPOS(t); kreg = *(const u32x4*)((const char*)P.K + (size_t)(koff + (unsigned)(kp_ * KPITCH * 2))); if (VAR == 0 && tid < 256) pereg = *(const u32x4*)((const char*)P.KPE + (size_t)(peoff + (unsigned)(kp_ * 64))); } while (0)
; #define LOADV(t) do { const int kp_ = TILE_KPOS(t); vreg = *(const u32x4*)((const char*)P.VT + (size_t)(voff + (unsigned)(kp_ * 2))); } while (0)
; template <int VAR>
; __device__ __forceinline__ void attn_phase(LAS unsigned char* lds, const AttnP P, int vcu, int G, int wave_s) {
;     ...
;         float mref = rowmax32(pc0, pc1), lrun = 0.f;
;         if (VAR == 1) { const float sk = P.sink[hq] * LOG2E; mref = __builtin_fmaxf(mref, sk); lrun = (hi == 0) ? __builtin_amdgcn_exp2f(sk - mref) : 0.f; }
;         f32x16 negm = {};
;         if (USE_NEGM) {
; #pragma unroll
;             for (int r = 0; r < 16; ++r) { pc0[r] -= mref; pc1[r] -= mref; negm[r] = -mref; }
;         }
;         float rmc = 0.f;
;         bool need_c = true;
;         __syncthreads();
;         for (int t = 0; t < nt; ++t) {
;             const bool hn = (t + 1 < nt);
;             if (hn) { const int t2 = (t + 2 < nt) ? t + 2 : nt - 1; LOADK(t2); LOADV(t + 1); }
	v_mfma_f32_32x32x16_bf16 v[34:49], v[6:9], v[134:137], v[34:49]
	v_mov_b64_e32 v[2:3], s[36:37]
	v_mov_b64_e32 v[16:17], s[50:51]
	v_mov_b64_e32 v[4:5], s[38:39]
	v_mov_b64_e32 v[6:7], s[40:41]
	v_mov_b64_e32 v[8:9], s[42:43]
	v_mov_b64_e32 v[10:11], s[44:45]
	v_mov_b64_e32 v[12:13], s[46:47]
	v_mfma_f32_32x32x16_bf16 v[18:33], v[50:53], v[134:137], v[18:33]
	s_nop 3
	v_max_f32_e32 v54, v35, v35
	v_max_f32_e32 v55, v34, v34
	v_max_f32_e32 v54, v55, v54
	v_mov_b64_e32 v[14:15], s[48:49]
	s_nop 3
	v_max3_f32 v50, v36, v37, v19
	v_max3_f32 v51, v54, v18, v20
	v_max3_f32 v51, v51, v21, v38
	v_max3_f32 v50, v50, v40, v41
	v_max3_f32 v51, v51, v39, v22
	v_max3_f32 v50, v50, v24, v25
	v_max3_f32 v51, v51, v23, v42
	v_max3_f32 v50, v50, v44, v45
	v_max3_f32 v51, v51, v43, v26
	v_max3_f32 v50, v50, v28, v29
	v_max3_f32 v51, v51, v27, v46
	v_max3_f32 v50, v50, v48, v49
	v_max3_f32 v51, v51, v47, v30
	v_max3_f32 v50, v50, v32, v33
	v_max3_f32 v50, v51, v31, v50
	v_mov_b32_e32 v51, v50
	s_nop 1
	v_permlane32_swap_b32_e32 v50, v51
	v_max_f32_e32 v51, v51, v51
	v_max_f32_e32 v50, v50, v50
	v_max_f32_e32 v180, v50, v51
	v_xor_b32_e32 v66, 0x80000000, v180
	v_sub_f32_e32 v65, v33, v180
	v_sub_f32_e32 v64, v32, v180
	v_sub_f32_e32 v63, v31, v180
	v_sub_f32_e32 v62, v30, v180
	v_sub_f32_e32 v61, v29, v180
	v_sub_f32_e32 v60, v28, v180
	v_sub_f32_e32 v59, v27, v180
	v_sub_f32_e32 v58, v26, v180
	v_sub_f32_e32 v57, v25, v180
	v_sub_f32_e32 v56, v24, v180
	v_sub_f32_e32 v55, v23, v180
	v_sub_f32_e32 v54, v22, v180
	v_sub_f32_e32 v53, v21, v180
	v_sub_f32_e32 v52, v20, v180
	v_sub_f32_e32 v51, v19, v180
	v_sub_f32_e32 v50, v18, v180
	v_mov_b64_e32 v[32:33], v[16:17]
	v_sub_f32_e32 v49, v49, v180
	v_sub_f32_e32 v48, v48, v180
	v_sub_f32_e32 v47, v47, v180
	v_sub_f32_e32 v46, v46, v180
	v_sub_f32_e32 v45, v45, v180
	v_sub_f32_e32 v44, v44, v180
	v_sub_f32_e32 v43, v43, v180
	v_sub_f32_e32 v42, v42, v180
	v_sub_f32_e32 v41, v41, v180
	v_sub_f32_e32 v40, v40, v180
	v_sub_f32_e32 v39, v39, v180
	v_sub_f32_e32 v38, v38, v180
	v_sub_f32_e32 v37, v37, v180
	v_sub_f32_e32 v36, v36, v180
	v_sub_f32_e32 v35, v35, v180
	v_sub_f32_e32 v34, v34, v180
	v_mov_b64_e32 v[30:31], v[14:15]
	v_mov_b64_e32 v[28:29], v[12:13]
	v_mov_b64_e32 v[26:27], v[10:11]
	v_mov_b64_e32 v[24:25], v[8:9]
	v_mov_b64_e32 v[22:23], v[6:7]
	v_mov_b64_e32 v[20:21], v[4:5]
	v_mov_b64_e32 v[18:19], v[2:3]
	v_mov_b32_e32 v67, v66
	v_mov_b32_e32 v68, v66
	v_mov_b32_e32 v69, v66
	v_mov_b32_e32 v70, v66
	v_mov_b32_e32 v71, v66
	v_mov_b32_e32 v72, v66
	v_mov_b32_e32 v73, v66
	v_mov_b32_e32 v74, v66
	v_mov_b32_e32 v75, v66
	v_mov_b32_e32 v76, v66
	v_mov_b32_e32 v77, v66
	v_mov_b32_e32 v78, v66
	v_mov_b32_e32 v79, v66
	v_mov_b32_e32 v80, v66
	v_mov_b32_e32 v81, v66
	v_add_u32_e32 v228, v166, v165
	v_mov_b32_e32 v167, v82
	v_add_u32_e32 v229, 0xb000, v174
	v_add_u32_e32 v181, 0xb000, v228
	s_waitcnt vmcnt(0)
	s_and_saveexec_b64 s[0:1], s[2:3]
	ds_write_b128 v176, v[138:141] offset:45184
	ds_write_b128 v176, v[160:163] offset:58496
	s_or_b64 exec, exec, s[0:1]
	ds_write_b128 v172, v[146:149] offset:45056
	ds_write_b128 v173, v[142:145] offset:35840
	ds_write_b128 v172, v[150:153] offset:58368
	s_add_i32 s19, s10, 4
	s_cmp_ge_i32 s19, s9
	s_cselect_b32 s1, s9, 0
	s_sub_i32 s19, s19, s1
	s_cmp_ge_i32 s19, s9
	s_cselect_b32 s1, s9, 0
	s_sub_i32 s19, s19, s1
	s_add_i32 s13, s10, 2
	s_cmp_ge_i32 s13, s9
	s_cselect_b32 s1, s9, 0
	s_sub_i32 s13, s13, s1
	s_cmp_ge_i32 s13, s9
	s_cselect_b32 s1, s9, 0
	s_sub_i32 s13, s13, s1
	s_and_saveexec_b64 s[0:1], s[2:3]
	s_cbranch_execz .Lmla_pre0
	v_lshl_add_u32 v222, s19, 12, v179
	global_load_dwordx4 v[138:141], v222, s[62:63]
.Lmla_pre0:
	s_or_b64 exec, exec, s[0:1]
	v_lshl_add_u32 v222, s19, 17, v178
	global_load_dwordx4 v[146:149], v222, s[52:53]
	v_lshl_add_u32 v222, s13, 7, v168
	global_load_dwordx4 v[142:145], v222, s[56:57]
	s_add_i32 s19, s10, 5
	s_cmp_ge_i32 s19, s9
	s_cselect_b32 s1, s9, 0
	s_sub_i32 s19, s19, s1
	s_cmp_ge_i32 s19, s9
	s_cselect_b32 s1, s9, 0
	s_sub_i32 s19, s19, s1
	s_add_i32 s13, s10, 3
	s_cmp_ge_i32 s13, s9
	s_cselect_b32 s1, s9, 0
	s_sub_i32 s13, s13, s1
	s_cmp_ge_i32 s13, s9
	s_cselect_b32 s1, s9, 0
	s_sub_i32 s13, s13, s1
	s_and_saveexec_b64 s[0:1], s[2:3]
	s_cbranch_execz .Lmla_pre1
	v_lshl_add_u32 v222, s19, 12, v179
	global_load_dwordx4 v[160:163], v222, s[62:63]
.Lmla_pre1:
	s_or_b64 exec, exec, s[0:1]
	v_lshl_add_u32 v222, s19, 17, v178
	global_load_dwordx4 v[150:153], v222, s[52:53]
	v_lshl_add_u32 v222, s13, 7, v168
	global_load_dwordx4 v[202:205], v222, s[56:57]
	s_add_i32 s20, s10, 4
	s_cmp_ge_i32 s20, s9
	s_cselect_b32 s1, s9, 0
	s_sub_i32 s20, s20, s1
	s_cmp_ge_i32 s20, s9
	s_cselect_b32 s1, s9, 0
	s_sub_i32 s20, s20, s1
	s_and_b64 vcc, exec, s[2:3]
	s_cbranch_vccnz .Lmla_noprio
	s_setprio 1

; template <int VAR>
; __device__ __forceinline__ void attn_phase(LAS unsigned char* lds, const AttnP P, int vcu, int G, int wave_s) {
;     ...
;                 if (ND0 == 6) {
;                     KR1(0); KR1(1); KR1(2); KR1(3); SB();
;                     QK1(0, negm); EX2(pc0, 0, w0.x); KR1(4); SB();
;                     QK1(1, negm); EX2(pc0, 2, w0.y); KR1(5); SB();
;                     QK1(2, pn0); EX2(pc0, 4, w0.z); KR1(6); SB();
;                     QK1(3, pn1); EX2(pc0, 6, w0.w); KR1(7); SB();
;                     QK1(4, pn0); EX2(pc0, 8, w1.x); KR1(8); SB();
;                     QK1(5, pn1); EX2(pc0, 10, w1.y); KR1(9); SB();
;                     QK1(6, pn0); EX2(pc0, 12, w1.z); KR1(10); SB();
;                     QK1(7, pn1); EX2(pc0, 14, w1.w); KR1(11); SB();
;                     QK1(8, pn0); EX2(pc1, 0, w2.x); VR1(0); SB();
;                     QK1(9, pn1); EX2(pc1, 2, w2.y); VR1(1); SB();
;                     QK1(10, pn0); EX2(pc1, 4, w2.z); VR1(2); SB();
;                     QK1(11, pn1); EX2(pc1, 6, w2.w); VR1(3); SB();
;                 } else {
;                     KR1(0); KR1(1); KR1(2); KR1(3); SB();
;                     QK1(0, negm); EX2(pc0, 0, w0.x); EX2(pc0, 2, w0.y); KR1(4); SB();
;                     QK1(1, negm); EX2(pc0, 4, w0.z); EX2(pc0, 6, w0.w); KR1(5); SB();
;                     QK1(2, pn0); EX2(pc0, 8, w1.x); EX2(pc0, 10, w1.y); KR1(6); SB();
;                     QK1(3, pn1); EX2(pc0, 12, w1.z); EX2(pc0, 14, w1.w); KR1(7); SB();
;                     QK1(4, pn0); EX2(pc1, 0, w2.x); VR1(0); SB();
;                     QK1(5, pn1); EX2(pc1, 2, w2.y); VR1(1); SB();
;                     QK1(6, pn0); EX2(pc1, 4, w2.z); VR1(2); SB();
;                     QK1(7, pn1); EX2(pc1, 6, w2.w); VR1(3); SB();
;                 }
;                 PV1(0, w0); EX2(pc1, 8, w3.x); VR1(4); SB();
;                 PV1(1, w0); EX2(pc1, 10, w3.y); VR1(5); SB();
;                 PV1(2, w1); EX2(pc1, 12, w3.z); VR1(6); SB();
;                 PV1(3, w1); EX2(pc1, 14, w3.w); VR1(7); SB();
;                 lrun += sacc;
;                 PV1(4, w2); MASK_TILE(pn0, pn1, t + 1); SB();
;                 PV1(5, w2); SB();
;                 PV1(6, w3); SB();
;                 PV1(7, w3); rmn = rowmax32(pn0, pn1); if (!USE_NEGM) rmn -= mref; SB();
;     ...
;             if (hn) { STOREK(t & 1); STOREV((t + 1) & 1); }
;             __syncthreads();
.Lmla_p0_go:
	v_exp_f32_e32 v222, v34
	v_exp_f32_e32 v223, v35
	v_add_f32_e32 v164, 0, v222
	v_cvt_pk_bf16_f32 v206, v222, v223
	v_add_f32_e32 v164, v223, v164
	v_exp_f32_e32 v224, v36
	v_exp_f32_e32 v225, v37
	v_add_f32_e32 v164, v224, v164
	v_cvt_pk_bf16_f32 v207, v224, v225
	v_add_f32_e32 v164, v225, v164
	s_waitcnt lgkmcnt(3)
	v_mfma_f32_32x32x16_bf16 v[82:97], v[182:185], v[114:117], v[66:81]
	ds_read_b128 v[198:201], v174 offset:22592
	v_exp_f32_e32 v222, v38
	v_exp_f32_e32 v223, v39
	v_add_f32_e32 v164, v222, v164
	v_cvt_pk_bf16_f32 v208, v222, v223
	v_add_f32_e32 v164, v223, v164
	s_waitcnt lgkmcnt(3)
	v_mfma_f32_32x32x16_bf16 v[98:113], v[186:189], v[114:117], v[66:81]
	ds_read_b128 v[182:185], v174 offset:29248
	v_exp_f32_e32 v224, v40
	v_exp_f32_e32 v225, v41
	v_add_f32_e32 v164, v224, v164
	v_cvt_pk_bf16_f32 v209, v224, v225
	v_add_f32_e32 v164, v225, v164
	s_waitcnt lgkmcnt(3)
	v_mfma_f32_32x32x16_bf16 v[82:97], v[190:193], v[118:121], v[82:97]
	ds_read_b128 v[186:189], v174 offset:22624
	v_exp_f32_e32 v222, v42
	v_exp_f32_e32 v223, v43
	v_add_f32_e32 v164, v222, v164
	v_cvt_pk_bf16_f32 v210, v222, v223
	v_add_f32_e32 v164, v223, v164
	s_waitcnt lgkmcnt(3)
	v_mfma_f32_32x32x16_bf16 v[98:113], v[194:197], v[118:121], v[98:113]
	ds_read_b128 v[190:193], v174 offset:29280
	v_exp_f32_e32 v224, v44
	v_exp_f32_e32 v225, v45
	v_add_f32_e32 v164, v224, v164
	v_cvt_pk_bf16_f32 v211, v224, v225
	v_add_f32_e32 v164, v225, v164
	s_waitcnt lgkmcnt(3)
	v_mfma_f32_32x32x16_bf16 v[82:97], v[198:201], v[122:125], v[82:97]
	ds_read_b128 v[194:197], v174 offset:22656
	v_exp_f32_e32 v222, v46
	v_exp_f32_e32 v223, v47
	v_add_f32_e32 v164, v222, v164
	v_cvt_pk_bf16_f32 v212, v222, v223
	v_add_f32_e32 v164, v223, v164
	s_waitcnt lgkmcnt(3)
	v_mfma_f32_32x32x16_bf16 v[98:113], v[182:185], v[122:125], v[98:113]
	ds_read_b128 v[198:201], v174 offset:29312
	v_exp_f32_e32 v224, v48
	v_exp_f32_e32 v225, v49
	v_add_f32_e32 v164, v224, v164
	v_cvt_pk_bf16_f32 v213, v224, v225
	v_add_f32_e32 v164, v225, v164
	s_waitcnt lgkmcnt(3)
	v_mfma_f32_32x32x16_bf16 v[82:97], v[186:189], v[126:129], v[82:97]
	ds_read_b128 v[182:185], v174 offset:22688
	v_exp_f32_e32 v222, v50
	v_exp_f32_e32 v223, v51
	v_add_f32_e32 v164, v222, v164
	v_cvt_pk_bf16_f32 v214, v222, v223
	v_add_f32_e32 v164, v223, v164
	s_waitcnt lgkmcnt(3)
	v_mfma_f32_32x32x16_bf16 v[98:113], v[190:193], v[126:129], v[98:113]
	ds_read_b128 v[186:189], v174 offset:29344
	v_exp_f32_e32 v224, v52
	v_exp_f32_e32 v225, v53
	v_add_f32_e32 v164, v224, v164
	v_cvt_pk_bf16_f32 v215, v224, v225
	v_add_f32_e32 v164, v225, v164
	s_waitcnt lgkmcnt(3)
	v_mfma_f32_32x32x16_bf16 v[82:97], v[194:197], v[130:133], v[82:97]
	ds_read_b128 v[190:193], v228 offset:13312
	v_exp_f32_e32 v222, v54
	v_exp_f32_e32 v223, v55
	v_add_f32_e32 v164, v222, v164
	v_cvt_pk_bf16_f32 v216, v222, v223
	v_add_f32_e32 v164, v223, v164
	s_waitcnt lgkmcnt(3)
	v_mfma_f32_32x32x16_bf16 v[98:113], v[198:201], v[130:133], v[98:113]
	ds_read_b128 v[194:197], v228 offset:17920
	v_exp_f32_e32 v224, v56
	v_exp_f32_e32 v225, v57
	v_add_f32_e32 v164, v224, v164
	v_cvt_pk_bf16_f32 v217, v224, v225
	v_add_f32_e32 v164, v225, v164
	s_waitcnt lgkmcnt(3)
	v_mfma_f32_32x32x16_bf16 v[82:97], v[182:185], v[134:137], v[82:97]
	ds_read_b128 v[198:201], v228 offset:13344
	v_exp_f32_e32 v222, v58
	v_exp_f32_e32 v223, v59
	v_add_f32_e32 v164, v222, v164
	v_cvt_pk_bf16_f32 v218, v222, v223
	v_add_f32_e32 v164, v223, v164
	s_waitcnt lgkmcnt(3)
	v_mfma_f32_32x32x16_bf16 v[98:113], v[186:189], v[134:137], v[98:113]
	ds_read_b128 v[182:185], v228 offset:17952
	v_exp_f32_e32 v224, v60
	v_exp_f32_e32 v225, v61
	v_add_f32_e32 v164, v224, v164
	v_cvt_pk_bf16_f32 v219, v224, v225
	v_add_f32_e32 v164, v225, v164
	s_waitcnt lgkmcnt(3)
	v_mfma_f32_32x32x16_bf16 v[2:17], v[190:193], v[206:209], v[2:17]
	ds_read_b128 v[186:189], v228 offset:13376
	v_exp_f32_e32 v222, v62
	v_exp_f32_e32 v223, v63
	v_add_f32_e32 v164, v222, v164
	v_cvt_pk_bf16_f32 v220, v222, v223
	v_add_f32_e32 v164, v223, v164
	s_waitcnt lgkmcnt(3)
	v_mfma_f32_32x32x16_bf16 v[18:33], v[194:197], v[206:209], v[18:33]
	ds_read_b128 v[190:193], v228 offset:17984
	v_exp_f32_e32 v224, v64
	v_exp_f32_e32 v225, v65
	v_add_f32_e32 v164, v224, v164
	v_cvt_pk_bf16_f32 v221, v224, v225
	v_add_f32_e32 v164, v225, v164
	s_mov_b32 s13, s20
	s_mov_b32 s20, s19
	s_add_i32 s19, s19, 1
	s_cmp_eq_u32 s19, s9
	s_cselect_b32 s19, 0, s19
	s_waitcnt lgkmcnt(3)
	v_mfma_f32_32x32x16_bf16 v[2:17], v[198:201], v[210:213], v[2:17]
	ds_read_b128 v[194:197], v228 offset:13408
	v_max3_f32 v224, v82, v83, v84
	v_max3_f32 v225, v98, v99, v100
	v_max3_f32 v224, v224, v85, v86
	v_max3_f32 v225, v225, v101, v102
	s_waitcnt vmcnt(2)
	v_add_u32_e32 v222, 0xb000, v172
	ds_write_b128 v222, v[146:149] offset:26624
	v_lshl_add_u32 v222, s19, 17, v178
	global_load_dwordx4 v[146:149], v222, s[52:53]
	s_waitcnt lgkmcnt(4)
	v_mfma_f32_32x32x16_bf16 v[18:33], v[182:185], v[210:213], v[18:33]
	ds_read_b128 v[198:201], v228 offset:18016
	v_max3_f32 v224, v224, v87, v88
	v_max3_f32 v225, v225, v103, v104
	v_max3_f32 v224, v224, v89, v90
	v_max3_f32 v225, v225, v105, v106
	s_and_b64 vcc, exec, s[2:3]
	s_cbranch_vccz .Lmla_p0_nope
	v_add_u32_e32 v222, 0xb000, v176
	ds_write_b128 v222, v[138:141] offset:26752
	v_lshl_add_u32 v222, s19, 12, v179
	global_load_dwordx4 v[138:141], v222, s[62:63]
.Lmla_p0_nope:
	s_waitcnt lgkmcnt(4)
	v_mfma_f32_32x32x16_bf16 v[2:17], v[186:189], v[214:217], v[2:17]
	ds_read_b128 v[182:185], v174 offset:45056
	v_max3_f32 v224, v224, v91, v92
	v_max3_f32 v225, v225, v107, v108
	v_max3_f32 v224, v224, v93, v94
	v_max3_f32 v225, v225, v109, v110
	v_add_u32_e32 v222, 0xb000, v173
	ds_write_b128 v222, v[142:145] offset:39936
	v_lshl_add_u32 v222, s13, 7, v168
	global_load_dwordx4 v[142:145], v222, s[56:57]
	s_waitcnt lgkmcnt(5)
	v_mfma_f32_32x32x16_bf16 v[18:33], v[190:193], v[214:217], v[18:33]
	ds_read_b128 v[186:189], v174 offset:51712
	v_max3_f32 v224, v224, v95, v96
	v_max3_f32 v225, v225, v111, v112
	v_max3_f32 v224, v224, v97, v113
	v_max_f32_e32 v224, v224, v225
	s_waitcnt lgkmcnt(5)
	v_mfma_f32_32x32x16_bf16 v[2:17], v[194:197], v[218:221], v[2:17]
	ds_read_b128 v[190:193], v174 offset:45088
	v_mov_b32_e32 v225, v224
	v_add_f32_e32 v1, v1, v164
	s_add_i32 s11, s11, 1
	v_permlane32_swap_b32_e32 v224, v225
	s_cmp_eq_u32 s9, s11
	v_max_f32_e32 v167, v224, v225
	s_waitcnt lgkmcnt(4)
	v_mfma_f32_32x32x16_bf16 v[18:33], v[198:201], v[218:221], v[18:33]
	ds_read_b128 v[194:197], v174 offset:51744
	v_cmp_lt_f32_e32 vcc, s66, v167
	s_cbranch_scc1 .Lmla_exit_p0

; template <int VAR>
; __device__ __forceinline__ void attn_phase(LAS unsigned char* lds, const AttnP P, int vcu, int G, int wave_s) {
;     ...
;                 if (ND0 == 6) {
;                     KR1(0); KR1(1); KR1(2); KR1(3); SB();
;                     QK1(0, negm); EX2(pc0, 0, w0.x); KR1(4); SB();
;                     QK1(1, negm); EX2(pc0, 2, w0.y); KR1(5); SB();
;                     QK1(2, pn0); EX2(pc0, 4, w0.z); KR1(6); SB();
;                     QK1(3, pn1); EX2(pc0, 6, w0.w); KR1(7); SB();
;                     QK1(4, pn0); EX2(pc0, 8, w1.x); KR1(8); SB();
;                     QK1(5, pn1); EX2(pc0, 10, w1.y); KR1(9); SB();
;                     QK1(6, pn0); EX2(pc0, 12, w1.z); KR1(10); SB();
;                     QK1(7, pn1); EX2(pc0, 14, w1.w); KR1(11); SB();
;                     QK1(8, pn0); EX2(pc1, 0, w2.x); VR1(0); SB();
;                     QK1(9, pn1); EX2(pc1, 2, w2.y); VR1(1); SB();
;                     QK1(10, pn0); EX2(pc1, 4, w2.z); VR1(2); SB();
;                     QK1(11, pn1); EX2(pc1, 6, w2.w); VR1(3); SB();
;                 } else {
;                     KR1(0); KR1(1); KR1(2); KR1(3); SB();
;                     QK1(0, negm); EX2(pc0, 0, w0.x); EX2(pc0, 2, w0.y); KR1(4); SB();
;                     QK1(1, negm); EX2(pc0, 4, w0.z); EX2(pc0, 6, w0.w); KR1(5); SB();
;                     QK1(2, pn0); EX2(pc0, 8, w1.x); EX2(pc0, 10, w1.y); KR1(6); SB();
;                     QK1(3, pn1); EX2(pc0, 12, w1.z); EX2(pc0, 14, w1.w); KR1(7); SB();
;                     QK1(4, pn0); EX2(pc1, 0, w2.x); VR1(0); SB();
;                     QK1(5, pn1); EX2(pc1, 2, w2.y); VR1(1); SB();
;                     QK1(6, pn0); EX2(pc1, 4, w2.z); VR1(2); SB();
;                     QK1(7, pn1); EX2(pc1, 6, w2.w); VR1(3); SB();
;                 }
;                 PV1(0, w0); EX2(pc1, 8, w3.x); VR1(4); SB();
;                 PV1(1, w0); EX2(pc1, 10, w3.y); VR1(5); SB();
;                 PV1(2, w1); EX2(pc1, 12, w3.z); VR1(6); SB();
;                 PV1(3, w1); EX2(pc1, 14, w3.w); VR1(7); SB();
;                 lrun += sacc;
;                 PV1(4, w2); MASK_TILE(pn0, pn1, t + 1); SB();
;                 PV1(5, w2); SB();
;                 PV1(6, w3); SB();
;                 PV1(7, w3); rmn = rowmax32(pn0, pn1); if (!USE_NEGM) rmn -= mref; SB();
;     ...
;             if (hn) { STOREK(t & 1); STOREV((t + 1) & 1); }
;             __syncthreads();
.Lmla_p1_go:
	v_exp_f32_e32 v222, v82
	v_exp_f32_e32 v223, v83
	v_add_f32_e32 v164, 0, v222
	v_cvt_pk_bf16_f32 v206, v222, v223
	v_add_f32_e32 v164, v223, v164
	v_exp_f32_e32 v224, v84
	v_exp_f32_e32 v225, v85
	v_add_f32_e32 v164, v224, v164
	v_cvt_pk_bf16_f32 v207, v224, v225
	v_add_f32_e32 v164, v225, v164
	s_waitcnt lgkmcnt(4)
	v_mfma_f32_32x32x16_bf16 v[34:49], v[182:185], v[114:117], v[66:81]
	ds_read_b128 v[198:201], v174 offset:45120
	v_exp_f32_e32 v222, v86
	v_exp_f32_e32 v223, v87
	v_add_f32_e32 v164, v222, v164
	v_cvt_pk_bf16_f32 v208, v222, v223
	v_add_f32_e32 v164, v223, v164
	s_waitcnt lgkmcnt(3)
	v_mfma_f32_32x32x16_bf16 v[50:65], v[186:189], v[114:117], v[66:81]
	ds_read_b128 v[182:185], v174 offset:51776
	v_exp_f32_e32 v224, v88
	v_exp_f32_e32 v225, v89
	v_add_f32_e32 v164, v224, v164
	v_cvt_pk_bf16_f32 v209, v224, v225
	v_add_f32_e32 v164, v225, v164
	s_waitcnt lgkmcnt(3)
	v_mfma_f32_32x32x16_bf16 v[34:49], v[190:193], v[118:121], v[34:49]
	ds_read_b128 v[186:189], v174 offset:45152
	v_exp_f32_e32 v222, v90
	v_exp_f32_e32 v223, v91
	v_add_f32_e32 v164, v222, v164
	v_cvt_pk_bf16_f32 v210, v222, v223
	v_add_f32_e32 v164, v223, v164
	s_waitcnt lgkmcnt(3)
	v_mfma_f32_32x32x16_bf16 v[50:65], v[194:197], v[118:121], v[50:65]
	ds_read_b128 v[190:193], v174 offset:51808
	v_exp_f32_e32 v224, v92
	v_exp_f32_e32 v225, v93
	v_add_f32_e32 v164, v224, v164
	v_cvt_pk_bf16_f32 v211, v224, v225
	v_add_f32_e32 v164, v225, v164
	s_waitcnt lgkmcnt(3)
	v_mfma_f32_32x32x16_bf16 v[34:49], v[198:201], v[122:125], v[34:49]
	ds_read_b128 v[194:197], v174 offset:45184
	v_exp_f32_e32 v222, v94
	v_exp_f32_e32 v223, v95
	v_add_f32_e32 v164, v222, v164
	v_cvt_pk_bf16_f32 v212, v222, v223
	v_add_f32_e32 v164, v223, v164
	s_waitcnt lgkmcnt(3)
	v_mfma_f32_32x32x16_bf16 v[50:65], v[182:185], v[122:125], v[50:65]
	ds_read_b128 v[198:201], v174 offset:51840
	v_exp_f32_e32 v224, v96
	v_exp_f32_e32 v225, v97
	v_add_f32_e32 v164, v224, v164
	v_cvt_pk_bf16_f32 v213, v224, v225
	v_add_f32_e32 v164, v225, v164
	s_waitcnt lgkmcnt(3)
	v_mfma_f32_32x32x16_bf16 v[34:49], v[186:189], v[126:129], v[34:49]
	ds_read_b128 v[182:185], v174 offset:45216
	v_exp_f32_e32 v222, v98
	v_exp_f32_e32 v223, v99
	v_add_f32_e32 v164, v222, v164
	v_cvt_pk_bf16_f32 v214, v222, v223
	v_add_f32_e32 v164, v223, v164
	s_waitcnt lgkmcnt(3)
	v_mfma_f32_32x32x16_bf16 v[50:65], v[190:193], v[126:129], v[50:65]
	ds_read_b128 v[186:189], v174 offset:51872
	v_exp_f32_e32 v224, v100
	v_exp_f32_e32 v225, v101
	v_add_f32_e32 v164, v224, v164
	v_cvt_pk_bf16_f32 v215, v224, v225
	v_add_f32_e32 v164, v225, v164
	s_waitcnt lgkmcnt(3)
	v_mfma_f32_32x32x16_bf16 v[34:49], v[194:197], v[130:133], v[34:49]
	ds_read_b128 v[190:193], v228 offset:35840
	v_exp_f32_e32 v222, v102
	v_exp_f32_e32 v223, v103
	v_add_f32_e32 v164, v222, v164
	v_cvt_pk_bf16_f32 v216, v222, v223
	v_add_f32_e32 v164, v223, v164
	s_waitcnt lgkmcnt(3)
	v_mfma_f32_32x32x16_bf16 v[50:65], v[198:201], v[130:133], v[50:65]
	ds_read_b128 v[194:197], v228 offset:40448
	v_exp_f32_e32 v224, v104
	v_exp_f32_e32 v225, v105
	v_add_f32_e32 v164, v224, v164
	v_cvt_pk_bf16_f32 v217, v224, v225
	v_add_f32_e32 v164, v225, v164
	s_waitcnt lgkmcnt(3)
	v_mfma_f32_32x32x16_bf16 v[34:49], v[182:185], v[134:137], v[34:49]
	ds_read_b128 v[198:201], v228 offset:35872
	v_exp_f32_e32 v222, v106
	v_exp_f32_e32 v223, v107
	v_add_f32_e32 v164, v222, v164
	v_cvt_pk_bf16_f32 v218, v222, v223
	v_add_f32_e32 v164, v223, v164
	s_waitcnt lgkmcnt(3)
	v_mfma_f32_32x32x16_bf16 v[50:65], v[186:189], v[134:137], v[50:65]
	ds_read_b128 v[182:185], v228 offset:40480
	v_exp_f32_e32 v224, v108
	v_exp_f32_e32 v225, v109
	v_add_f32_e32 v164, v224, v164
	v_cvt_pk_bf16_f32 v219, v224, v225
	v_add_f32_e32 v164, v225, v164
	s_waitcnt lgkmcnt(3)
	v_mfma_f32_32x32x16_bf16 v[2:17], v[190:193], v[206:209], v[2:17]
	ds_read_b128 v[186:189], v228 offset:35904
	v_exp_f32_e32 v222, v110
	v_exp_f32_e32 v223, v111
	v_add_f32_e32 v164, v222, v164
	v_cvt_pk_bf16_f32 v220, v222, v223
	v_add_f32_e32 v164, v223, v164
	s_waitcnt lgkmcnt(3)
	v_mfma_f32_32x32x16_bf16 v[18:33], v[194:197], v[206:209], v[18:33]
	ds_read_b128 v[190:193], v228 offset:40512
	v_exp_f32_e32 v224, v112
	v_exp_f32_e32 v225, v113
	v_add_f32_e32 v164, v224, v164
	v_cvt_pk_bf16_f32 v221, v224, v225
	v_add_f32_e32 v164, v225, v164
	s_mov_b32 s13, s20
	s_mov_b32 s20, s19
	s_add_i32 s19, s19, 1
	s_cmp_eq_u32 s19, s9
	s_cselect_b32 s19, 0, s19
	s_waitcnt lgkmcnt(3)
	v_mfma_f32_32x32x16_bf16 v[2:17], v[198:201], v[210:213], v[2:17]
	ds_read_b128 v[194:197], v228 offset:35936
	v_max3_f32 v224, v34, v35, v36
	v_max3_f32 v225, v50, v51, v52
	v_max3_f32 v224, v224, v37, v38
	v_max3_f32 v225, v225, v53, v54
	s_waitcnt vmcnt(2)
	ds_write_b128 v172, v[150:153]
	v_lshl_add_u32 v222, s19, 17, v178
	global_load_dwordx4 v[150:153], v222, s[52:53]
	s_waitcnt lgkmcnt(4)
	v_mfma_f32_32x32x16_bf16 v[18:33], v[182:185], v[210:213], v[18:33]
	ds_read_b128 v[198:201], v228 offset:40544
	v_max3_f32 v224, v224, v39, v40
	v_max3_f32 v225, v225, v55, v56
	v_max3_f32 v224, v224, v41, v42
	v_max3_f32 v225, v225, v57, v58
	s_and_b64 vcc, exec, s[2:3]
	s_cbranch_vccz .Lmla_p1_nope
	ds_write_b128 v176, v[160:163] offset:128
	v_lshl_add_u32 v222, s19, 12, v179
	global_load_dwordx4 v[160:163], v222, s[62:63]
.Lmla_p1_nope:
	s_waitcnt lgkmcnt(4)
	v_mfma_f32_32x32x16_bf16 v[2:17], v[186:189], v[214:217], v[2:17]
	ds_read_b128 v[182:185], v229 offset:13312
	v_max3_f32 v224, v224, v43, v44
	v_max3_f32 v225, v225, v59, v60
	v_max3_f32 v224, v224, v45, v46
	v_max3_f32 v225, v225, v61, v62
	v_add_u32_e32 v222, 0xb000, v173
	ds_write_b128 v222, v[202:205] offset:49152
	v_lshl_add_u32 v222, s13, 7, v168
	global_load_dwordx4 v[202:205], v222, s[56:57]
	s_waitcnt lgkmcnt(5)
	v_mfma_f32_32x32x16_bf16 v[18:33], v[190:193], v[214:217], v[18:33]
	ds_read_b128 v[186:189], v229 offset:19968
	v_max3_f32 v224, v224, v47, v48
	v_max3_f32 v225, v225, v63, v64
	v_max3_f32 v224, v224, v49, v65
	v_max_f32_e32 v224, v224, v225
	s_waitcnt lgkmcnt(5)
	v_mfma_f32_32x32x16_bf16 v[2:17], v[194:197], v[218:221], v[2:17]
	ds_read_b128 v[190:193], v229 offset:13344
	v_mov_b32_e32 v225, v224
	v_add_f32_e32 v1, v1, v164
	s_add_i32 s11, s11, 1
	v_permlane32_swap_b32_e32 v224, v225
	s_cmp_eq_u32 s9, s11
	v_max_f32_e32 v167, v224, v225
	s_waitcnt lgkmcnt(4)
	v_mfma_f32_32x32x16_bf16 v[18:33], v[198:201], v[218:221], v[18:33]
	ds_read_b128 v[194:197], v229 offset:20000
	v_cmp_lt_f32_e32 vcc, s66, v167
	s_waitcnt lgkmcnt(3)
	s_barrier
	s_cbranch_scc1 .Lmla_exit_p1

; template <int VAR>
; __device__ __forceinline__ void attn_phase(LAS unsigned char* lds, const AttnP P, int vcu, int G, int wave_s) {
;     ...
;                 if (ND0 == 6) {
;                     KR1(0); KR1(1); KR1(2); KR1(3); SB();
;                     QK1(0, negm); EX2(pc0, 0, w0.x); KR1(4); SB();
;                     QK1(1, negm); EX2(pc0, 2, w0.y); KR1(5); SB();
;                     QK1(2, pn0); EX2(pc0, 4, w0.z); KR1(6); SB();
;                     QK1(3, pn1); EX2(pc0, 6, w0.w); KR1(7); SB();
;                     QK1(4, pn0); EX2(pc0, 8, w1.x); KR1(8); SB();
;                     QK1(5, pn1); EX2(pc0, 10, w1.y); KR1(9); SB();
;                     QK1(6, pn0); EX2(pc0, 12, w1.z); KR1(10); SB();
;                     QK1(7, pn1); EX2(pc0, 14, w1.w); KR1(11); SB();
;                     QK1(8, pn0); EX2(pc1, 0, w2.x); VR1(0); SB();
;                     QK1(9, pn1); EX2(pc1, 2, w2.y); VR1(1); SB();
;                     QK1(10, pn0); EX2(pc1, 4, w2.z); VR1(2); SB();
;                     QK1(11, pn1); EX2(pc1, 6, w2.w); VR1(3); SB();
;                 } else {
;                     KR1(0); KR1(1); KR1(2); KR1(3); SB();
;                     QK1(0, negm); EX2(pc0, 0, w0.x); EX2(pc0, 2, w0.y); KR1(4); SB();
;                     QK1(1, negm); EX2(pc0, 4, w0.z); EX2(pc0, 6, w0.w); KR1(5); SB();
;                     QK1(2, pn0); EX2(pc0, 8, w1.x); EX2(pc0, 10, w1.y); KR1(6); SB();
;                     QK1(3, pn1); EX2(pc0, 12, w1.z); EX2(pc0, 14, w1.w); KR1(7); SB();
;                     QK1(4, pn0); EX2(pc1, 0, w2.x); VR1(0); SB();
;                     QK1(5, pn1); EX2(pc1, 2, w2.y); VR1(1); SB();
;                     QK1(6, pn0); EX2(pc1, 4, w2.z); VR1(2); SB();
;                     QK1(7, pn1); EX2(pc1, 6, w2.w); VR1(3); SB();
;                 }
;                 PV1(0, w0); EX2(pc1, 8, w3.x); VR1(4); SB();
;                 PV1(1, w0); EX2(pc1, 10, w3.y); VR1(5); SB();
;                 PV1(2, w1); EX2(pc1, 12, w3.z); VR1(6); SB();
;                 PV1(3, w1); EX2(pc1, 14, w3.w); VR1(7); SB();
;                 lrun += sacc;
;                 PV1(4, w2); MASK_TILE(pn0, pn1, t + 1); SB();
;                 PV1(5, w2); SB();
;                 PV1(6, w3); SB();
;                 PV1(7, w3); rmn = rowmax32(pn0, pn1); if (!USE_NEGM) rmn -= mref; SB();
;     ...
;             if (hn) { STOREK(t & 1); STOREV((t + 1) & 1); }
;             __syncthreads();
.Lmla_p2_go:
	v_exp_f32_e32 v222, v34
	v_exp_f32_e32 v223, v35
	v_add_f32_e32 v164, 0, v222
	v_cvt_pk_bf16_f32 v206, v222, v223
	v_add_f32_e32 v164, v223, v164
	v_exp_f32_e32 v224, v36
	v_exp_f32_e32 v225, v37
	v_add_f32_e32 v164, v224, v164
	v_cvt_pk_bf16_f32 v207, v224, v225
	v_add_f32_e32 v164, v225, v164
	s_waitcnt lgkmcnt(3)
	v_mfma_f32_32x32x16_bf16 v[82:97], v[182:185], v[114:117], v[66:81]
	ds_read_b128 v[198:201], v229 offset:13376
	v_exp_f32_e32 v222, v38
	v_exp_f32_e32 v223, v39
	v_add_f32_e32 v164, v222, v164
	v_cvt_pk_bf16_f32 v208, v222, v223
	v_add_f32_e32 v164, v223, v164
	s_waitcnt lgkmcnt(3)
	v_mfma_f32_32x32x16_bf16 v[98:113], v[186:189], v[114:117], v[66:81]
	ds_read_b128 v[182:185], v229 offset:20032
	v_exp_f32_e32 v224, v40
	v_exp_f32_e32 v225, v41
	v_add_f32_e32 v164, v224, v164
	v_cvt_pk_bf16_f32 v209, v224, v225
	v_add_f32_e32 v164, v225, v164
	s_waitcnt lgkmcnt(3)
	v_mfma_f32_32x32x16_bf16 v[82:97], v[190:193], v[118:121], v[82:97]
	ds_read_b128 v[186:189], v229 offset:13408
	v_exp_f32_e32 v222, v42
	v_exp_f32_e32 v223, v43
	v_add_f32_e32 v164, v222, v164
	v_cvt_pk_bf16_f32 v210, v222, v223
	v_add_f32_e32 v164, v223, v164
	s_waitcnt lgkmcnt(3)
	v_mfma_f32_32x32x16_bf16 v[98:113], v[194:197], v[118:121], v[98:113]
	ds_read_b128 v[190:193], v229 offset:20064
	v_exp_f32_e32 v224, v44
	v_exp_f32_e32 v225, v45
	v_add_f32_e32 v164, v224, v164
	v_cvt_pk_bf16_f32 v211, v224, v225
	v_add_f32_e32 v164, v225, v164
	s_waitcnt lgkmcnt(3)
	v_mfma_f32_32x32x16_bf16 v[82:97], v[198:201], v[122:125], v[82:97]
	ds_read_b128 v[194:197], v229 offset:13440
	v_exp_f32_e32 v222, v46
	v_exp_f32_e32 v223, v47
	v_add_f32_e32 v164, v222, v164
	v_cvt_pk_bf16_f32 v212, v222, v223
	v_add_f32_e32 v164, v223, v164
	s_waitcnt lgkmcnt(3)
	v_mfma_f32_32x32x16_bf16 v[98:113], v[182:185], v[122:125], v[98:113]
	ds_read_b128 v[198:201], v229 offset:20096
	v_exp_f32_e32 v224, v48
	v_exp_f32_e32 v225, v49
	v_add_f32_e32 v164, v224, v164
	v_cvt_pk_bf16_f32 v213, v224, v225
	v_add_f32_e32 v164, v225, v164
	s_waitcnt lgkmcnt(3)
	v_mfma_f32_32x32x16_bf16 v[82:97], v[186:189], v[126:129], v[82:97]
	ds_read_b128 v[182:185], v229 offset:13472
	v_exp_f32_e32 v222, v50
	v_exp_f32_e32 v223, v51
	v_add_f32_e32 v164, v222, v164
	v_cvt_pk_bf16_f32 v214, v222, v223
	v_add_f32_e32 v164, v223, v164
	s_waitcnt lgkmcnt(3)
	v_mfma_f32_32x32x16_bf16 v[98:113], v[190:193], v[126:129], v[98:113]
	ds_read_b128 v[186:189], v229 offset:20128
	v_exp_f32_e32 v224, v52
	v_exp_f32_e32 v225, v53
	v_add_f32_e32 v164, v224, v164
	v_cvt_pk_bf16_f32 v215, v224, v225
	v_add_f32_e32 v164, v225, v164
	s_waitcnt lgkmcnt(3)
	v_mfma_f32_32x32x16_bf16 v[82:97], v[194:197], v[130:133], v[82:97]
	ds_read_b128 v[190:193], v181 offset:39936
	v_exp_f32_e32 v222, v54
	v_exp_f32_e32 v223, v55
	v_add_f32_e32 v164, v222, v164
	v_cvt_pk_bf16_f32 v216, v222, v223
	v_add_f32_e32 v164, v223, v164
	s_waitcnt lgkmcnt(3)
	v_mfma_f32_32x32x16_bf16 v[98:113], v[198:201], v[130:133], v[98:113]
	ds_read_b128 v[194:197], v181 offset:44544
	v_exp_f32_e32 v224, v56
	v_exp_f32_e32 v225, v57
	v_add_f32_e32 v164, v224, v164
	v_cvt_pk_bf16_f32 v217, v224, v225
	v_add_f32_e32 v164, v225, v164
	s_waitcnt lgkmcnt(3)
	v_mfma_f32_32x32x16_bf16 v[82:97], v[182:185], v[134:137], v[82:97]
	ds_read_b128 v[198:201], v181 offset:39968
	v_exp_f32_e32 v222, v58
	v_exp_f32_e32 v223, v59
	v_add_f32_e32 v164, v222, v164
	v_cvt_pk_bf16_f32 v218, v222, v223
	v_add_f32_e32 v164, v223, v164
	s_waitcnt lgkmcnt(3)
	v_mfma_f32_32x32x16_bf16 v[98:113], v[186:189], v[134:137], v[98:113]
	ds_read_b128 v[182:185], v181 offset:44576
	v_exp_f32_e32 v224, v60
	v_exp_f32_e32 v225, v61
	v_add_f32_e32 v164, v224, v164
	v_cvt_pk_bf16_f32 v219, v224, v225
	v_add_f32_e32 v164, v225, v164
	s_waitcnt lgkmcnt(3)
	v_mfma_f32_32x32x16_bf16 v[2:17], v[190:193], v[206:209], v[2:17]
	ds_read_b128 v[186:189], v181 offset:40000
	v_exp_f32_e32 v222, v62
	v_exp_f32_e32 v223, v63
	v_add_f32_e32 v164, v222, v164
	v_cvt_pk_bf16_f32 v220, v222, v223
	v_add_f32_e32 v164, v223, v164
	s_waitcnt lgkmcnt(3)
	v_mfma_f32_32x32x16_bf16 v[18:33], v[194:197], v[206:209], v[18:33]
	ds_read_b128 v[190:193], v181 offset:44608
	v_exp_f32_e32 v224, v64
	v_exp_f32_e32 v225, v65
	v_add_f32_e32 v164, v224, v164
	v_cvt_pk_bf16_f32 v221, v224, v225
	v_add_f32_e32 v164, v225, v164
	s_mov_b32 s13, s20
	s_mov_b32 s20, s19
	s_add_i32 s19, s19, 1
	s_cmp_eq_u32 s19, s9
	s_cselect_b32 s19, 0, s19
	s_waitcnt lgkmcnt(3)
	v_mfma_f32_32x32x16_bf16 v[2:17], v[198:201], v[210:213], v[2:17]
	ds_read_b128 v[194:197], v181 offset:40032
	v_max3_f32 v224, v82, v83, v84
	v_max3_f32 v225, v98, v99, v100
	v_max3_f32 v224, v224, v85, v86
	v_max3_f32 v225, v225, v101, v102
	s_waitcnt vmcnt(2)
	ds_write_b128 v172, v[146:149] offset:22528
	v_lshl_add_u32 v222, s19, 17, v178
	global_load_dwordx4 v[146:149], v222, s[52:53]
	s_waitcnt lgkmcnt(4)
	v_mfma_f32_32x32x16_bf16 v[18:33], v[182:185], v[210:213], v[18:33]
	ds_read_b128 v[198:201], v181 offset:44640
	v_max3_f32 v224, v224, v87, v88
	v_max3_f32 v225, v225, v103, v104
	v_max3_f32 v224, v224, v89, v90
	v_max3_f32 v225, v225, v105, v106
	s_and_b64 vcc, exec, s[2:3]
	s_cbranch_vccz .Lmla_p2_nope
	ds_write_b128 v176, v[138:141] offset:22656
	v_lshl_add_u32 v222, s19, 12, v179
	global_load_dwordx4 v[138:141], v222, s[62:63]
.Lmla_p2_nope:
	s_waitcnt lgkmcnt(4)
	v_mfma_f32_32x32x16_bf16 v[2:17], v[186:189], v[214:217], v[2:17]
	ds_read_b128 v[182:185], v229 offset:26624
	v_max3_f32 v224, v224, v91, v92
	v_max3_f32 v225, v225, v107, v108
	v_max3_f32 v224, v224, v93, v94
	v_max3_f32 v225, v225, v109, v110
	ds_write_b128 v173, v[142:145] offset:13312
	v_lshl_add_u32 v222, s13, 7, v168
	global_load_dwordx4 v[142:145], v222, s[56:57]
	s_waitcnt lgkmcnt(5)
	v_mfma_f32_32x32x16_bf16 v[18:33], v[190:193], v[214:217], v[18:33]
	ds_read_b128 v[186:189], v229 offset:33280
	v_max3_f32 v224, v224, v95, v96
	v_max3_f32 v225, v225, v111, v112
	v_max3_f32 v224, v224, v97, v113
	v_max_f32_e32 v224, v224, v225
	s_waitcnt lgkmcnt(5)
	v_mfma_f32_32x32x16_bf16 v[2:17], v[194:197], v[218:221], v[2:17]
	ds_read_b128 v[190:193], v229 offset:26656
	v_mov_b32_e32 v225, v224
	v_add_f32_e32 v1, v1, v164
	s_add_i32 s11, s11, 1
	v_permlane32_swap_b32_e32 v224, v225
	s_cmp_eq_u32 s9, s11
	v_max_f32_e32 v167, v224, v225
	s_waitcnt lgkmcnt(4)
	v_mfma_f32_32x32x16_bf16 v[18:33], v[198:201], v[218:221], v[18:33]
	ds_read_b128 v[194:197], v229 offset:33312
	v_cmp_lt_f32_e32 vcc, s66, v167
	s_cbranch_scc1 .Lmla_exit_p2

; template <int VAR>
; __device__ __forceinline__ void attn_phase(LAS unsigned char* lds, const AttnP P, int vcu, int G, int wave_s) {
;     ...
;                 if (ND0 == 6) {
;                     KR1(0); KR1(1); KR1(2); KR1(3); SB();
;                     QK1(0, negm); EX2(pc0, 0, w0.x); KR1(4); SB();
;                     QK1(1, negm); EX2(pc0, 2, w0.y); KR1(5); SB();
;                     QK1(2, pn0); EX2(pc0, 4, w0.z); KR1(6); SB();
;                     QK1(3, pn1); EX2(pc0, 6, w0.w); KR1(7); SB();
;                     QK1(4, pn0); EX2(pc0, 8, w1.x); KR1(8); SB();
;                     QK1(5, pn1); EX2(pc0, 10, w1.y); KR1(9); SB();
;                     QK1(6, pn0); EX2(pc0, 12, w1.z); KR1(10); SB();
;                     QK1(7, pn1); EX2(pc0, 14, w1.w); KR1(11); SB();
;                     QK1(8, pn0); EX2(pc1, 0, w2.x); VR1(0); SB();
;                     QK1(9, pn1); EX2(pc1, 2, w2.y); VR1(1); SB();
;                     QK1(10, pn0); EX2(pc1, 4, w2.z); VR1(2); SB();
;                     QK1(11, pn1); EX2(pc1, 6, w2.w); VR1(3); SB();
;                 } else {
;                     KR1(0); KR1(1); KR1(2); KR1(3); SB();
;                     QK1(0, negm); EX2(pc0, 0, w0.x); EX2(pc0, 2, w0.y); KR1(4); SB();
;                     QK1(1, negm); EX2(pc0, 4, w0.z); EX2(pc0, 6, w0.w); KR1(5); SB();
;                     QK1(2, pn0); EX2(pc0, 8, w1.x); EX2(pc0, 10, w1.y); KR1(6); SB();
;                     QK1(3, pn1); EX2(pc0, 12, w1.z); EX2(pc0, 14, w1.w); KR1(7); SB();
;                     QK1(4, pn0); EX2(pc1, 0, w2.x); VR1(0); SB();
;                     QK1(5, pn1); EX2(pc1, 2, w2.y); VR1(1); SB();
;                     QK1(6, pn0); EX2(pc1, 4, w2.z); VR1(2); SB();
;                     QK1(7, pn1); EX2(pc1, 6, w2.w); VR1(3); SB();
;                 }
;                 PV1(0, w0); EX2(pc1, 8, w3.x); VR1(4); SB();
;                 PV1(1, w0); EX2(pc1, 10, w3.y); VR1(5); SB();
;                 PV1(2, w1); EX2(pc1, 12, w3.z); VR1(6); SB();
;                 PV1(3, w1); EX2(pc1, 14, w3.w); VR1(7); SB();
;                 lrun += sacc;
;                 PV1(4, w2); MASK_TILE(pn0, pn1, t + 1); SB();
;                 PV1(5, w2); SB();
;                 PV1(6, w3); SB();
;                 PV1(7, w3); rmn = rowmax32(pn0, pn1); if (!USE_NEGM) rmn -= mref; SB();
;     ...
;             if (hn) { STOREK(t & 1); STOREV((t + 1) & 1); }
;             __syncthreads();
.Lmla_p3_go:
	v_exp_f32_e32 v222, v82
	v_exp_f32_e32 v223, v83
	v_add_f32_e32 v164, 0, v222
	v_cvt_pk_bf16_f32 v206, v222, v223
	v_add_f32_e32 v164, v223, v164
	v_exp_f32_e32 v224, v84
	v_exp_f32_e32 v225, v85
	v_add_f32_e32 v164, v224, v164
	v_cvt_pk_bf16_f32 v207, v224, v225
	v_add_f32_e32 v164, v225, v164
	s_waitcnt lgkmcnt(4)
	v_mfma_f32_32x32x16_bf16 v[34:49], v[182:185], v[114:117], v[66:81]
	ds_read_b128 v[198:201], v229 offset:26688
	v_exp_f32_e32 v222, v86
	v_exp_f32_e32 v223, v87
	v_add_f32_e32 v164, v222, v164
	v_cvt_pk_bf16_f32 v208, v222, v223
	v_add_f32_e32 v164, v223, v164
	s_waitcnt lgkmcnt(3)
	v_mfma_f32_32x32x16_bf16 v[50:65], v[186:189], v[114:117], v[66:81]
	ds_read_b128 v[182:185], v229 offset:33344
	v_exp_f32_e32 v224, v88
	v_exp_f32_e32 v225, v89
	v_add_f32_e32 v164, v224, v164
	v_cvt_pk_bf16_f32 v209, v224, v225
	v_add_f32_e32 v164, v225, v164
	s_waitcnt lgkmcnt(3)
	v_mfma_f32_32x32x16_bf16 v[34:49], v[190:193], v[118:121], v[34:49]
	ds_read_b128 v[186:189], v229 offset:26720
	v_exp_f32_e32 v222, v90
	v_exp_f32_e32 v223, v91
	v_add_f32_e32 v164, v222, v164
	v_cvt_pk_bf16_f32 v210, v222, v223
	v_add_f32_e32 v164, v223, v164
	s_waitcnt lgkmcnt(3)
	v_mfma_f32_32x32x16_bf16 v[50:65], v[194:197], v[118:121], v[50:65]
	ds_read_b128 v[190:193], v229 offset:33376
	v_exp_f32_e32 v224, v92
	v_exp_f32_e32 v225, v93
	v_add_f32_e32 v164, v224, v164
	v_cvt_pk_bf16_f32 v211, v224, v225
	v_add_f32_e32 v164, v225, v164
	s_waitcnt lgkmcnt(3)
	v_mfma_f32_32x32x16_bf16 v[34:49], v[198:201], v[122:125], v[34:49]
	ds_read_b128 v[194:197], v229 offset:26752
	v_exp_f32_e32 v222, v94
	v_exp_f32_e32 v223, v95
	v_add_f32_e32 v164, v222, v164
	v_cvt_pk_bf16_f32 v212, v222, v223
	v_add_f32_e32 v164, v223, v164
	s_waitcnt lgkmcnt(3)
	v_mfma_f32_32x32x16_bf16 v[50:65], v[182:185], v[122:125], v[50:65]
	ds_read_b128 v[198:201], v229 offset:33408
	v_exp_f32_e32 v224, v96
	v_exp_f32_e32 v225, v97
	v_add_f32_e32 v164, v224, v164
	v_cvt_pk_bf16_f32 v213, v224, v225
	v_add_f32_e32 v164, v225, v164
	s_waitcnt lgkmcnt(3)
	v_mfma_f32_32x32x16_bf16 v[34:49], v[186:189], v[126:129], v[34:49]
	ds_read_b128 v[182:185], v229 offset:26784
	v_exp_f32_e32 v222, v98
	v_exp_f32_e32 v223, v99
	v_add_f32_e32 v164, v222, v164
	v_cvt_pk_bf16_f32 v214, v222, v223
	v_add_f32_e32 v164, v223, v164
	s_waitcnt lgkmcnt(3)
	v_mfma_f32_32x32x16_bf16 v[50:65], v[190:193], v[126:129], v[50:65]
	ds_read_b128 v[186:189], v229 offset:33440
	v_exp_f32_e32 v224, v100
	v_exp_f32_e32 v225, v101
	v_add_f32_e32 v164, v224, v164
	v_cvt_pk_bf16_f32 v215, v224, v225
	v_add_f32_e32 v164, v225, v164
	s_waitcnt lgkmcnt(3)
	v_mfma_f32_32x32x16_bf16 v[34:49], v[194:197], v[130:133], v[34:49]
	ds_read_b128 v[190:193], v181 offset:49152
	v_exp_f32_e32 v222, v102
	v_exp_f32_e32 v223, v103
	v_add_f32_e32 v164, v222, v164
	v_cvt_pk_bf16_f32 v216, v222, v223
	v_add_f32_e32 v164, v223, v164
	s_waitcnt lgkmcnt(3)
	v_mfma_f32_32x32x16_bf16 v[50:65], v[198:201], v[130:133], v[50:65]
	ds_read_b128 v[194:197], v181 offset:53760
	v_exp_f32_e32 v224, v104
	v_exp_f32_e32 v225, v105
	v_add_f32_e32 v164, v224, v164
	v_cvt_pk_bf16_f32 v217, v224, v225
	v_add_f32_e32 v164, v225, v164
	s_waitcnt lgkmcnt(3)
	v_mfma_f32_32x32x16_bf16 v[34:49], v[182:185], v[134:137], v[34:49]
	ds_read_b128 v[198:201], v181 offset:49184
	v_exp_f32_e32 v222, v106
	v_exp_f32_e32 v223, v107
	v_add_f32_e32 v164, v222, v164
	v_cvt_pk_bf16_f32 v218, v222, v223
	v_add_f32_e32 v164, v223, v164
	s_waitcnt lgkmcnt(3)
	v_mfma_f32_32x32x16_bf16 v[50:65], v[186:189], v[134:137], v[50:65]
	ds_read_b128 v[182:185], v181 offset:53792
	v_exp_f32_e32 v224, v108
	v_exp_f32_e32 v225, v109
	v_add_f32_e32 v164, v224, v164
	v_cvt_pk_bf16_f32 v219, v224, v225
	v_add_f32_e32 v164, v225, v164
	s_waitcnt lgkmcnt(3)
	v_mfma_f32_32x32x16_bf16 v[2:17], v[190:193], v[206:209], v[2:17]
	ds_read_b128 v[186:189], v181 offset:49216
	v_exp_f32_e32 v222, v110
	v_exp_f32_e32 v223, v111
	v_add_f32_e32 v164, v222, v164
	v_cvt_pk_bf16_f32 v220, v222, v223
	v_add_f32_e32 v164, v223, v164
	s_waitcnt lgkmcnt(3)
	v_mfma_f32_32x32x16_bf16 v[18:33], v[194:197], v[206:209], v[18:33]
	ds_read_b128 v[190:193], v181 offset:53824
	v_exp_f32_e32 v224, v112
	v_exp_f32_e32 v225, v113
	v_add_f32_e32 v164, v224, v164
	v_cvt_pk_bf16_f32 v221, v224, v225
	v_add_f32_e32 v164, v225, v164
	s_mov_b32 s13, s20
	s_mov_b32 s20, s19
	s_add_i32 s19, s19, 1
	s_cmp_eq_u32 s19, s9
	s_cselect_b32 s19, 0, s19
	s_waitcnt lgkmcnt(3)
	v_mfma_f32_32x32x16_bf16 v[2:17], v[198:201], v[210:213], v[2:17]
	ds_read_b128 v[194:197], v181 offset:49248
	v_max3_f32 v224, v34, v35, v36
	v_max3_f32 v225, v50, v51, v52
	v_max3_f32 v224, v224, v37, v38
	v_max3_f32 v225, v225, v53, v54
	s_waitcnt vmcnt(2)
	ds_write_b128 v172, v[150:153] offset:45056
	v_lshl_add_u32 v222, s19, 17, v178
	global_load_dwordx4 v[150:153], v222, s[52:53]
	s_waitcnt lgkmcnt(4)
	v_mfma_f32_32x32x16_bf16 v[18:33], v[182:185], v[210:213], v[18:33]
	ds_read_b128 v[198:201], v181 offset:53856
	v_max3_f32 v224, v224, v39, v40
	v_max3_f32 v225, v225, v55, v56
	v_max3_f32 v224, v224, v41, v42
	v_max3_f32 v225, v225, v57, v58
	s_and_b64 vcc, exec, s[2:3]
	s_cbranch_vccz .Lmla_p3_nope
	ds_write_b128 v176, v[160:163] offset:45184
	v_lshl_add_u32 v222, s19, 12, v179
	global_load_dwordx4 v[160:163], v222, s[62:63]
.Lmla_p3_nope:
	s_waitcnt lgkmcnt(4)
	v_mfma_f32_32x32x16_bf16 v[2:17], v[186:189], v[214:217], v[2:17]
	ds_read_b128 v[182:185], v174
	v_max3_f32 v224, v224, v43, v44
	v_max3_f32 v225, v225, v59, v60
	v_max3_f32 v224, v224, v45, v46
	v_max3_f32 v225, v225, v61, v62
	ds_write_b128 v173, v[202:205] offset:35840
	v_lshl_add_u32 v222, s13, 7, v168
	global_load_dwordx4 v[202:205], v222, s[56:57]
	s_waitcnt lgkmcnt(5)
	v_mfma_f32_32x32x16_bf16 v[18:33], v[190:193], v[214:217], v[18:33]
	ds_read_b128 v[186:189], v174 offset:6656
	v_max3_f32 v224, v224, v47, v48
	v_max3_f32 v225, v225, v63, v64
	v_max3_f32 v224, v224, v49, v65
	v_max_f32_e32 v224, v224, v225
	s_waitcnt lgkmcnt(5)
	v_mfma_f32_32x32x16_bf16 v[2:17], v[194:197], v[218:221], v[2:17]
	ds_read_b128 v[190:193], v174 offset:32
	v_mov_b32_e32 v225, v224
	v_add_f32_e32 v1, v1, v164
	s_add_i32 s11, s11, 1
	v_permlane32_swap_b32_e32 v224, v225
	s_cmp_eq_u32 s9, s11
	v_max_f32_e32 v167, v224, v225
	s_waitcnt lgkmcnt(4)
	v_mfma_f32_32x32x16_bf16 v[18:33], v[198:201], v[218:221], v[18:33]
	ds_read_b128 v[194:197], v174 offset:6688
	v_cmp_lt_f32_e32 vcc, s66, v167
	s_waitcnt lgkmcnt(3)
	s_barrier
	s_cbranch_scc1 .Lmla_exit_p3

; template <int VAR>
; __device__ __forceinline__ void attn_phase(LAS unsigned char* lds, const AttnP P, int vcu, int G, int wave_s) {
;     ...
;                 if (ND0 == 6) {
;                     KR1(0); KR1(1); KR1(2); KR1(3); SB();
;                     QK1(0, negm); EX2(pc0, 0, w0.x); KR1(4); SB();
;                     QK1(1, negm); EX2(pc0, 2, w0.y); KR1(5); SB();
;                     QK1(2, pn0); EX2(pc0, 4, w0.z); KR1(6); SB();
;                     QK1(3, pn1); EX2(pc0, 6, w0.w); KR1(7); SB();
;                     QK1(4, pn0); EX2(pc0, 8, w1.x); KR1(8); SB();
;                     QK1(5, pn1); EX2(pc0, 10, w1.y); KR1(9); SB();
;                     QK1(6, pn0); EX2(pc0, 12, w1.z); KR1(10); SB();
;                     QK1(7, pn1); EX2(pc0, 14, w1.w); KR1(11); SB();
;                     QK1(8, pn0); EX2(pc1, 0, w2.x); VR1(0); SB();
;                     QK1(9, pn1); EX2(pc1, 2, w2.y); VR1(1); SB();
;                     QK1(10, pn0); EX2(pc1, 4, w2.z); VR1(2); SB();
;                     QK1(11, pn1); EX2(pc1, 6, w2.w); VR1(3); SB();
;                 } else {
;                     KR1(0); KR1(1); KR1(2); KR1(3); SB();
;                     QK1(0, negm); EX2(pc0, 0, w0.x); EX2(pc0, 2, w0.y); KR1(4); SB();
;                     QK1(1, negm); EX2(pc0, 4, w0.z); EX2(pc0, 6, w0.w); KR1(5); SB();
;                     QK1(2, pn0); EX2(pc0, 8, w1.x); EX2(pc0, 10, w1.y); KR1(6); SB();
;                     QK1(3, pn1); EX2(pc0, 12, w1.z); EX2(pc0, 14, w1.w); KR1(7); SB();
;                     QK1(4, pn0); EX2(pc1, 0, w2.x); VR1(0); SB();
;                     QK1(5, pn1); EX2(pc1, 2, w2.y); VR1(1); SB();
;                     QK1(6, pn0); EX2(pc1, 4, w2.z); VR1(2); SB();
;                     QK1(7, pn1); EX2(pc1, 6, w2.w); VR1(3); SB();
;                 }
;                 PV1(0, w0); EX2(pc1, 8, w3.x); VR1(4); SB();
;                 PV1(1, w0); EX2(pc1, 10, w3.y); VR1(5); SB();
;                 PV1(2, w1); EX2(pc1, 12, w3.z); VR1(6); SB();
;                 PV1(3, w1); EX2(pc1, 14, w3.w); VR1(7); SB();
;                 lrun += sacc;
;                 PV1(4, w2); MASK_TILE(pn0, pn1, t + 1); SB();
;                 PV1(5, w2); SB();
;                 PV1(6, w3); SB();
;                 PV1(7, w3); rmn = rowmax32(pn0, pn1); if (!USE_NEGM) rmn -= mref; SB();
;     ...
;             if (hn) { STOREK(t & 1); STOREV((t + 1) & 1); }
;             __syncthreads();
.Lmla_p4_go:
	v_exp_f32_e32 v222, v34
	v_exp_f32_e32 v223, v35
	v_add_f32_e32 v164, 0, v222
	v_cvt_pk_bf16_f32 v206, v222, v223
	v_add_f32_e32 v164, v223, v164
	v_exp_f32_e32 v224, v36
	v_exp_f32_e32 v225, v37
	v_add_f32_e32 v164, v224, v164
	v_cvt_pk_bf16_f32 v207, v224, v225
	v_add_f32_e32 v164, v225, v164
	s_waitcnt lgkmcnt(3)
	v_mfma_f32_32x32x16_bf16 v[82:97], v[182:185], v[114:117], v[66:81]
	ds_read_b128 v[198:201], v174 offset:64
	v_exp_f32_e32 v222, v38
	v_exp_f32_e32 v223, v39
	v_add_f32_e32 v164, v222, v164
	v_cvt_pk_bf16_f32 v208, v222, v223
	v_add_f32_e32 v164, v223, v164
	s_waitcnt lgkmcnt(3)
	v_mfma_f32_32x32x16_bf16 v[98:113], v[186:189], v[114:117], v[66:81]
	ds_read_b128 v[182:185], v174 offset:6720
	v_exp_f32_e32 v224, v40
	v_exp_f32_e32 v225, v41
	v_add_f32_e32 v164, v224, v164
	v_cvt_pk_bf16_f32 v209, v224, v225
	v_add_f32_e32 v164, v225, v164
	s_waitcnt lgkmcnt(3)
	v_mfma_f32_32x32x16_bf16 v[82:97], v[190:193], v[118:121], v[82:97]
	ds_read_b128 v[186:189], v174 offset:96
	v_exp_f32_e32 v222, v42
	v_exp_f32_e32 v223, v43
	v_add_f32_e32 v164, v222, v164
	v_cvt_pk_bf16_f32 v210, v222, v223
	v_add_f32_e32 v164, v223, v164
	s_waitcnt lgkmcnt(3)
	v_mfma_f32_32x32x16_bf16 v[98:113], v[194:197], v[118:121], v[98:113]
	ds_read_b128 v[190:193], v174 offset:6752
	v_exp_f32_e32 v224, v44
	v_exp_f32_e32 v225, v45
	v_add_f32_e32 v164, v224, v164
	v_cvt_pk_bf16_f32 v211, v224, v225
	v_add_f32_e32 v164, v225, v164
	s_waitcnt lgkmcnt(3)
	v_mfma_f32_32x32x16_bf16 v[82:97], v[198:201], v[122:125], v[82:97]
	ds_read_b128 v[194:197], v174 offset:128
	v_exp_f32_e32 v222, v46
	v_exp_f32_e32 v223, v47
	v_add_f32_e32 v164, v222, v164
	v_cvt_pk_bf16_f32 v212, v222, v223
	v_add_f32_e32 v164, v223, v164
	s_waitcnt lgkmcnt(3)
	v_mfma_f32_32x32x16_bf16 v[98:113], v[182:185], v[122:125], v[98:113]
	ds_read_b128 v[198:201], v174 offset:6784
	v_exp_f32_e32 v224, v48
	v_exp_f32_e32 v225, v49
	v_add_f32_e32 v164, v224, v164
	v_cvt_pk_bf16_f32 v213, v224, v225
	v_add_f32_e32 v164, v225, v164
	s_waitcnt lgkmcnt(3)
	v_mfma_f32_32x32x16_bf16 v[82:97], v[186:189], v[126:129], v[82:97]
	ds_read_b128 v[182:185], v174 offset:160
	v_exp_f32_e32 v222, v50
	v_exp_f32_e32 v223, v51
	v_add_f32_e32 v164, v222, v164
	v_cvt_pk_bf16_f32 v214, v222, v223
	v_add_f32_e32 v164, v223, v164
	s_waitcnt lgkmcnt(3)
	v_mfma_f32_32x32x16_bf16 v[98:113], v[190:193], v[126:129], v[98:113]
	ds_read_b128 v[186:189], v174 offset:6816
	v_exp_f32_e32 v224, v52
	v_exp_f32_e32 v225, v53
	v_add_f32_e32 v164, v224, v164
	v_cvt_pk_bf16_f32 v215, v224, v225
	v_add_f32_e32 v164, v225, v164
	s_waitcnt lgkmcnt(3)
	v_mfma_f32_32x32x16_bf16 v[82:97], v[194:197], v[130:133], v[82:97]
	ds_read_b128 v[190:193], v228 offset:13312
	v_exp_f32_e32 v222, v54
	v_exp_f32_e32 v223, v55
	v_add_f32_e32 v164, v222, v164
	v_cvt_pk_bf16_f32 v216, v222, v223
	v_add_f32_e32 v164, v223, v164
	s_waitcnt lgkmcnt(3)
	v_mfma_f32_32x32x16_bf16 v[98:113], v[198:201], v[130:133], v[98:113]
	ds_read_b128 v[194:197], v228 offset:17920
	v_exp_f32_e32 v224, v56
	v_exp_f32_e32 v225, v57
	v_add_f32_e32 v164, v224, v164
	v_cvt_pk_bf16_f32 v217, v224, v225
	v_add_f32_e32 v164, v225, v164
	s_waitcnt lgkmcnt(3)
	v_mfma_f32_32x32x16_bf16 v[82:97], v[182:185], v[134:137], v[82:97]
	ds_read_b128 v[198:201], v228 offset:13344
	v_exp_f32_e32 v222, v58
	v_exp_f32_e32 v223, v59
	v_add_f32_e32 v164, v222, v164
	v_cvt_pk_bf16_f32 v218, v222, v223
	v_add_f32_e32 v164, v223, v164
	s_waitcnt lgkmcnt(3)
	v_mfma_f32_32x32x16_bf16 v[98:113], v[186:189], v[134:137], v[98:113]
	ds_read_b128 v[182:185], v228 offset:17952
	v_exp_f32_e32 v224, v60
	v_exp_f32_e32 v225, v61
	v_add_f32_e32 v164, v224, v164
	v_cvt_pk_bf16_f32 v219, v224, v225
	v_add_f32_e32 v164, v225, v164
	s_waitcnt lgkmcnt(3)
	v_mfma_f32_32x32x16_bf16 v[2:17], v[190:193], v[206:209], v[2:17]
	ds_read_b128 v[186:189], v228 offset:13376
	v_exp_f32_e32 v222, v62
	v_exp_f32_e32 v223, v63
	v_add_f32_e32 v164, v222, v164
	v_cvt_pk_bf16_f32 v220, v222, v223
	v_add_f32_e32 v164, v223, v164
	s_waitcnt lgkmcnt(3)
	v_mfma_f32_32x32x16_bf16 v[18:33], v[194:197], v[206:209], v[18:33]
	ds_read_b128 v[190:193], v228 offset:17984
	v_exp_f32_e32 v224, v64
	v_exp_f32_e32 v225, v65
	v_add_f32_e32 v164, v224, v164
	v_cvt_pk_bf16_f32 v221, v224, v225
	v_add_f32_e32 v164, v225, v164
	s_mov_b32 s13, s20
	s_mov_b32 s20, s19
	s_add_i32 s19, s19, 1
	s_cmp_eq_u32 s19, s9
	s_cselect_b32 s19, 0, s19
	s_waitcnt lgkmcnt(3)
	v_mfma_f32_32x32x16_bf16 v[2:17], v[198:201], v[210:213], v[2:17]
	ds_read_b128 v[194:197], v228 offset:13408
	v_max3_f32 v224, v82, v83, v84
	v_max3_f32 v225, v98, v99, v100
	v_max3_f32 v224, v224, v85, v86
	v_max3_f32 v225, v225, v101, v102
	s_waitcnt vmcnt(2)
	ds_write_b128 v172, v[146:149] offset:58368
	v_lshl_add_u32 v222, s19, 17, v178
	global_load_dwordx4 v[146:149], v222, s[52:53]
	s_waitcnt lgkmcnt(4)
	v_mfma_f32_32x32x16_bf16 v[18:33], v[182:185], v[210:213], v[18:33]
	ds_read_b128 v[198:201], v228 offset:18016
	v_max3_f32 v224, v224, v87, v88
	v_max3_f32 v225, v225, v103, v104
	v_max3_f32 v224, v224, v89, v90
	v_max3_f32 v225, v225, v105, v106
	s_and_b64 vcc, exec, s[2:3]
	s_cbranch_vccz .Lmla_p4_nope
	ds_write_b128 v176, v[138:141] offset:58496
	v_lshl_add_u32 v222, s19, 12, v179
	global_load_dwordx4 v[138:141], v222, s[62:63]
.Lmla_p4_nope:
	s_waitcnt lgkmcnt(4)
	v_mfma_f32_32x32x16_bf16 v[2:17], v[186:189], v[214:217], v[2:17]
	ds_read_b128 v[182:185], v174 offset:22528
	v_max3_f32 v224, v224, v91, v92
	v_max3_f32 v225, v225, v107, v108
	v_max3_f32 v224, v224, v93, v94
	v_max3_f32 v225, v225, v109, v110
	v_add_u32_e32 v222, 0xb000, v173
	ds_write_b128 v222, v[142:145] offset:39936
	v_lshl_add_u32 v222, s13, 7, v168
	global_load_dwordx4 v[142:145], v222, s[56:57]
	s_waitcnt lgkmcnt(5)
	v_mfma_f32_32x32x16_bf16 v[18:33], v[190:193], v[214:217], v[18:33]
	ds_read_b128 v[186:189], v174 offset:29184
	v_max3_f32 v224, v224, v95, v96
	v_max3_f32 v225, v225, v111, v112
	v_max3_f32 v224, v224, v97, v113
	v_max_f32_e32 v224, v224, v225
	s_waitcnt lgkmcnt(5)
	v_mfma_f32_32x32x16_bf16 v[2:17], v[194:197], v[218:221], v[2:17]
	ds_read_b128 v[190:193], v174 offset:22560
	v_mov_b32_e32 v225, v224
	v_add_f32_e32 v1, v1, v164
	s_add_i32 s11, s11, 1
	v_permlane32_swap_b32_e32 v224, v225
	s_cmp_eq_u32 s9, s11
	v_max_f32_e32 v167, v224, v225
	s_waitcnt lgkmcnt(4)
	v_mfma_f32_32x32x16_bf16 v[18:33], v[198:201], v[218:221], v[18:33]
	ds_read_b128 v[194:197], v174 offset:29216
	v_cmp_lt_f32_e32 vcc, s66, v167
	s_cbranch_scc1 .Lmla_exit_p4

; template <int VAR>
; __device__ __forceinline__ void attn_phase(LAS unsigned char* lds, const AttnP P, int vcu, int G, int wave_s) {
;     ...
;                 if (ND0 == 6) {
;                     KR1(0); KR1(1); KR1(2); KR1(3); SB();
;                     QK1(0, negm); EX2(pc0, 0, w0.x); KR1(4); SB();
;                     QK1(1, negm); EX2(pc0, 2, w0.y); KR1(5); SB();
;                     QK1(2, pn0); EX2(pc0, 4, w0.z); KR1(6); SB();
;                     QK1(3, pn1); EX2(pc0, 6, w0.w); KR1(7); SB();
;                     QK1(4, pn0); EX2(pc0, 8, w1.x); KR1(8); SB();
;                     QK1(5, pn1); EX2(pc0, 10, w1.y); KR1(9); SB();
;                     QK1(6, pn0); EX2(pc0, 12, w1.z); KR1(10); SB();
;                     QK1(7, pn1); EX2(pc0, 14, w1.w); KR1(11); SB();
;                     QK1(8, pn0); EX2(pc1, 0, w2.x); VR1(0); SB();
;                     QK1(9, pn1); EX2(pc1, 2, w2.y); VR1(1); SB();
;                     QK1(10, pn0); EX2(pc1, 4, w2.z); VR1(2); SB();
;                     QK1(11, pn1); EX2(pc1, 6, w2.w); VR1(3); SB();
;                 } else {
;                     KR1(0); KR1(1); KR1(2); KR1(3); SB();
;                     QK1(0, negm); EX2(pc0, 0, w0.x); EX2(pc0, 2, w0.y); KR1(4); SB();
;                     QK1(1, negm); EX2(pc0, 4, w0.z); EX2(pc0, 6, w0.w); KR1(5); SB();
;                     QK1(2, pn0); EX2(pc0, 8, w1.x); EX2(pc0, 10, w1.y); KR1(6); SB();
;                     QK1(3, pn1); EX2(pc0, 12, w1.z); EX2(pc0, 14, w1.w); KR1(7); SB();
;                     QK1(4, pn0); EX2(pc1, 0, w2.x); VR1(0); SB();
;                     QK1(5, pn1); EX2(pc1, 2, w2.y); VR1(1); SB();
;                     QK1(6, pn0); EX2(pc1, 4, w2.z); VR1(2); SB();
;                     QK1(7, pn1); EX2(pc1, 6, w2.w); VR1(3); SB();
;                 }
;                 PV1(0, w0); EX2(pc1, 8, w3.x); VR1(4); SB();
;                 PV1(1, w0); EX2(pc1, 10, w3.y); VR1(5); SB();
;                 PV1(2, w1); EX2(pc1, 12, w3.z); VR1(6); SB();
;                 PV1(3, w1); EX2(pc1, 14, w3.w); VR1(7); SB();
;                 lrun += sacc;
;                 PV1(4, w2); MASK_TILE(pn0, pn1, t + 1); SB();
;                 PV1(5, w2); SB();
;                 PV1(6, w3); SB();
;                 PV1(7, w3); rmn = rowmax32(pn0, pn1); if (!USE_NEGM) rmn -= mref; SB();
;     ...
;             if (hn) { STOREK(t & 1); STOREV((t + 1) & 1); }
;             __syncthreads();
.Lmla_p5_go:
	v_exp_f32_e32 v222, v82
	v_exp_f32_e32 v223, v83
	v_add_f32_e32 v164, 0, v222
	v_cvt_pk_bf16_f32 v206, v222, v223
	v_add_f32_e32 v164, v223, v164
	v_exp_f32_e32 v224, v84
	v_exp_f32_e32 v225, v85
	v_add_f32_e32 v164, v224, v164
	v_cvt_pk_bf16_f32 v207, v224, v225
	v_add_f32_e32 v164, v225, v164
	s_waitcnt lgkmcnt(4)
	v_mfma_f32_32x32x16_bf16 v[34:49], v[182:185], v[114:117], v[66:81]
	ds_read_b128 v[198:201], v174 offset:22592
	v_exp_f32_e32 v222, v86
	v_exp_f32_e32 v223, v87
	v_add_f32_e32 v164, v222, v164
	v_cvt_pk_bf16_f32 v208, v222, v223
	v_add_f32_e32 v164, v223, v164
	s_waitcnt lgkmcnt(3)
	v_mfma_f32_32x32x16_bf16 v[50:65], v[186:189], v[114:117], v[66:81]
	ds_read_b128 v[182:185], v174 offset:29248
	v_exp_f32_e32 v224, v88
	v_exp_f32_e32 v225, v89
	v_add_f32_e32 v164, v224, v164
	v_cvt_pk_bf16_f32 v209, v224, v225
	v_add_f32_e32 v164, v225, v164
	s_waitcnt lgkmcnt(3)
	v_mfma_f32_32x32x16_bf16 v[34:49], v[190:193], v[118:121], v[34:49]
	ds_read_b128 v[186:189], v174 offset:22624
	v_exp_f32_e32 v222, v90
	v_exp_f32_e32 v223, v91
	v_add_f32_e32 v164, v222, v164
	v_cvt_pk_bf16_f32 v210, v222, v223
	v_add_f32_e32 v164, v223, v164
	s_waitcnt lgkmcnt(3)
	v_mfma_f32_32x32x16_bf16 v[50:65], v[194:197], v[118:121], v[50:65]
	ds_read_b128 v[190:193], v174 offset:29280
	v_exp_f32_e32 v224, v92
	v_exp_f32_e32 v225, v93
	v_add_f32_e32 v164, v224, v164
	v_cvt_pk_bf16_f32 v211, v224, v225
	v_add_f32_e32 v164, v225, v164
	s_waitcnt lgkmcnt(3)
	v_mfma_f32_32x32x16_bf16 v[34:49], v[198:201], v[122:125], v[34:49]
	ds_read_b128 v[194:197], v174 offset:22656
	v_exp_f32_e32 v222, v94
	v_exp_f32_e32 v223, v95
	v_add_f32_e32 v164, v222, v164
	v_cvt_pk_bf16_f32 v212, v222, v223
	v_add_f32_e32 v164, v223, v164
	s_waitcnt lgkmcnt(3)
	v_mfma_f32_32x32x16_bf16 v[50:65], v[182:185], v[122:125], v[50:65]
	ds_read_b128 v[198:201], v174 offset:29312
	v_exp_f32_e32 v224, v96
	v_exp_f32_e32 v225, v97
	v_add_f32_e32 v164, v224, v164
	v_cvt_pk_bf16_f32 v213, v224, v225
	v_add_f32_e32 v164, v225, v164
	s_waitcnt lgkmcnt(3)
	v_mfma_f32_32x32x16_bf16 v[34:49], v[186:189], v[126:129], v[34:49]
	ds_read_b128 v[182:185], v174 offset:22688
	v_exp_f32_e32 v222, v98
	v_exp_f32_e32 v223, v99
	v_add_f32_e32 v164, v222, v164
	v_cvt_pk_bf16_f32 v214, v222, v223
	v_add_f32_e32 v164, v223, v164
	s_waitcnt lgkmcnt(3)
	v_mfma_f32_32x32x16_bf16 v[50:65], v[190:193], v[126:129], v[50:65]
	ds_read_b128 v[186:189], v174 offset:29344
	v_exp_f32_e32 v224, v100
	v_exp_f32_e32 v225, v101
	v_add_f32_e32 v164, v224, v164
	v_cvt_pk_bf16_f32 v215, v224, v225
	v_add_f32_e32 v164, v225, v164
	s_waitcnt lgkmcnt(3)
	v_mfma_f32_32x32x16_bf16 v[34:49], v[194:197], v[130:133], v[34:49]
	ds_read_b128 v[190:193], v228 offset:35840
	v_exp_f32_e32 v222, v102
	v_exp_f32_e32 v223, v103
	v_add_f32_e32 v164, v222, v164
	v_cvt_pk_bf16_f32 v216, v222, v223
	v_add_f32_e32 v164, v223, v164
	s_waitcnt lgkmcnt(3)
	v_mfma_f32_32x32x16_bf16 v[50:65], v[198:201], v[130:133], v[50:65]
	ds_read_b128 v[194:197], v228 offset:40448
	v_exp_f32_e32 v224, v104
	v_exp_f32_e32 v225, v105
	v_add_f32_e32 v164, v224, v164
	v_cvt_pk_bf16_f32 v217, v224, v225
	v_add_f32_e32 v164, v225, v164
	s_waitcnt lgkmcnt(3)
	v_mfma_f32_32x32x16_bf16 v[34:49], v[182:185], v[134:137], v[34:49]
	ds_read_b128 v[198:201], v228 offset:35872
	v_exp_f32_e32 v222, v106
	v_exp_f32_e32 v223, v107
	v_add_f32_e32 v164, v222, v164
	v_cvt_pk_bf16_f32 v218, v222, v223
	v_add_f32_e32 v164, v223, v164
	s_waitcnt lgkmcnt(3)
	v_mfma_f32_32x32x16_bf16 v[50:65], v[186:189], v[134:137], v[50:65]
	ds_read_b128 v[182:185], v228 offset:40480
	v_exp_f32_e32 v224, v108
	v_exp_f32_e32 v225, v109
	v_add_f32_e32 v164, v224, v164
	v_cvt_pk_bf16_f32 v219, v224, v225
	v_add_f32_e32 v164, v225, v164
	s_waitcnt lgkmcnt(3)
	v_mfma_f32_32x32x16_bf16 v[2:17], v[190:193], v[206:209], v[2:17]
	ds_read_b128 v[186:189], v228 offset:35904
	v_exp_f32_e32 v222, v110
	v_exp_f32_e32 v223, v111
	v_add_f32_e32 v164, v222, v164
	v_cvt_pk_bf16_f32 v220, v222, v223
	v_add_f32_e32 v164, v223, v164
	s_waitcnt lgkmcnt(3)
	v_mfma_f32_32x32x16_bf16 v[18:33], v[194:197], v[206:209], v[18:33]
	ds_read_b128 v[190:193], v228 offset:40512
	v_exp_f32_e32 v224, v112
	v_exp_f32_e32 v225, v113
	v_add_f32_e32 v164, v224, v164
	v_cvt_pk_bf16_f32 v221, v224, v225
	v_add_f32_e32 v164, v225, v164
	s_mov_b32 s13, s20
	s_mov_b32 s20, s19
	s_add_i32 s19, s19, 1
	s_cmp_eq_u32 s19, s9
	s_cselect_b32 s19, 0, s19
	s_waitcnt lgkmcnt(3)
	v_mfma_f32_32x32x16_bf16 v[2:17], v[198:201], v[210:213], v[2:17]
	ds_read_b128 v[194:197], v228 offset:35936
	v_max3_f32 v224, v34, v35, v36
	v_max3_f32 v225, v50, v51, v52
	v_max3_f32 v224, v224, v37, v38
	v_max3_f32 v225, v225, v53, v54
	s_waitcnt vmcnt(2)
	v_add_u32_e32 v222, 0xb000, v172
	ds_write_b128 v222, v[150:153] offset:26624
	v_lshl_add_u32 v222, s19, 17, v178
	global_load_dwordx4 v[150:153], v222, s[52:53]
	s_waitcnt lgkmcnt(4)
	v_mfma_f32_32x32x16_bf16 v[18:33], v[182:185], v[210:213], v[18:33]
	ds_read_b128 v[198:201], v228 offset:40544
	v_max3_f32 v224, v224, v39, v40
	v_max3_f32 v225, v225, v55, v56
	v_max3_f32 v224, v224, v41, v42
	v_max3_f32 v225, v225, v57, v58
	s_and_b64 vcc, exec, s[2:3]
	s_cbranch_vccz .Lmla_p5_nope
	v_add_u32_e32 v222, 0xb000, v176
	ds_write_b128 v222, v[160:163] offset:26752
	v_lshl_add_u32 v222, s19, 12, v179
	global_load_dwordx4 v[160:163], v222, s[62:63]
.Lmla_p5_nope:
	s_waitcnt lgkmcnt(4)
	v_mfma_f32_32x32x16_bf16 v[2:17], v[186:189], v[214:217], v[2:17]
	ds_read_b128 v[182:185], v174 offset:45056
	v_max3_f32 v224, v224, v43, v44
	v_max3_f32 v225, v225, v59, v60
	v_max3_f32 v224, v224, v45, v46
	v_max3_f32 v225, v225, v61, v62
	v_add_u32_e32 v222, 0xb000, v173
	ds_write_b128 v222, v[202:205] offset:49152
	v_lshl_add_u32 v222, s13, 7, v168
	global_load_dwordx4 v[202:205], v222, s[56:57]
	s_waitcnt lgkmcnt(5)
	v_mfma_f32_32x32x16_bf16 v[18:33], v[190:193], v[214:217], v[18:33]
	ds_read_b128 v[186:189], v174 offset:51712
	v_max3_f32 v224, v224, v47, v48
	v_max3_f32 v225, v225, v63, v64
	v_max3_f32 v224, v224, v49, v65
	v_max_f32_e32 v224, v224, v225
	s_waitcnt lgkmcnt(5)
	v_mfma_f32_32x32x16_bf16 v[2:17], v[194:197], v[218:221], v[2:17]
	ds_read_b128 v[190:193], v174 offset:45088
	v_mov_b32_e32 v225, v224
	v_add_f32_e32 v1, v1, v164
	s_add_i32 s11, s11, 1
	v_permlane32_swap_b32_e32 v224, v225
	s_cmp_eq_u32 s9, s11
	v_max_f32_e32 v167, v224, v225
	s_waitcnt lgkmcnt(4)
	v_mfma_f32_32x32x16_bf16 v[18:33], v[198:201], v[218:221], v[18:33]
	ds_read_b128 v[194:197], v174 offset:51744
	v_cmp_lt_f32_e32 vcc, s66, v167
	s_waitcnt lgkmcnt(3)
	s_barrier
	s_cbranch_scc1 .Lmla_exit_p5

; template <int VAR>
; __device__ __forceinline__ void attn_phase(LAS unsigned char* lds, const AttnP P, int vcu, int G, int wave_s) {
;     ...
;                 if (ND0 == 6) {
;                     KR1(0); KR1(1); KR1(2); KR1(3); SB();
;                     QK1(0, negm); EX2(pc0, 0, w0.x); KR1(4); SB();
;                     QK1(1, negm); EX2(pc0, 2, w0.y); KR1(5); SB();
;                     QK1(2, pn0); EX2(pc0, 4, w0.z); KR1(6); SB();
;                     QK1(3, pn1); EX2(pc0, 6, w0.w); KR1(7); SB();
;                     QK1(4, pn0); EX2(pc0, 8, w1.x); KR1(8); SB();
;                     QK1(5, pn1); EX2(pc0, 10, w1.y); KR1(9); SB();
;                     QK1(6, pn0); EX2(pc0, 12, w1.z); KR1(10); SB();
;                     QK1(7, pn1); EX2(pc0, 14, w1.w); KR1(11); SB();
;                     QK1(8, pn0); EX2(pc1, 0, w2.x); VR1(0); SB();
;                     QK1(9, pn1); EX2(pc1, 2, w2.y); VR1(1); SB();
;                     QK1(10, pn0); EX2(pc1, 4, w2.z); VR1(2); SB();
;                     QK1(11, pn1); EX2(pc1, 6, w2.w); VR1(3); SB();
;                 } else {
;                     KR1(0); KR1(1); KR1(2); KR1(3); SB();
;                     QK1(0, negm); EX2(pc0, 0, w0.x); EX2(pc0, 2, w0.y); KR1(4); SB();
;                     QK1(1, negm); EX2(pc0, 4, w0.z); EX2(pc0, 6, w0.w); KR1(5); SB();
;                     QK1(2, pn0); EX2(pc0, 8, w1.x); EX2(pc0, 10, w1.y); KR1(6); SB();
;                     QK1(3, pn1); EX2(pc0, 12, w1.z); EX2(pc0, 14, w1.w); KR1(7); SB();
;                     QK1(4, pn0); EX2(pc1, 0, w2.x); VR1(0); SB();
;                     QK1(5, pn1); EX2(pc1, 2, w2.y); VR1(1); SB();
;                     QK1(6, pn0); EX2(pc1, 4, w2.z); VR1(2); SB();
;                     QK1(7, pn1); EX2(pc1, 6, w2.w); VR1(3); SB();
;                 }
;                 PV1(0, w0); EX2(pc1, 8, w3.x); VR1(4); SB();
;                 PV1(1, w0); EX2(pc1, 10, w3.y); VR1(5); SB();
;                 PV1(2, w1); EX2(pc1, 12, w3.z); VR1(6); SB();
;                 PV1(3, w1); EX2(pc1, 14, w3.w); VR1(7); SB();
;                 lrun += sacc;
;                 PV1(4, w2); MASK_TILE(pn0, pn1, t + 1); SB();
;                 PV1(5, w2); SB();
;                 PV1(6, w3); SB();
;                 PV1(7, w3); rmn = rowmax32(pn0, pn1); if (!USE_NEGM) rmn -= mref; SB();
;     ...
;             if (hn) { STOREK(t & 1); STOREV((t + 1) & 1); }
;             __syncthreads();
.Lmla_p6_go:
	v_exp_f32_e32 v222, v34
	v_exp_f32_e32 v223, v35
	v_add_f32_e32 v164, 0, v222
	v_cvt_pk_bf16_f32 v206, v222, v223
	v_add_f32_e32 v164, v223, v164
	v_exp_f32_e32 v224, v36
	v_exp_f32_e32 v225, v37
	v_add_f32_e32 v164, v224, v164
	v_cvt_pk_bf16_f32 v207, v224, v225
	v_add_f32_e32 v164, v225, v164
	s_waitcnt lgkmcnt(3)
	v_mfma_f32_32x32x16_bf16 v[82:97], v[182:185], v[114:117], v[66:81]
	ds_read_b128 v[198:201], v174 offset:45120
	v_exp_f32_e32 v222, v38
	v_exp_f32_e32 v223, v39
	v_add_f32_e32 v164, v222, v164
	v_cvt_pk_bf16_f32 v208, v222, v223
	v_add_f32_e32 v164, v223, v164
	s_waitcnt lgkmcnt(3)
	v_mfma_f32_32x32x16_bf16 v[98:113], v[186:189], v[114:117], v[66:81]
	ds_read_b128 v[182:185], v174 offset:51776
	v_exp_f32_e32 v224, v40
	v_exp_f32_e32 v225, v41
	v_add_f32_e32 v164, v224, v164
	v_cvt_pk_bf16_f32 v209, v224, v225
	v_add_f32_e32 v164, v225, v164
	s_waitcnt lgkmcnt(3)
	v_mfma_f32_32x32x16_bf16 v[82:97], v[190:193], v[118:121], v[82:97]
	ds_read_b128 v[186:189], v174 offset:45152
	v_exp_f32_e32 v222, v42
	v_exp_f32_e32 v223, v43
	v_add_f32_e32 v164, v222, v164
	v_cvt_pk_bf16_f32 v210, v222, v223
	v_add_f32_e32 v164, v223, v164
	s_waitcnt lgkmcnt(3)
	v_mfma_f32_32x32x16_bf16 v[98:113], v[194:197], v[118:121], v[98:113]
	ds_read_b128 v[190:193], v174 offset:51808
	v_exp_f32_e32 v224, v44
	v_exp_f32_e32 v225, v45
	v_add_f32_e32 v164, v224, v164
	v_cvt_pk_bf16_f32 v211, v224, v225
	v_add_f32_e32 v164, v225, v164
	s_waitcnt lgkmcnt(3)
	v_mfma_f32_32x32x16_bf16 v[82:97], v[198:201], v[122:125], v[82:97]
	ds_read_b128 v[194:197], v174 offset:45184
	v_exp_f32_e32 v222, v46
	v_exp_f32_e32 v223, v47
	v_add_f32_e32 v164, v222, v164
	v_cvt_pk_bf16_f32 v212, v222, v223
	v_add_f32_e32 v164, v223, v164
	s_waitcnt lgkmcnt(3)
	v_mfma_f32_32x32x16_bf16 v[98:113], v[182:185], v[122:125], v[98:113]
	ds_read_b128 v[198:201], v174 offset:51840
	v_exp_f32_e32 v224, v48
	v_exp_f32_e32 v225, v49
	v_add_f32_e32 v164, v224, v164
	v_cvt_pk_bf16_f32 v213, v224, v225
	v_add_f32_e32 v164, v225, v164
	s_waitcnt lgkmcnt(3)
	v_mfma_f32_32x32x16_bf16 v[82:97], v[186:189], v[126:129], v[82:97]
	ds_read_b128 v[182:185], v174 offset:45216
	v_exp_f32_e32 v222, v50
	v_exp_f32_e32 v223, v51
	v_add_f32_e32 v164, v222, v164
	v_cvt_pk_bf16_f32 v214, v222, v223
	v_add_f32_e32 v164, v223, v164
	s_waitcnt lgkmcnt(3)
	v_mfma_f32_32x32x16_bf16 v[98:113], v[190:193], v[126:129], v[98:113]
	ds_read_b128 v[186:189], v174 offset:51872
	v_exp_f32_e32 v224, v52
	v_exp_f32_e32 v225, v53
	v_add_f32_e32 v164, v224, v164
	v_cvt_pk_bf16_f32 v215, v224, v225
	v_add_f32_e32 v164, v225, v164
	s_waitcnt lgkmcnt(3)
	v_mfma_f32_32x32x16_bf16 v[82:97], v[194:197], v[130:133], v[82:97]
	ds_read_b128 v[190:193], v181 offset:39936
	v_exp_f32_e32 v222, v54
	v_exp_f32_e32 v223, v55
	v_add_f32_e32 v164, v222, v164
	v_cvt_pk_bf16_f32 v216, v222, v223
	v_add_f32_e32 v164, v223, v164
	s_waitcnt lgkmcnt(3)
	v_mfma_f32_32x32x16_bf16 v[98:113], v[198:201], v[130:133], v[98:113]
	ds_read_b128 v[194:197], v181 offset:44544
	v_exp_f32_e32 v224, v56
	v_exp_f32_e32 v225, v57
	v_add_f32_e32 v164, v224, v164
	v_cvt_pk_bf16_f32 v217, v224, v225
	v_add_f32_e32 v164, v225, v164
	s_waitcnt lgkmcnt(3)
	v_mfma_f32_32x32x16_bf16 v[82:97], v[182:185], v[134:137], v[82:97]
	ds_read_b128 v[198:201], v181 offset:39968
	v_exp_f32_e32 v222, v58
	v_exp_f32_e32 v223, v59
	v_add_f32_e32 v164, v222, v164
	v_cvt_pk_bf16_f32 v218, v222, v223
	v_add_f32_e32 v164, v223, v164
	s_waitcnt lgkmcnt(3)
	v_mfma_f32_32x32x16_bf16 v[98:113], v[186:189], v[134:137], v[98:113]
	ds_read_b128 v[182:185], v181 offset:44576
	v_exp_f32_e32 v224, v60
	v_exp_f32_e32 v225, v61
	v_add_f32_e32 v164, v224, v164
	v_cvt_pk_bf16_f32 v219, v224, v225
	v_add_f32_e32 v164, v225, v164
	s_waitcnt lgkmcnt(3)
	v_mfma_f32_32x32x16_bf16 v[2:17], v[190:193], v[206:209], v[2:17]
	ds_read_b128 v[186:189], v181 offset:40000
	v_exp_f32_e32 v222, v62
	v_exp_f32_e32 v223, v63
	v_add_f32_e32 v164, v222, v164
	v_cvt_pk_bf16_f32 v220, v222, v223
	v_add_f32_e32 v164, v223, v164
	s_waitcnt lgkmcnt(3)
	v_mfma_f32_32x32x16_bf16 v[18:33], v[194:197], v[206:209], v[18:33]
	ds_read_b128 v[190:193], v181 offset:44608
	v_exp_f32_e32 v224, v64
	v_exp_f32_e32 v225, v65
	v_add_f32_e32 v164, v224, v164
	v_cvt_pk_bf16_f32 v221, v224, v225
	v_add_f32_e32 v164, v225, v164
	s_mov_b32 s13, s20
	s_mov_b32 s20, s19
	s_add_i32 s19, s19, 1
	s_cmp_eq_u32 s19, s9
	s_cselect_b32 s19, 0, s19
	s_waitcnt lgkmcnt(3)
	v_mfma_f32_32x32x16_bf16 v[2:17], v[198:201], v[210:213], v[2:17]
	ds_read_b128 v[194:197], v181 offset:40032
	v_max3_f32 v224, v82, v83, v84
	v_max3_f32 v225, v98, v99, v100
	v_max3_f32 v224, v224, v85, v86
	v_max3_f32 v225, v225, v101, v102
	s_waitcnt vmcnt(2)
	ds_write_b128 v172, v[146:149]
	v_lshl_add_u32 v222, s19, 17, v178
	global_load_dwordx4 v[146:149], v222, s[52:53]
	s_waitcnt lgkmcnt(4)
	v_mfma_f32_32x32x16_bf16 v[18:33], v[182:185], v[210:213], v[18:33]
	ds_read_b128 v[198:201], v181 offset:44640
	v_max3_f32 v224, v224, v87, v88
	v_max3_f32 v225, v225, v103, v104
	v_max3_f32 v224, v224, v89, v90
	v_max3_f32 v225, v225, v105, v106
	s_and_b64 vcc, exec, s[2:3]
	s_cbranch_vccz .Lmla_p6_nope
	ds_write_b128 v176, v[138:141] offset:128
	v_lshl_add_u32 v222, s19, 12, v179
	global_load_dwordx4 v[138:141], v222, s[62:63]
.Lmla_p6_nope:
	s_waitcnt lgkmcnt(4)
	v_mfma_f32_32x32x16_bf16 v[2:17], v[186:189], v[214:217], v[2:17]
	ds_read_b128 v[182:185], v229 offset:13312
	v_max3_f32 v224, v224, v91, v92
	v_max3_f32 v225, v225, v107, v108
	v_max3_f32 v224, v224, v93, v94
	v_max3_f32 v225, v225, v109, v110
	ds_write_b128 v173, v[142:145] offset:13312
	v_lshl_add_u32 v222, s13, 7, v168
	global_load_dwordx4 v[142:145], v222, s[56:57]
	s_waitcnt lgkmcnt(5)
	v_mfma_f32_32x32x16_bf16 v[18:33], v[190:193], v[214:217], v[18:33]
	ds_read_b128 v[186:189], v229 offset:19968
	v_max3_f32 v224, v224, v95, v96
	v_max3_f32 v225, v225, v111, v112
	v_max3_f32 v224, v224, v97, v113
	v_max_f32_e32 v224, v224, v225
	s_waitcnt lgkmcnt(5)
	v_mfma_f32_32x32x16_bf16 v[2:17], v[194:197], v[218:221], v[2:17]
	ds_read_b128 v[190:193], v229 offset:13344
	v_mov_b32_e32 v225, v224
	v_add_f32_e32 v1, v1, v164
	s_add_i32 s11, s11, 1
	v_permlane32_swap_b32_e32 v224, v225
	s_cmp_eq_u32 s9, s11
	v_max_f32_e32 v167, v224, v225
	s_waitcnt lgkmcnt(4)
	v_mfma_f32_32x32x16_bf16 v[18:33], v[198:201], v[218:221], v[18:33]
	ds_read_b128 v[194:197], v229 offset:20000
	v_cmp_lt_f32_e32 vcc, s66, v167
	s_cbranch_scc1 .Lmla_exit_p6

; template <int VAR>
; __device__ __forceinline__ void attn_phase(LAS unsigned char* lds, const AttnP P, int vcu, int G, int wave_s) {
;     ...
;                 if (ND0 == 6) {
;                     KR1(0); KR1(1); KR1(2); KR1(3); SB();
;                     QK1(0, negm); EX2(pc0, 0, w0.x); KR1(4); SB();
;                     QK1(1, negm); EX2(pc0, 2, w0.y); KR1(5); SB();
;                     QK1(2, pn0); EX2(pc0, 4, w0.z); KR1(6); SB();
;                     QK1(3, pn1); EX2(pc0, 6, w0.w); KR1(7); SB();
;                     QK1(4, pn0); EX2(pc0, 8, w1.x); KR1(8); SB();
;                     QK1(5, pn1); EX2(pc0, 10, w1.y); KR1(9); SB();
;                     QK1(6, pn0); EX2(pc0, 12, w1.z); KR1(10); SB();
;                     QK1(7, pn1); EX2(pc0, 14, w1.w); KR1(11); SB();
;                     QK1(8, pn0); EX2(pc1, 0, w2.x); VR1(0); SB();
;                     QK1(9, pn1); EX2(pc1, 2, w2.y); VR1(1); SB();
;                     QK1(10, pn0); EX2(pc1, 4, w2.z); VR1(2); SB();
;                     QK1(11, pn1); EX2(pc1, 6, w2.w); VR1(3); SB();
;                 } else {
;                     KR1(0); KR1(1); KR1(2); KR1(3); SB();
;                     QK1(0, negm); EX2(pc0, 0, w0.x); EX2(pc0, 2, w0.y); KR1(4); SB();
;                     QK1(1, negm); EX2(pc0, 4, w0.z); EX2(pc0, 6, w0.w); KR1(5); SB();
;                     QK1(2, pn0); EX2(pc0, 8, w1.x); EX2(pc0, 10, w1.y); KR1(6); SB();
;                     QK1(3, pn1); EX2(pc0, 12, w1.z); EX2(pc0, 14, w1.w); KR1(7); SB();
;                     QK1(4, pn0); EX2(pc1, 0, w2.x); VR1(0); SB();
;                     QK1(5, pn1); EX2(pc1, 2, w2.y); VR1(1); SB();
;                     QK1(6, pn0); EX2(pc1, 4, w2.z); VR1(2); SB();
;                     QK1(7, pn1); EX2(pc1, 6, w2.w); VR1(3); SB();
;                 }
;                 PV1(0, w0); EX2(pc1, 8, w3.x); VR1(4); SB();
;                 PV1(1, w0); EX2(pc1, 10, w3.y); VR1(5); SB();
;                 PV1(2, w1); EX2(pc1, 12, w3.z); VR1(6); SB();
;                 PV1(3, w1); EX2(pc1, 14, w3.w); VR1(7); SB();
;                 lrun += sacc;
;                 PV1(4, w2); MASK_TILE(pn0, pn1, t + 1); SB();
;                 PV1(5, w2); SB();
;                 PV1(6, w3); SB();
;                 PV1(7, w3); rmn = rowmax32(pn0, pn1); if (!USE_NEGM) rmn -= mref; SB();
;     ...
;             if (hn) { STOREK(t & 1); STOREV((t + 1) & 1); }
;             __syncthreads();
.Lmla_p7_go:
	v_exp_f32_e32 v222, v82
	v_exp_f32_e32 v223, v83
	v_add_f32_e32 v164, 0, v222
	v_cvt_pk_bf16_f32 v206, v222, v223
	v_add_f32_e32 v164, v223, v164
	v_exp_f32_e32 v224, v84
	v_exp_f32_e32 v225, v85
	v_add_f32_e32 v164, v224, v164
	v_cvt_pk_bf16_f32 v207, v224, v225
	v_add_f32_e32 v164, v225, v164
	s_waitcnt lgkmcnt(4)
	v_mfma_f32_32x32x16_bf16 v[34:49], v[182:185], v[114:117], v[66:81]
	ds_read_b128 v[198:201], v229 offset:13376
	v_exp_f32_e32 v222, v86
	v_exp_f32_e32 v223, v87
	v_add_f32_e32 v164, v222, v164
	v_cvt_pk_bf16_f32 v208, v222, v223
	v_add_f32_e32 v164, v223, v164
	s_waitcnt lgkmcnt(3)
	v_mfma_f32_32x32x16_bf16 v[50:65], v[186:189], v[114:117], v[66:81]
	ds_read_b128 v[182:185], v229 offset:20032
	v_exp_f32_e32 v224, v88
	v_exp_f32_e32 v225, v89
	v_add_f32_e32 v164, v224, v164
	v_cvt_pk_bf16_f32 v209, v224, v225
	v_add_f32_e32 v164, v225, v164
	s_waitcnt lgkmcnt(3)
	v_mfma_f32_32x32x16_bf16 v[34:49], v[190:193], v[118:121], v[34:49]
	ds_read_b128 v[186:189], v229 offset:13408
	v_exp_f32_e32 v222, v90
	v_exp_f32_e32 v223, v91
	v_add_f32_e32 v164, v222, v164
	v_cvt_pk_bf16_f32 v210, v222, v223
	v_add_f32_e32 v164, v223, v164
	s_waitcnt lgkmcnt(3)
	v_mfma_f32_32x32x16_bf16 v[50:65], v[194:197], v[118:121], v[50:65]
	ds_read_b128 v[190:193], v229 offset:20064
	v_exp_f32_e32 v224, v92
	v_exp_f32_e32 v225, v93
	v_add_f32_e32 v164, v224, v164
	v_cvt_pk_bf16_f32 v211, v224, v225
	v_add_f32_e32 v164, v225, v164
	s_waitcnt lgkmcnt(3)
	v_mfma_f32_32x32x16_bf16 v[34:49], v[198:201], v[122:125], v[34:49]
	ds_read_b128 v[194:197], v229 offset:13440
	v_exp_f32_e32 v222, v94
	v_exp_f32_e32 v223, v95
	v_add_f32_e32 v164, v222, v164
	v_cvt_pk_bf16_f32 v212, v222, v223
	v_add_f32_e32 v164, v223, v164
	s_waitcnt lgkmcnt(3)
	v_mfma_f32_32x32x16_bf16 v[50:65], v[182:185], v[122:125], v[50:65]
	ds_read_b128 v[198:201], v229 offset:20096
	v_exp_f32_e32 v224, v96
	v_exp_f32_e32 v225, v97
	v_add_f32_e32 v164, v224, v164
	v_cvt_pk_bf16_f32 v213, v224, v225
	v_add_f32_e32 v164, v225, v164
	s_waitcnt lgkmcnt(3)
	v_mfma_f32_32x32x16_bf16 v[34:49], v[186:189], v[126:129], v[34:49]
	ds_read_b128 v[182:185], v229 offset:13472
	v_exp_f32_e32 v222, v98
	v_exp_f32_e32 v223, v99
	v_add_f32_e32 v164, v222, v164
	v_cvt_pk_bf16_f32 v214, v222, v223
	v_add_f32_e32 v164, v223, v164
	s_waitcnt lgkmcnt(3)
	v_mfma_f32_32x32x16_bf16 v[50:65], v[190:193], v[126:129], v[50:65]
	ds_read_b128 v[186:189], v229 offset:20128
	v_exp_f32_e32 v224, v100
	v_exp_f32_e32 v225, v101
	v_add_f32_e32 v164, v224, v164
	v_cvt_pk_bf16_f32 v215, v224, v225
	v_add_f32_e32 v164, v225, v164
	s_waitcnt lgkmcnt(3)
	v_mfma_f32_32x32x16_bf16 v[34:49], v[194:197], v[130:133], v[34:49]
	ds_read_b128 v[190:193], v181 offset:49152
	v_exp_f32_e32 v222, v102
	v_exp_f32_e32 v223, v103
	v_add_f32_e32 v164, v222, v164
	v_cvt_pk_bf16_f32 v216, v222, v223
	v_add_f32_e32 v164, v223, v164
	s_waitcnt lgkmcnt(3)
	v_mfma_f32_32x32x16_bf16 v[50:65], v[198:201], v[130:133], v[50:65]
	ds_read_b128 v[194:197], v181 offset:53760
	v_exp_f32_e32 v224, v104
	v_exp_f32_e32 v225, v105
	v_add_f32_e32 v164, v224, v164
	v_cvt_pk_bf16_f32 v217, v224, v225
	v_add_f32_e32 v164, v225, v164
	s_waitcnt lgkmcnt(3)
	v_mfma_f32_32x32x16_bf16 v[34:49], v[182:185], v[134:137], v[34:49]
	ds_read_b128 v[198:201], v181 offset:49184
	v_exp_f32_e32 v222, v106
	v_exp_f32_e32 v223, v107
	v_add_f32_e32 v164, v222, v164
	v_cvt_pk_bf16_f32 v218, v222, v223
	v_add_f32_e32 v164, v223, v164
	s_waitcnt lgkmcnt(3)
	v_mfma_f32_32x32x16_bf16 v[50:65], v[186:189], v[134:137], v[50:65]
	ds_read_b128 v[182:185], v181 offset:53792
	v_exp_f32_e32 v224, v108
	v_exp_f32_e32 v225, v109
	v_add_f32_e32 v164, v224, v164
	v_cvt_pk_bf16_f32 v219, v224, v225
	v_add_f32_e32 v164, v225, v164
	s_waitcnt lgkmcnt(3)
	v_mfma_f32_32x32x16_bf16 v[2:17], v[190:193], v[206:209], v[2:17]
	ds_read_b128 v[186:189], v181 offset:49216
	v_exp_f32_e32 v222, v110
	v_exp_f32_e32 v223, v111
	v_add_f32_e32 v164, v222, v164
	v_cvt_pk_bf16_f32 v220, v222, v223
	v_add_f32_e32 v164, v223, v164
	s_waitcnt lgkmcnt(3)
	v_mfma_f32_32x32x16_bf16 v[18:33], v[194:197], v[206:209], v[18:33]
	ds_read_b128 v[190:193], v181 offset:53824
	v_exp_f32_e32 v224, v112
	v_exp_f32_e32 v225, v113
	v_add_f32_e32 v164, v224, v164
	v_cvt_pk_bf16_f32 v221, v224, v225
	v_add_f32_e32 v164, v225, v164
	s_mov_b32 s13, s20
	s_mov_b32 s20, s19
	s_add_i32 s19, s19, 1
	s_cmp_eq_u32 s19, s9
	s_cselect_b32 s19, 0, s19
	s_waitcnt lgkmcnt(3)
	v_mfma_f32_32x32x16_bf16 v[2:17], v[198:201], v[210:213], v[2:17]
	ds_read_b128 v[194:197], v181 offset:49248
	v_max3_f32 v224, v34, v35, v36
	v_max3_f32 v225, v50, v51, v52
	v_max3_f32 v224, v224, v37, v38
	v_max3_f32 v225, v225, v53, v54
	s_waitcnt vmcnt(2)
	ds_write_b128 v172, v[150:153] offset:22528
	v_lshl_add_u32 v222, s19, 17, v178
	global_load_dwordx4 v[150:153], v222, s[52:53]
	s_waitcnt lgkmcnt(4)
	v_mfma_f32_32x32x16_bf16 v[18:33], v[182:185], v[210:213], v[18:33]
	ds_read_b128 v[198:201], v181 offset:53856
	v_max3_f32 v224, v224, v39, v40
	v_max3_f32 v225, v225, v55, v56
	v_max3_f32 v224, v224, v41, v42
	v_max3_f32 v225, v225, v57, v58
	s_and_b64 vcc, exec, s[2:3]
	s_cbranch_vccz .Lmla_p7_nope
	ds_write_b128 v176, v[160:163] offset:22656
	v_lshl_add_u32 v222, s19, 12, v179
	global_load_dwordx4 v[160:163], v222, s[62:63]
.Lmla_p7_nope:
	s_waitcnt lgkmcnt(4)
	v_mfma_f32_32x32x16_bf16 v[2:17], v[186:189], v[214:217], v[2:17]
	ds_read_b128 v[182:185], v229 offset:26624
	v_max3_f32 v224, v224, v43, v44
	v_max3_f32 v225, v225, v59, v60
	v_max3_f32 v224, v224, v45, v46
	v_max3_f32 v225, v225, v61, v62
	ds_write_b128 v173, v[202:205] offset:35840
	v_lshl_add_u32 v222, s13, 7, v168
	global_load_dwordx4 v[202:205], v222, s[56:57]
	s_waitcnt lgkmcnt(5)
	v_mfma_f32_32x32x16_bf16 v[18:33], v[190:193], v[214:217], v[18:33]
	ds_read_b128 v[186:189], v229 offset:33280
	v_max3_f32 v224, v224, v47, v48
	v_max3_f32 v225, v225, v63, v64
	v_max3_f32 v224, v224, v49, v65
	v_max_f32_e32 v224, v224, v225
	s_waitcnt lgkmcnt(5)
	v_mfma_f32_32x32x16_bf16 v[2:17], v[194:197], v[218:221], v[2:17]
	ds_read_b128 v[190:193], v229 offset:26656
	v_mov_b32_e32 v225, v224
	v_add_f32_e32 v1, v1, v164
	s_add_i32 s11, s11, 1
	v_permlane32_swap_b32_e32 v224, v225
	s_cmp_eq_u32 s9, s11
	v_max_f32_e32 v167, v224, v225
	s_waitcnt lgkmcnt(4)
	v_mfma_f32_32x32x16_bf16 v[18:33], v[198:201], v[218:221], v[18:33]
	ds_read_b128 v[194:197], v229 offset:33312
	v_cmp_lt_f32_e32 vcc, s66, v167
	s_waitcnt lgkmcnt(3)
	s_barrier
	s_cbranch_scc1 .Lmla_exit_p7

; template <int VAR>
; __device__ __forceinline__ void attn_phase(LAS unsigned char* lds, const AttnP P, int vcu, int G, int wave_s) {
;     ...
;                 if (ND0 == 6) {
;                     KR1(0); KR1(1); KR1(2); KR1(3); SB();
;                     QK1(0, negm); EX2(pc0, 0, w0.x); KR1(4); SB();
;                     QK1(1, negm); EX2(pc0, 2, w0.y); KR1(5); SB();
;                     QK1(2, pn0); EX2(pc0, 4, w0.z); KR1(6); SB();
;                     QK1(3, pn1); EX2(pc0, 6, w0.w); KR1(7); SB();
;                     QK1(4, pn0); EX2(pc0, 8, w1.x); KR1(8); SB();
;                     QK1(5, pn1); EX2(pc0, 10, w1.y); KR1(9); SB();
;                     QK1(6, pn0); EX2(pc0, 12, w1.z); KR1(10); SB();
;                     QK1(7, pn1); EX2(pc0, 14, w1.w); KR1(11); SB();
;                     QK1(8, pn0); EX2(pc1, 0, w2.x); VR1(0); SB();
;                     QK1(9, pn1); EX2(pc1, 2, w2.y); VR1(1); SB();
;                     QK1(10, pn0); EX2(pc1, 4, w2.z); VR1(2); SB();
;                     QK1(11, pn1); EX2(pc1, 6, w2.w); VR1(3); SB();
;                 } else {
;                     KR1(0); KR1(1); KR1(2); KR1(3); SB();
;                     QK1(0, negm); EX2(pc0, 0, w0.x); EX2(pc0, 2, w0.y); KR1(4); SB();
;                     QK1(1, negm); EX2(pc0, 4, w0.z); EX2(pc0, 6, w0.w); KR1(5); SB();
;                     QK1(2, pn0); EX2(pc0, 8, w1.x); EX2(pc0, 10, w1.y); KR1(6); SB();
;                     QK1(3, pn1); EX2(pc0, 12, w1.z); EX2(pc0, 14, w1.w); KR1(7); SB();
;                     QK1(4, pn0); EX2(pc1, 0, w2.x); VR1(0); SB();
;                     QK1(5, pn1); EX2(pc1, 2, w2.y); VR1(1); SB();
;                     QK1(6, pn0); EX2(pc1, 4, w2.z); VR1(2); SB();
;                     QK1(7, pn1); EX2(pc1, 6, w2.w); VR1(3); SB();
;                 }
;                 PV1(0, w0); EX2(pc1, 8, w3.x); VR1(4); SB();
;                 PV1(1, w0); EX2(pc1, 10, w3.y); VR1(5); SB();
;                 PV1(2, w1); EX2(pc1, 12, w3.z); VR1(6); SB();
;                 PV1(3, w1); EX2(pc1, 14, w3.w); VR1(7); SB();
;                 lrun += sacc;
;                 PV1(4, w2); MASK_TILE(pn0, pn1, t + 1); SB();
;                 PV1(5, w2); SB();
;                 PV1(6, w3); SB();
;                 PV1(7, w3); rmn = rowmax32(pn0, pn1); if (!USE_NEGM) rmn -= mref; SB();
;     ...
;             if (hn) { STOREK(t & 1); STOREV((t + 1) & 1); }
;             __syncthreads();
.Lmla_p8_go:
	v_exp_f32_e32 v222, v34
	v_exp_f32_e32 v223, v35
	v_add_f32_e32 v164, 0, v222
	v_cvt_pk_bf16_f32 v206, v222, v223
	v_add_f32_e32 v164, v223, v164
	v_exp_f32_e32 v224, v36
	v_exp_f32_e32 v225, v37
	v_add_f32_e32 v164, v224, v164
	v_cvt_pk_bf16_f32 v207, v224, v225
	v_add_f32_e32 v164, v225, v164
	s_waitcnt lgkmcnt(3)
	v_mfma_f32_32x32x16_bf16 v[82:97], v[182:185], v[114:117], v[66:81]
	ds_read_b128 v[198:201], v229 offset:26688
	v_exp_f32_e32 v222, v38
	v_exp_f32_e32 v223, v39
	v_add_f32_e32 v164, v222, v164
	v_cvt_pk_bf16_f32 v208, v222, v223
	v_add_f32_e32 v164, v223, v164
	s_waitcnt lgkmcnt(3)
	v_mfma_f32_32x32x16_bf16 v[98:113], v[186:189], v[114:117], v[66:81]
	ds_read_b128 v[182:185], v229 offset:33344
	v_exp_f32_e32 v224, v40
	v_exp_f32_e32 v225, v41
	v_add_f32_e32 v164, v224, v164
	v_cvt_pk_bf16_f32 v209, v224, v225
	v_add_f32_e32 v164, v225, v164
	s_waitcnt lgkmcnt(3)
	v_mfma_f32_32x32x16_bf16 v[82:97], v[190:193], v[118:121], v[82:97]
	ds_read_b128 v[186:189], v229 offset:26720
	v_exp_f32_e32 v222, v42
	v_exp_f32_e32 v223, v43
	v_add_f32_e32 v164, v222, v164
	v_cvt_pk_bf16_f32 v210, v222, v223
	v_add_f32_e32 v164, v223, v164
	s_waitcnt lgkmcnt(3)
	v_mfma_f32_32x32x16_bf16 v[98:113], v[194:197], v[118:121], v[98:113]
	ds_read_b128 v[190:193], v229 offset:33376
	v_exp_f32_e32 v224, v44
	v_exp_f32_e32 v225, v45
	v_add_f32_e32 v164, v224, v164
	v_cvt_pk_bf16_f32 v211, v224, v225
	v_add_f32_e32 v164, v225, v164
	s_waitcnt lgkmcnt(3)
	v_mfma_f32_32x32x16_bf16 v[82:97], v[198:201], v[122:125], v[82:97]
	ds_read_b128 v[194:197], v229 offset:26752
	v_exp_f32_e32 v222, v46
	v_exp_f32_e32 v223, v47
	v_add_f32_e32 v164, v222, v164
	v_cvt_pk_bf16_f32 v212, v222, v223
	v_add_f32_e32 v164, v223, v164
	s_waitcnt lgkmcnt(3)
	v_mfma_f32_32x32x16_bf16 v[98:113], v[182:185], v[122:125], v[98:113]
	ds_read_b128 v[198:201], v229 offset:33408
	v_exp_f32_e32 v224, v48
	v_exp_f32_e32 v225, v49
	v_add_f32_e32 v164, v224, v164
	v_cvt_pk_bf16_f32 v213, v224, v225
	v_add_f32_e32 v164, v225, v164
	s_waitcnt lgkmcnt(3)
	v_mfma_f32_32x32x16_bf16 v[82:97], v[186:189], v[126:129], v[82:97]
	ds_read_b128 v[182:185], v229 offset:26784
	v_exp_f32_e32 v222, v50
	v_exp_f32_e32 v223, v51
	v_add_f32_e32 v164, v222, v164
	v_cvt_pk_bf16_f32 v214, v222, v223
	v_add_f32_e32 v164, v223, v164
	s_waitcnt lgkmcnt(3)
	v_mfma_f32_32x32x16_bf16 v[98:113], v[190:193], v[126:129], v[98:113]
	ds_read_b128 v[186:189], v229 offset:33440
	v_exp_f32_e32 v224, v52
	v_exp_f32_e32 v225, v53
	v_add_f32_e32 v164, v224, v164
	v_cvt_pk_bf16_f32 v215, v224, v225
	v_add_f32_e32 v164, v225, v164
	s_waitcnt lgkmcnt(3)
	v_mfma_f32_32x32x16_bf16 v[82:97], v[194:197], v[130:133], v[82:97]
	ds_read_b128 v[190:193], v228 offset:13312
	v_exp_f32_e32 v222, v54
	v_exp_f32_e32 v223, v55
	v_add_f32_e32 v164, v222, v164
	v_cvt_pk_bf16_f32 v216, v222, v223
	v_add_f32_e32 v164, v223, v164
	s_waitcnt lgkmcnt(3)
	v_mfma_f32_32x32x16_bf16 v[98:113], v[198:201], v[130:133], v[98:113]
	ds_read_b128 v[194:197], v228 offset:17920
	v_exp_f32_e32 v224, v56
	v_exp_f32_e32 v225, v57
	v_add_f32_e32 v164, v224, v164
	v_cvt_pk_bf16_f32 v217, v224, v225
	v_add_f32_e32 v164, v225, v164
	s_waitcnt lgkmcnt(3)
	v_mfma_f32_32x32x16_bf16 v[82:97], v[182:185], v[134:137], v[82:97]
	ds_read_b128 v[198:201], v228 offset:13344
	v_exp_f32_e32 v222, v58
	v_exp_f32_e32 v223, v59
	v_add_f32_e32 v164, v222, v164
	v_cvt_pk_bf16_f32 v218, v222, v223
	v_add_f32_e32 v164, v223, v164
	s_waitcnt lgkmcnt(3)
	v_mfma_f32_32x32x16_bf16 v[98:113], v[186:189], v[134:137], v[98:113]
	ds_read_b128 v[182:185], v228 offset:17952
	v_exp_f32_e32 v224, v60
	v_exp_f32_e32 v225, v61
	v_add_f32_e32 v164, v224, v164
	v_cvt_pk_bf16_f32 v219, v224, v225
	v_add_f32_e32 v164, v225, v164
	s_waitcnt lgkmcnt(3)
	v_mfma_f32_32x32x16_bf16 v[2:17], v[190:193], v[206:209], v[2:17]
	ds_read_b128 v[186:189], v228 offset:13376
	v_exp_f32_e32 v222, v62
	v_exp_f32_e32 v223, v63
	v_add_f32_e32 v164, v222, v164
	v_cvt_pk_bf16_f32 v220, v222, v223
	v_add_f32_e32 v164, v223, v164
	s_waitcnt lgkmcnt(3)
	v_mfma_f32_32x32x16_bf16 v[18:33], v[194:197], v[206:209], v[18:33]
	ds_read_b128 v[190:193], v228 offset:17984
	v_exp_f32_e32 v224, v64
	v_exp_f32_e32 v225, v65
	v_add_f32_e32 v164, v224, v164
	v_cvt_pk_bf16_f32 v221, v224, v225
	v_add_f32_e32 v164, v225, v164
	s_mov_b32 s13, s20
	s_mov_b32 s20, s19
	s_add_i32 s19, s19, 1
	s_cmp_eq_u32 s19, s9
	s_cselect_b32 s19, 0, s19
	s_waitcnt lgkmcnt(3)
	v_mfma_f32_32x32x16_bf16 v[2:17], v[198:201], v[210:213], v[2:17]
	ds_read_b128 v[194:197], v228 offset:13408
	v_max3_f32 v224, v82, v83, v84
	v_max3_f32 v225, v98, v99, v100
	v_max3_f32 v224, v224, v85, v86
	v_max3_f32 v225, v225, v101, v102
	s_waitcnt vmcnt(2)
	ds_write_b128 v172, v[146:149] offset:45056
	v_lshl_add_u32 v222, s19, 17, v178
	global_load_dwordx4 v[146:149], v222, s[52:53]
	s_waitcnt lgkmcnt(4)
	v_mfma_f32_32x32x16_bf16 v[18:33], v[182:185], v[210:213], v[18:33]
	ds_read_b128 v[198:201], v228 offset:18016
	v_max3_f32 v224, v224, v87, v88
	v_max3_f32 v225, v225, v103, v104
	v_max3_f32 v224, v224, v89, v90
	v_max3_f32 v225, v225, v105, v106
	s_and_b64 vcc, exec, s[2:3]
	s_cbranch_vccz .Lmla_p8_nope
	ds_write_b128 v176, v[138:141] offset:45184
	v_lshl_add_u32 v222, s19, 12, v179
	global_load_dwordx4 v[138:141], v222, s[62:63]
.Lmla_p8_nope:
	s_waitcnt lgkmcnt(4)
	v_mfma_f32_32x32x16_bf16 v[2:17], v[186:189], v[214:217], v[2:17]
	ds_read_b128 v[182:185], v174
	v_max3_f32 v224, v224, v91, v92
	v_max3_f32 v225, v225, v107, v108
	v_max3_f32 v224, v224, v93, v94
	v_max3_f32 v225, v225, v109, v110
	v_add_u32_e32 v222, 0xb000, v173
	ds_write_b128 v222, v[142:145] offset:39936
	v_lshl_add_u32 v222, s13, 7, v168
	global_load_dwordx4 v[142:145], v222, s[56:57]
	s_waitcnt lgkmcnt(5)
	v_mfma_f32_32x32x16_bf16 v[18:33], v[190:193], v[214:217], v[18:33]
	ds_read_b128 v[186:189], v174 offset:6656
	v_max3_f32 v224, v224, v95, v96
	v_max3_f32 v225, v225, v111, v112
	v_max3_f32 v224, v224, v97, v113
	v_max_f32_e32 v224, v224, v225
	s_waitcnt lgkmcnt(5)
	v_mfma_f32_32x32x16_bf16 v[2:17], v[194:197], v[218:221], v[2:17]
	ds_read_b128 v[190:193], v174 offset:32
	v_mov_b32_e32 v225, v224
	v_add_f32_e32 v1, v1, v164
	s_add_i32 s11, s11, 1
	v_permlane32_swap_b32_e32 v224, v225
	s_cmp_eq_u32 s9, s11
	v_max_f32_e32 v167, v224, v225
	s_waitcnt lgkmcnt(4)
	v_mfma_f32_32x32x16_bf16 v[18:33], v[198:201], v[218:221], v[18:33]
	ds_read_b128 v[194:197], v174 offset:6688
	v_cmp_lt_f32_e32 vcc, s66, v167
	s_cbranch_scc1 .Lmla_exit_p8

; template <int VAR>
; __device__ __forceinline__ void attn_phase(LAS unsigned char* lds, const AttnP P, int vcu, int G, int wave_s) {
;     ...
;                 if (ND0 == 6) {
;                     KR1(0); KR1(1); KR1(2); KR1(3); SB();
;                     QK1(0, negm); EX2(pc0, 0, w0.x); KR1(4); SB();
;                     QK1(1, negm); EX2(pc0, 2, w0.y); KR1(5); SB();
;                     QK1(2, pn0); EX2(pc0, 4, w0.z); KR1(6); SB();
;                     QK1(3, pn1); EX2(pc0, 6, w0.w); KR1(7); SB();
;                     QK1(4, pn0); EX2(pc0, 8, w1.x); KR1(8); SB();
;                     QK1(5, pn1); EX2(pc0, 10, w1.y); KR1(9); SB();
;                     QK1(6, pn0); EX2(pc0, 12, w1.z); KR1(10); SB();
;                     QK1(7, pn1); EX2(pc0, 14, w1.w); KR1(11); SB();
;                     QK1(8, pn0); EX2(pc1, 0, w2.x); VR1(0); SB();
;                     QK1(9, pn1); EX2(pc1, 2, w2.y); VR1(1); SB();
;                     QK1(10, pn0); EX2(pc1, 4, w2.z); VR1(2); SB();
;                     QK1(11, pn1); EX2(pc1, 6, w2.w); VR1(3); SB();
;                 } else {
;                     KR1(0); KR1(1); KR1(2); KR1(3); SB();
;                     QK1(0, negm); EX2(pc0, 0, w0.x); EX2(pc0, 2, w0.y); KR1(4); SB();
;                     QK1(1, negm); EX2(pc0, 4, w0.z); EX2(pc0, 6, w0.w); KR1(5); SB();
;                     QK1(2, pn0); EX2(pc0, 8, w1.x); EX2(pc0, 10, w1.y); KR1(6); SB();
;                     QK1(3, pn1); EX2(pc0, 12, w1.z); EX2(pc0, 14, w1.w); KR1(7); SB();
;                     QK1(4, pn0); EX2(pc1, 0, w2.x); VR1(0); SB();
;                     QK1(5, pn1); EX2(pc1, 2, w2.y); VR1(1); SB();
;                     QK1(6, pn0); EX2(pc1, 4, w2.z); VR1(2); SB();
;                     QK1(7, pn1); EX2(pc1, 6, w2.w); VR1(3); SB();
;                 }
;                 PV1(0, w0); EX2(pc1, 8, w3.x); VR1(4); SB();
;                 PV1(1, w0); EX2(pc1, 10, w3.y); VR1(5); SB();
;                 PV1(2, w1); EX2(pc1, 12, w3.z); VR1(6); SB();
;                 PV1(3, w1); EX2(pc1, 14, w3.w); VR1(7); SB();
;                 lrun += sacc;
;                 PV1(4, w2); MASK_TILE(pn0, pn1, t + 1); SB();
;                 PV1(5, w2); SB();
;                 PV1(6, w3); SB();
;                 PV1(7, w3); rmn = rowmax32(pn0, pn1); if (!USE_NEGM) rmn -= mref; SB();
;     ...
;             if (hn) { STOREK(t & 1); STOREV((t + 1) & 1); }
;             __syncthreads();
.Lmla_p9_go:
	v_exp_f32_e32 v222, v82
	v_exp_f32_e32 v223, v83
	v_add_f32_e32 v164, 0, v222
	v_cvt_pk_bf16_f32 v206, v222, v223
	v_add_f32_e32 v164, v223, v164
	v_exp_f32_e32 v224, v84
	v_exp_f32_e32 v225, v85
	v_add_f32_e32 v164, v224, v164
	v_cvt_pk_bf16_f32 v207, v224, v225
	v_add_f32_e32 v164, v225, v164
	s_waitcnt lgkmcnt(4)
	v_mfma_f32_32x32x16_bf16 v[34:49], v[182:185], v[114:117], v[66:81]
	ds_read_b128 v[198:201], v174 offset:64
	v_exp_f32_e32 v222, v86
	v_exp_f32_e32 v223, v87
	v_add_f32_e32 v164, v222, v164
	v_cvt_pk_bf16_f32 v208, v222, v223
	v_add_f32_e32 v164, v223, v164
	s_waitcnt lgkmcnt(3)
	v_mfma_f32_32x32x16_bf16 v[50:65], v[186:189], v[114:117], v[66:81]
	ds_read_b128 v[182:185], v174 offset:6720
	v_exp_f32_e32 v224, v88
	v_exp_f32_e32 v225, v89
	v_add_f32_e32 v164, v224, v164
	v_cvt_pk_bf16_f32 v209, v224, v225
	v_add_f32_e32 v164, v225, v164
	s_waitcnt lgkmcnt(3)
	v_mfma_f32_32x32x16_bf16 v[34:49], v[190:193], v[118:121], v[34:49]
	ds_read_b128 v[186:189], v174 offset:96
	v_exp_f32_e32 v222, v90
	v_exp_f32_e32 v223, v91
	v_add_f32_e32 v164, v222, v164
	v_cvt_pk_bf16_f32 v210, v222, v223
	v_add_f32_e32 v164, v223, v164
	s_waitcnt lgkmcnt(3)
	v_mfma_f32_32x32x16_bf16 v[50:65], v[194:197], v[118:121], v[50:65]
	ds_read_b128 v[190:193], v174 offset:6752
	v_exp_f32_e32 v224, v92
	v_exp_f32_e32 v225, v93
	v_add_f32_e32 v164, v224, v164
	v_cvt_pk_bf16_f32 v211, v224, v225
	v_add_f32_e32 v164, v225, v164
	s_waitcnt lgkmcnt(3)
	v_mfma_f32_32x32x16_bf16 v[34:49], v[198:201], v[122:125], v[34:49]
	ds_read_b128 v[194:197], v174 offset:128
	v_exp_f32_e32 v222, v94
	v_exp_f32_e32 v223, v95
	v_add_f32_e32 v164, v222, v164
	v_cvt_pk_bf16_f32 v212, v222, v223
	v_add_f32_e32 v164, v223, v164
	s_waitcnt lgkmcnt(3)
	v_mfma_f32_32x32x16_bf16 v[50:65], v[182:185], v[122:125], v[50:65]
	ds_read_b128 v[198:201], v174 offset:6784
	v_exp_f32_e32 v224, v96
	v_exp_f32_e32 v225, v97
	v_add_f32_e32 v164, v224, v164
	v_cvt_pk_bf16_f32 v213, v224, v225
	v_add_f32_e32 v164, v225, v164
	s_waitcnt lgkmcnt(3)
	v_mfma_f32_32x32x16_bf16 v[34:49], v[186:189], v[126:129], v[34:49]
	ds_read_b128 v[182:185], v174 offset:160
	v_exp_f32_e32 v222, v98
	v_exp_f32_e32 v223, v99
	v_add_f32_e32 v164, v222, v164
	v_cvt_pk_bf16_f32 v214, v222, v223
	v_add_f32_e32 v164, v223, v164
	s_waitcnt lgkmcnt(3)
	v_mfma_f32_32x32x16_bf16 v[50:65], v[190:193], v[126:129], v[50:65]
	ds_read_b128 v[186:189], v174 offset:6816
	v_exp_f32_e32 v224, v100
	v_exp_f32_e32 v225, v101
	v_add_f32_e32 v164, v224, v164
	v_cvt_pk_bf16_f32 v215, v224, v225
	v_add_f32_e32 v164, v225, v164
	s_waitcnt lgkmcnt(3)
	v_mfma_f32_32x32x16_bf16 v[34:49], v[194:197], v[130:133], v[34:49]
	ds_read_b128 v[190:193], v228 offset:35840
	v_exp_f32_e32 v222, v102
	v_exp_f32_e32 v223, v103
	v_add_f32_e32 v164, v222, v164
	v_cvt_pk_bf16_f32 v216, v222, v223
	v_add_f32_e32 v164, v223, v164
	s_waitcnt lgkmcnt(3)
	v_mfma_f32_32x32x16_bf16 v[50:65], v[198:201], v[130:133], v[50:65]
	ds_read_b128 v[194:197], v228 offset:40448
	v_exp_f32_e32 v224, v104
	v_exp_f32_e32 v225, v105
	v_add_f32_e32 v164, v224, v164
	v_cvt_pk_bf16_f32 v217, v224, v225
	v_add_f32_e32 v164, v225, v164
	s_waitcnt lgkmcnt(3)
	v_mfma_f32_32x32x16_bf16 v[34:49], v[182:185], v[134:137], v[34:49]
	ds_read_b128 v[198:201], v228 offset:35872
	v_exp_f32_e32 v222, v106
	v_exp_f32_e32 v223, v107
	v_add_f32_e32 v164, v222, v164
	v_cvt_pk_bf16_f32 v218, v222, v223
	v_add_f32_e32 v164, v223, v164
	s_waitcnt lgkmcnt(3)
	v_mfma_f32_32x32x16_bf16 v[50:65], v[186:189], v[134:137], v[50:65]
	ds_read_b128 v[182:185], v228 offset:40480
	v_exp_f32_e32 v224, v108
	v_exp_f32_e32 v225, v109
	v_add_f32_e32 v164, v224, v164
	v_cvt_pk_bf16_f32 v219, v224, v225
	v_add_f32_e32 v164, v225, v164
	s_waitcnt lgkmcnt(3)
	v_mfma_f32_32x32x16_bf16 v[2:17], v[190:193], v[206:209], v[2:17]
	ds_read_b128 v[186:189], v228 offset:35904
	v_exp_f32_e32 v222, v110
	v_exp_f32_e32 v223, v111
	v_add_f32_e32 v164, v222, v164
	v_cvt_pk_bf16_f32 v220, v222, v223
	v_add_f32_e32 v164, v223, v164
	s_waitcnt lgkmcnt(3)
	v_mfma_f32_32x32x16_bf16 v[18:33], v[194:197], v[206:209], v[18:33]
	ds_read_b128 v[190:193], v228 offset:40512
	v_exp_f32_e32 v224, v112
	v_exp_f32_e32 v225, v113
	v_add_f32_e32 v164, v224, v164
	v_cvt_pk_bf16_f32 v221, v224, v225
	v_add_f32_e32 v164, v225, v164
	s_mov_b32 s13, s20
	s_mov_b32 s20, s19
	s_add_i32 s19, s19, 1
	s_cmp_eq_u32 s19, s9
	s_cselect_b32 s19, 0, s19
	s_waitcnt lgkmcnt(3)
	v_mfma_f32_32x32x16_bf16 v[2:17], v[198:201], v[210:213], v[2:17]
	ds_read_b128 v[194:197], v228 offset:35936
	v_max3_f32 v224, v34, v35, v36
	v_max3_f32 v225, v50, v51, v52
	v_max3_f32 v224, v224, v37, v38
	v_max3_f32 v225, v225, v53, v54
	s_waitcnt vmcnt(2)
	ds_write_b128 v172, v[150:153] offset:58368
	v_lshl_add_u32 v222, s19, 17, v178
	global_load_dwordx4 v[150:153], v222, s[52:53]
	s_waitcnt lgkmcnt(4)
	v_mfma_f32_32x32x16_bf16 v[18:33], v[182:185], v[210:213], v[18:33]
	ds_read_b128 v[198:201], v228 offset:40544
	v_max3_f32 v224, v224, v39, v40
	v_max3_f32 v225, v225, v55, v56
	v_max3_f32 v224, v224, v41, v42
	v_max3_f32 v225, v225, v57, v58
	s_and_b64 vcc, exec, s[2:3]
	s_cbranch_vccz .Lmla_p9_nope
	ds_write_b128 v176, v[160:163] offset:58496
	v_lshl_add_u32 v222, s19, 12, v179
	global_load_dwordx4 v[160:163], v222, s[62:63]
.Lmla_p9_nope:
	s_waitcnt lgkmcnt(4)
	v_mfma_f32_32x32x16_bf16 v[2:17], v[186:189], v[214:217], v[2:17]
	ds_read_b128 v[182:185], v174 offset:22528
	v_max3_f32 v224, v224, v43, v44
	v_max3_f32 v225, v225, v59, v60
	v_max3_f32 v224, v224, v45, v46
	v_max3_f32 v225, v225, v61, v62
	v_add_u32_e32 v222, 0xb000, v173
	ds_write_b128 v222, v[202:205] offset:49152
	v_lshl_add_u32 v222, s13, 7, v168
	global_load_dwordx4 v[202:205], v222, s[56:57]
	s_waitcnt lgkmcnt(5)
	v_mfma_f32_32x32x16_bf16 v[18:33], v[190:193], v[214:217], v[18:33]
	ds_read_b128 v[186:189], v174 offset:29184
	v_max3_f32 v224, v224, v47, v48
	v_max3_f32 v225, v225, v63, v64
	v_max3_f32 v224, v224, v49, v65
	v_max_f32_e32 v224, v224, v225
	s_waitcnt lgkmcnt(5)
	v_mfma_f32_32x32x16_bf16 v[2:17], v[194:197], v[218:221], v[2:17]
	ds_read_b128 v[190:193], v174 offset:22560
	v_mov_b32_e32 v225, v224
	v_add_f32_e32 v1, v1, v164
	s_add_i32 s11, s11, 1
	v_permlane32_swap_b32_e32 v224, v225
	s_cmp_eq_u32 s9, s11
	v_max_f32_e32 v167, v224, v225
	s_waitcnt lgkmcnt(4)
	v_mfma_f32_32x32x16_bf16 v[18:33], v[198:201], v[218:221], v[18:33]
	ds_read_b128 v[194:197], v174 offset:29216
	v_cmp_lt_f32_e32 vcc, s66, v167
	s_waitcnt lgkmcnt(3)
	s_barrier
	s_cbranch_scc1 .Lmla_exit_p9

; template <int VAR>
; __device__ __forceinline__ void attn_phase(LAS unsigned char* lds, const AttnP P, int vcu, int G, int wave_s) {
;     ...
;                 if (ND0 == 6) {
;                     KR1(0); KR1(1); KR1(2); KR1(3); SB();
;                     QK1(0, negm); EX2(pc0, 0, w0.x); KR1(4); SB();
;                     QK1(1, negm); EX2(pc0, 2, w0.y); KR1(5); SB();
;                     QK1(2, pn0); EX2(pc0, 4, w0.z); KR1(6); SB();
;                     QK1(3, pn1); EX2(pc0, 6, w0.w); KR1(7); SB();
;                     QK1(4, pn0); EX2(pc0, 8, w1.x); KR1(8); SB();
;                     QK1(5, pn1); EX2(pc0, 10, w1.y); KR1(9); SB();
;                     QK1(6, pn0); EX2(pc0, 12, w1.z); KR1(10); SB();
;                     QK1(7, pn1); EX2(pc0, 14, w1.w); KR1(11); SB();
;                     QK1(8, pn0); EX2(pc1, 0, w2.x); VR1(0); SB();
;                     QK1(9, pn1); EX2(pc1, 2, w2.y); VR1(1); SB();
;                     QK1(10, pn0); EX2(pc1, 4, w2.z); VR1(2); SB();
;                     QK1(11, pn1); EX2(pc1, 6, w2.w); VR1(3); SB();
;                 } else {
;                     KR1(0); KR1(1); KR1(2); KR1(3); SB();
;                     QK1(0, negm); EX2(pc0, 0, w0.x); EX2(pc0, 2, w0.y); KR1(4); SB();
;                     QK1(1, negm); EX2(pc0, 4, w0.z); EX2(pc0, 6, w0.w); KR1(5); SB();
;                     QK1(2, pn0); EX2(pc0, 8, w1.x); EX2(pc0, 10, w1.y); KR1(6); SB();
;                     QK1(3, pn1); EX2(pc0, 12, w1.z); EX2(pc0, 14, w1.w); KR1(7); SB();
;                     QK1(4, pn0); EX2(pc1, 0, w2.x); VR1(0); SB();
;                     QK1(5, pn1); EX2(pc1, 2, w2.y); VR1(1); SB();
;                     QK1(6, pn0); EX2(pc1, 4, w2.z); VR1(2); SB();
;                     QK1(7, pn1); EX2(pc1, 6, w2.w); VR1(3); SB();
;                 }
;                 PV1(0, w0); EX2(pc1, 8, w3.x); VR1(4); SB();
;                 PV1(1, w0); EX2(pc1, 10, w3.y); VR1(5); SB();
;                 PV1(2, w1); EX2(pc1, 12, w3.z); VR1(6); SB();
;                 PV1(3, w1); EX2(pc1, 14, w3.w); VR1(7); SB();
;                 lrun += sacc;
;                 PV1(4, w2); MASK_TILE(pn0, pn1, t + 1); SB();
;                 PV1(5, w2); SB();
;                 PV1(6, w3); SB();
;                 PV1(7, w3); rmn = rowmax32(pn0, pn1); if (!USE_NEGM) rmn -= mref; SB();
;     ...
;             if (hn) { STOREK(t & 1); STOREV((t + 1) & 1); }
;             __syncthreads();
.Lmla_p10_go:
	v_exp_f32_e32 v222, v34
	v_exp_f32_e32 v223, v35
	v_add_f32_e32 v164, 0, v222
	v_cvt_pk_bf16_f32 v206, v222, v223
	v_add_f32_e32 v164, v223, v164
	v_exp_f32_e32 v224, v36
	v_exp_f32_e32 v225, v37
	v_add_f32_e32 v164, v224, v164
	v_cvt_pk_bf16_f32 v207, v224, v225
	v_add_f32_e32 v164, v225, v164
	s_waitcnt lgkmcnt(3)
	v_mfma_f32_32x32x16_bf16 v[82:97], v[182:185], v[114:117], v[66:81]
	ds_read_b128 v[198:201], v174 offset:22592
	v_exp_f32_e32 v222, v38
	v_exp_f32_e32 v223, v39
	v_add_f32_e32 v164, v222, v164
	v_cvt_pk_bf16_f32 v208, v222, v223
	v_add_f32_e32 v164, v223, v164
	s_waitcnt lgkmcnt(3)
	v_mfma_f32_32x32x16_bf16 v[98:113], v[186:189], v[114:117], v[66:81]
	ds_read_b128 v[182:185], v174 offset:29248
	v_exp_f32_e32 v224, v40
	v_exp_f32_e32 v225, v41
	v_add_f32_e32 v164, v224, v164
	v_cvt_pk_bf16_f32 v209, v224, v225
	v_add_f32_e32 v164, v225, v164
	s_waitcnt lgkmcnt(3)
	v_mfma_f32_32x32x16_bf16 v[82:97], v[190:193], v[118:121], v[82:97]
	ds_read_b128 v[186:189], v174 offset:22624
	v_exp_f32_e32 v222, v42
	v_exp_f32_e32 v223, v43
	v_add_f32_e32 v164, v222, v164
	v_cvt_pk_bf16_f32 v210, v222, v223
	v_add_f32_e32 v164, v223, v164
	s_waitcnt lgkmcnt(3)
	v_mfma_f32_32x32x16_bf16 v[98:113], v[194:197], v[118:121], v[98:113]
	ds_read_b128 v[190:193], v174 offset:29280
	v_exp_f32_e32 v224, v44
	v_exp_f32_e32 v225, v45
	v_add_f32_e32 v164, v224, v164
	v_cvt_pk_bf16_f32 v211, v224, v225
	v_add_f32_e32 v164, v225, v164
	s_waitcnt lgkmcnt(3)
	v_mfma_f32_32x32x16_bf16 v[82:97], v[198:201], v[122:125], v[82:97]
	ds_read_b128 v[194:197], v174 offset:22656
	v_exp_f32_e32 v222, v46
	v_exp_f32_e32 v223, v47
	v_add_f32_e32 v164, v222, v164
	v_cvt_pk_bf16_f32 v212, v222, v223
	v_add_f32_e32 v164, v223, v164
	s_waitcnt lgkmcnt(3)
	v_mfma_f32_32x32x16_bf16 v[98:113], v[182:185], v[122:125], v[98:113]
	ds_read_b128 v[198:201], v174 offset:29312
	v_exp_f32_e32 v224, v48
	v_exp_f32_e32 v225, v49
	v_add_f32_e32 v164, v224, v164
	v_cvt_pk_bf16_f32 v213, v224, v225
	v_add_f32_e32 v164, v225, v164
	s_waitcnt lgkmcnt(3)
	v_mfma_f32_32x32x16_bf16 v[82:97], v[186:189], v[126:129], v[82:97]
	ds_read_b128 v[182:185], v174 offset:22688
	v_exp_f32_e32 v222, v50
	v_exp_f32_e32 v223, v51
	v_add_f32_e32 v164, v222, v164
	v_cvt_pk_bf16_f32 v214, v222, v223
	v_add_f32_e32 v164, v223, v164
	s_waitcnt lgkmcnt(3)
	v_mfma_f32_32x32x16_bf16 v[98:113], v[190:193], v[126:129], v[98:113]
	ds_read_b128 v[186:189], v174 offset:29344
	v_exp_f32_e32 v224, v52
	v_exp_f32_e32 v225, v53
	v_add_f32_e32 v164, v224, v164
	v_cvt_pk_bf16_f32 v215, v224, v225
	v_add_f32_e32 v164, v225, v164
	s_waitcnt lgkmcnt(3)
	v_mfma_f32_32x32x16_bf16 v[82:97], v[194:197], v[130:133], v[82:97]
	ds_read_b128 v[190:193], v181 offset:39936
	v_exp_f32_e32 v222, v54
	v_exp_f32_e32 v223, v55
	v_add_f32_e32 v164, v222, v164
	v_cvt_pk_bf16_f32 v216, v222, v223
	v_add_f32_e32 v164, v223, v164
	s_waitcnt lgkmcnt(3)
	v_mfma_f32_32x32x16_bf16 v[98:113], v[198:201], v[130:133], v[98:113]
	ds_read_b128 v[194:197], v181 offset:44544
	v_exp_f32_e32 v224, v56
	v_exp_f32_e32 v225, v57
	v_add_f32_e32 v164, v224, v164
	v_cvt_pk_bf16_f32 v217, v224, v225
	v_add_f32_e32 v164, v225, v164
	s_waitcnt lgkmcnt(3)
	v_mfma_f32_32x32x16_bf16 v[82:97], v[182:185], v[134:137], v[82:97]
	ds_read_b128 v[198:201], v181 offset:39968
	v_exp_f32_e32 v222, v58
	v_exp_f32_e32 v223, v59
	v_add_f32_e32 v164, v222, v164
	v_cvt_pk_bf16_f32 v218, v222, v223
	v_add_f32_e32 v164, v223, v164
	s_waitcnt lgkmcnt(3)
	v_mfma_f32_32x32x16_bf16 v[98:113], v[186:189], v[134:137], v[98:113]
	ds_read_b128 v[182:185], v181 offset:44576
	v_exp_f32_e32 v224, v60
	v_exp_f32_e32 v225, v61
	v_add_f32_e32 v164, v224, v164
	v_cvt_pk_bf16_f32 v219, v224, v225
	v_add_f32_e32 v164, v225, v164
	s_waitcnt lgkmcnt(3)
	v_mfma_f32_32x32x16_bf16 v[2:17], v[190:193], v[206:209], v[2:17]
	ds_read_b128 v[186:189], v181 offset:40000
	v_exp_f32_e32 v222, v62
	v_exp_f32_e32 v223, v63
	v_add_f32_e32 v164, v222, v164
	v_cvt_pk_bf16_f32 v220, v222, v223
	v_add_f32_e32 v164, v223, v164
	s_waitcnt lgkmcnt(3)
	v_mfma_f32_32x32x16_bf16 v[18:33], v[194:197], v[206:209], v[18:33]
	ds_read_b128 v[190:193], v181 offset:44608
	v_exp_f32_e32 v224, v64
	v_exp_f32_e32 v225, v65
	v_add_f32_e32 v164, v224, v164
	v_cvt_pk_bf16_f32 v221, v224, v225
	v_add_f32_e32 v164, v225, v164
	s_mov_b32 s13, s20
	s_mov_b32 s20, s19
	s_add_i32 s19, s19, 1
	s_cmp_eq_u32 s19, s9
	s_cselect_b32 s19, 0, s19
	s_waitcnt lgkmcnt(3)
	v_mfma_f32_32x32x16_bf16 v[2:17], v[198:201], v[210:213], v[2:17]
	ds_read_b128 v[194:197], v181 offset:40032
	v_max3_f32 v224, v82, v83, v84
	v_max3_f32 v225, v98, v99, v100
	v_max3_f32 v224, v224, v85, v86
	v_max3_f32 v225, v225, v101, v102
	s_waitcnt vmcnt(2)
	v_add_u32_e32 v222, 0xb000, v172
	ds_write_b128 v222, v[146:149] offset:26624
	v_lshl_add_u32 v222, s19, 17, v178
	global_load_dwordx4 v[146:149], v222, s[52:53]
	s_waitcnt lgkmcnt(4)
	v_mfma_f32_32x32x16_bf16 v[18:33], v[182:185], v[210:213], v[18:33]
	ds_read_b128 v[198:201], v181 offset:44640
	v_max3_f32 v224, v224, v87, v88
	v_max3_f32 v225, v225, v103, v104
	v_max3_f32 v224, v224, v89, v90
	v_max3_f32 v225, v225, v105, v106
	s_and_b64 vcc, exec, s[2:3]
	s_cbranch_vccz .Lmla_p10_nope
	v_add_u32_e32 v222, 0xb000, v176
	ds_write_b128 v222, v[138:141] offset:26752
	v_lshl_add_u32 v222, s19, 12, v179
	global_load_dwordx4 v[138:141], v222, s[62:63]
.Lmla_p10_nope:
	s_waitcnt lgkmcnt(4)
	v_mfma_f32_32x32x16_bf16 v[2:17], v[186:189], v[214:217], v[2:17]
	ds_read_b128 v[182:185], v174 offset:45056
	v_max3_f32 v224, v224, v91, v92
	v_max3_f32 v225, v225, v107, v108
	v_max3_f32 v224, v224, v93, v94
	v_max3_f32 v225, v225, v109, v110
	ds_write_b128 v173, v[142:145] offset:13312
	v_lshl_add_u32 v222, s13, 7, v168
	global_load_dwordx4 v[142:145], v222, s[56:57]
	s_waitcnt lgkmcnt(5)
	v_mfma_f32_32x32x16_bf16 v[18:33], v[190:193], v[214:217], v[18:33]
	ds_read_b128 v[186:189], v174 offset:51712
	v_max3_f32 v224, v224, v95, v96
	v_max3_f32 v225, v225, v111, v112
	v_max3_f32 v224, v224, v97, v113
	v_max_f32_e32 v224, v224, v225
	s_waitcnt lgkmcnt(5)
	v_mfma_f32_32x32x16_bf16 v[2:17], v[194:197], v[218:221], v[2:17]
	ds_read_b128 v[190:193], v174 offset:45088
	v_mov_b32_e32 v225, v224
	v_add_f32_e32 v1, v1, v164
	s_add_i32 s11, s11, 1
	v_permlane32_swap_b32_e32 v224, v225
	s_cmp_eq_u32 s9, s11
	v_max_f32_e32 v167, v224, v225
	s_waitcnt lgkmcnt(4)
	v_mfma_f32_32x32x16_bf16 v[18:33], v[198:201], v[218:221], v[18:33]
	ds_read_b128 v[194:197], v174 offset:51744
	v_cmp_lt_f32_e32 vcc, s66, v167
	s_cbranch_scc1 .Lmla_exit_p10

; template <int VAR>
; __device__ __forceinline__ void attn_phase(LAS unsigned char* lds, const AttnP P, int vcu, int G, int wave_s) {
;     ...
;                 if (ND0 == 6) {
;                     KR1(0); KR1(1); KR1(2); KR1(3); SB();
;                     QK1(0, negm); EX2(pc0, 0, w0.x); KR1(4); SB();
;                     QK1(1, negm); EX2(pc0, 2, w0.y); KR1(5); SB();
;                     QK1(2, pn0); EX2(pc0, 4, w0.z); KR1(6); SB();
;                     QK1(3, pn1); EX2(pc0, 6, w0.w); KR1(7); SB();
;                     QK1(4, pn0); EX2(pc0, 8, w1.x); KR1(8); SB();
;                     QK1(5, pn1); EX2(pc0, 10, w1.y); KR1(9); SB();
;                     QK1(6, pn0); EX2(pc0, 12, w1.z); KR1(10); SB();
;                     QK1(7, pn1); EX2(pc0, 14, w1.w); KR1(11); SB();
;                     QK1(8, pn0); EX2(pc1, 0, w2.x); VR1(0); SB();
;                     QK1(9, pn1); EX2(pc1, 2, w2.y); VR1(1); SB();
;                     QK1(10, pn0); EX2(pc1, 4, w2.z); VR1(2); SB();
;                     QK1(11, pn1); EX2(pc1, 6, w2.w); VR1(3); SB();
;                 } else {
;                     KR1(0); KR1(1); KR1(2); KR1(3); SB();
;                     QK1(0, negm); EX2(pc0, 0, w0.x); EX2(pc0, 2, w0.y); KR1(4); SB();
;                     QK1(1, negm); EX2(pc0, 4, w0.z); EX2(pc0, 6, w0.w); KR1(5); SB();
;                     QK1(2, pn0); EX2(pc0, 8, w1.x); EX2(pc0, 10, w1.y); KR1(6); SB();
;                     QK1(3, pn1); EX2(pc0, 12, w1.z); EX2(pc0, 14, w1.w); KR1(7); SB();
;                     QK1(4, pn0); EX2(pc1, 0, w2.x); VR1(0); SB();
;                     QK1(5, pn1); EX2(pc1, 2, w2.y); VR1(1); SB();
;                     QK1(6, pn0); EX2(pc1, 4, w2.z); VR1(2); SB();
;                     QK1(7, pn1); EX2(pc1, 6, w2.w); VR1(3); SB();
;                 }
;                 PV1(0, w0); EX2(pc1, 8, w3.x); VR1(4); SB();
;                 PV1(1, w0); EX2(pc1, 10, w3.y); VR1(5); SB();
;                 PV1(2, w1); EX2(pc1, 12, w3.z); VR1(6); SB();
;                 PV1(3, w1); EX2(pc1, 14, w3.w); VR1(7); SB();
;                 lrun += sacc;
;                 PV1(4, w2); MASK_TILE(pn0, pn1, t + 1); SB();
;                 PV1(5, w2); SB();
;                 PV1(6, w3); SB();
;                 PV1(7, w3); rmn = rowmax32(pn0, pn1); if (!USE_NEGM) rmn -= mref; SB();
;     ...
;             if (hn) { STOREK(t & 1); STOREV((t + 1) & 1); }
;             __syncthreads();
.Lmla_p11_go:
	v_exp_f32_e32 v222, v82
	v_exp_f32_e32 v223, v83
	v_add_f32_e32 v164, 0, v222
	v_cvt_pk_bf16_f32 v206, v222, v223
	v_add_f32_e32 v164, v223, v164
	v_exp_f32_e32 v224, v84
	v_exp_f32_e32 v225, v85
	v_add_f32_e32 v164, v224, v164
	v_cvt_pk_bf16_f32 v207, v224, v225
	v_add_f32_e32 v164, v225, v164
	s_waitcnt lgkmcnt(4)
	v_mfma_f32_32x32x16_bf16 v[34:49], v[182:185], v[114:117], v[66:81]
	ds_read_b128 v[198:201], v174 offset:45120
	v_exp_f32_e32 v222, v86
	v_exp_f32_e32 v223, v87
	v_add_f32_e32 v164, v222, v164
	v_cvt_pk_bf16_f32 v208, v222, v223
	v_add_f32_e32 v164, v223, v164
	s_waitcnt lgkmcnt(3)
	v_mfma_f32_32x32x16_bf16 v[50:65], v[186:189], v[114:117], v[66:81]
	ds_read_b128 v[182:185], v174 offset:51776
	v_exp_f32_e32 v224, v88
	v_exp_f32_e32 v225, v89
	v_add_f32_e32 v164, v224, v164
	v_cvt_pk_bf16_f32 v209, v224, v225
	v_add_f32_e32 v164, v225, v164
	s_waitcnt lgkmcnt(3)
	v_mfma_f32_32x32x16_bf16 v[34:49], v[190:193], v[118:121], v[34:49]
	ds_read_b128 v[186:189], v174 offset:45152
	v_exp_f32_e32 v222, v90
	v_exp_f32_e32 v223, v91
	v_add_f32_e32 v164, v222, v164
	v_cvt_pk_bf16_f32 v210, v222, v223
	v_add_f32_e32 v164, v223, v164
	s_waitcnt lgkmcnt(3)
	v_mfma_f32_32x32x16_bf16 v[50:65], v[194:197], v[118:121], v[50:65]
	ds_read_b128 v[190:193], v174 offset:51808
	v_exp_f32_e32 v224, v92
	v_exp_f32_e32 v225, v93
	v_add_f32_e32 v164, v224, v164
	v_cvt_pk_bf16_f32 v211, v224, v225
	v_add_f32_e32 v164, v225, v164
	s_waitcnt lgkmcnt(3)
	v_mfma_f32_32x32x16_bf16 v[34:49], v[198:201], v[122:125], v[34:49]
	ds_read_b128 v[194:197], v174 offset:45184
	v_exp_f32_e32 v222, v94
	v_exp_f32_e32 v223, v95
	v_add_f32_e32 v164, v222, v164
	v_cvt_pk_bf16_f32 v212, v222, v223
	v_add_f32_e32 v164, v223, v164
	s_waitcnt lgkmcnt(3)
	v_mfma_f32_32x32x16_bf16 v[50:65], v[182:185], v[122:125], v[50:65]
	ds_read_b128 v[198:201], v174 offset:51840
	v_exp_f32_e32 v224, v96
	v_exp_f32_e32 v225, v97
	v_add_f32_e32 v164, v224, v164
	v_cvt_pk_bf16_f32 v213, v224, v225
	v_add_f32_e32 v164, v225, v164
	s_waitcnt lgkmcnt(3)
	v_mfma_f32_32x32x16_bf16 v[34:49], v[186:189], v[126:129], v[34:49]
	ds_read_b128 v[182:185], v174 offset:45216
	v_exp_f32_e32 v222, v98
	v_exp_f32_e32 v223, v99
	v_add_f32_e32 v164, v222, v164
	v_cvt_pk_bf16_f32 v214, v222, v223
	v_add_f32_e32 v164, v223, v164
	s_waitcnt lgkmcnt(3)
	v_mfma_f32_32x32x16_bf16 v[50:65], v[190:193], v[126:129], v[50:65]
	ds_read_b128 v[186:189], v174 offset:51872
	v_exp_f32_e32 v224, v100
	v_exp_f32_e32 v225, v101
	v_add_f32_e32 v164, v224, v164
	v_cvt_pk_bf16_f32 v215, v224, v225
	v_add_f32_e32 v164, v225, v164
	s_waitcnt lgkmcnt(3)
	v_mfma_f32_32x32x16_bf16 v[34:49], v[194:197], v[130:133], v[34:49]
	ds_read_b128 v[190:193], v181 offset:49152
	v_exp_f32_e32 v222, v102
	v_exp_f32_e32 v223, v103
	v_add_f32_e32 v164, v222, v164
	v_cvt_pk_bf16_f32 v216, v222, v223
	v_add_f32_e32 v164, v223, v164
	s_waitcnt lgkmcnt(3)
	v_mfma_f32_32x32x16_bf16 v[50:65], v[198:201], v[130:133], v[50:65]
	ds_read_b128 v[194:197], v181 offset:53760
	v_exp_f32_e32 v224, v104
	v_exp_f32_e32 v225, v105
	v_add_f32_e32 v164, v224, v164
	v_cvt_pk_bf16_f32 v217, v224, v225
	v_add_f32_e32 v164, v225, v164
	s_waitcnt lgkmcnt(3)
	v_mfma_f32_32x32x16_bf16 v[34:49], v[182:185], v[134:137], v[34:49]
	ds_read_b128 v[198:201], v181 offset:49184
	v_exp_f32_e32 v222, v106
	v_exp_f32_e32 v223, v107
	v_add_f32_e32 v164, v222, v164
	v_cvt_pk_bf16_f32 v218, v222, v223
	v_add_f32_e32 v164, v223, v164
	s_waitcnt lgkmcnt(3)
	v_mfma_f32_32x32x16_bf16 v[50:65], v[186:189], v[134:137], v[50:65]
	ds_read_b128 v[182:185], v181 offset:53792
	v_exp_f32_e32 v224, v108
	v_exp_f32_e32 v225, v109
	v_add_f32_e32 v164, v224, v164
	v_cvt_pk_bf16_f32 v219, v224, v225
	v_add_f32_e32 v164, v225, v164
	s_waitcnt lgkmcnt(3)
	v_mfma_f32_32x32x16_bf16 v[2:17], v[190:193], v[206:209], v[2:17]
	ds_read_b128 v[186:189], v181 offset:49216
	v_exp_f32_e32 v222, v110
	v_exp_f32_e32 v223, v111
	v_add_f32_e32 v164, v222, v164
	v_cvt_pk_bf16_f32 v220, v222, v223
	v_add_f32_e32 v164, v223, v164
	s_waitcnt lgkmcnt(3)
	v_mfma_f32_32x32x16_bf16 v[18:33], v[194:197], v[206:209], v[18:33]
	ds_read_b128 v[190:193], v181 offset:53824
	v_exp_f32_e32 v224, v112
	v_exp_f32_e32 v225, v113
	v_add_f32_e32 v164, v224, v164
	v_cvt_pk_bf16_f32 v221, v224, v225
	v_add_f32_e32 v164, v225, v164
	s_mov_b32 s13, s20
	s_mov_b32 s20, s19
	s_add_i32 s19, s19, 1
	s_cmp_eq_u32 s19, s9
	s_cselect_b32 s19, 0, s19
	s_waitcnt lgkmcnt(3)
	v_mfma_f32_32x32x16_bf16 v[2:17], v[198:201], v[210:213], v[2:17]
	ds_read_b128 v[194:197], v181 offset:49248
	v_max3_f32 v224, v34, v35, v36
	v_max3_f32 v225, v50, v51, v52
	v_max3_f32 v224, v224, v37, v38
	v_max3_f32 v225, v225, v53, v54
	s_waitcnt vmcnt(2)
	ds_write_b128 v172, v[150:153]
	v_lshl_add_u32 v222, s19, 17, v178
	global_load_dwordx4 v[150:153], v222, s[52:53]
	s_waitcnt lgkmcnt(4)
	v_mfma_f32_32x32x16_bf16 v[18:33], v[182:185], v[210:213], v[18:33]
	ds_read_b128 v[198:201], v181 offset:53856
	v_max3_f32 v224, v224, v39, v40
	v_max3_f32 v225, v225, v55, v56
	v_max3_f32 v224, v224, v41, v42
	v_max3_f32 v225, v225, v57, v58
	s_and_b64 vcc, exec, s[2:3]
	s_cbranch_vccz .Lmla_p11_nope
	ds_write_b128 v176, v[160:163] offset:128
	v_lshl_add_u32 v222, s19, 12, v179
	global_load_dwordx4 v[160:163], v222, s[62:63]
.Lmla_p11_nope:
	s_waitcnt lgkmcnt(4)
	v_mfma_f32_32x32x16_bf16 v[2:17], v[186:189], v[214:217], v[2:17]
	ds_read_b128 v[182:185], v229 offset:13312
	v_max3_f32 v224, v224, v43, v44
	v_max3_f32 v225, v225, v59, v60
	v_max3_f32 v224, v224, v45, v46
	v_max3_f32 v225, v225, v61, v62
	ds_write_b128 v173, v[202:205] offset:35840
	v_lshl_add_u32 v222, s13, 7, v168
	global_load_dwordx4 v[202:205], v222, s[56:57]
	s_waitcnt lgkmcnt(5)
	v_mfma_f32_32x32x16_bf16 v[18:33], v[190:193], v[214:217], v[18:33]
	ds_read_b128 v[186:189], v229 offset:19968
	v_max3_f32 v224, v224, v47, v48
	v_max3_f32 v225, v225, v63, v64
	v_max3_f32 v224, v224, v49, v65
	v_max_f32_e32 v224, v224, v225
	s_waitcnt lgkmcnt(5)
	v_mfma_f32_32x32x16_bf16 v[2:17], v[194:197], v[218:221], v[2:17]
	ds_read_b128 v[190:193], v229 offset:13344
	v_mov_b32_e32 v225, v224
	v_add_f32_e32 v1, v1, v164
	s_add_i32 s11, s11, 1
	v_permlane32_swap_b32_e32 v224, v225
	s_cmp_eq_u32 s9, s11
	v_max_f32_e32 v167, v224, v225
	s_waitcnt lgkmcnt(4)
	v_mfma_f32_32x32x16_bf16 v[18:33], v[198:201], v[218:221], v[18:33]
	ds_read_b128 v[194:197], v229 offset:20000
	v_cmp_lt_f32_e32 vcc, s66, v167
	s_waitcnt lgkmcnt(3)
	s_barrier
	s_cbranch_scc1 .Lmla_exit_p11

; template <int VAR>
; __device__ __forceinline__ void attn_phase(LAS unsigned char* lds, const AttnP P, int vcu, int G, int wave_s) {
;     ...
;                 if (ND0 == 6) {
;                     KR1(0); KR1(1); KR1(2); KR1(3); SB();
;                     QK1(0, negm); EX2(pc0, 0, w0.x); KR1(4); SB();
;                     QK1(1, negm); EX2(pc0, 2, w0.y); KR1(5); SB();
;                     QK1(2, pn0); EX2(pc0, 4, w0.z); KR1(6); SB();
;                     QK1(3, pn1); EX2(pc0, 6, w0.w); KR1(7); SB();
;                     QK1(4, pn0); EX2(pc0, 8, w1.x); KR1(8); SB();
;                     QK1(5, pn1); EX2(pc0, 10, w1.y); KR1(9); SB();
;                     QK1(6, pn0); EX2(pc0, 12, w1.z); KR1(10); SB();
;                     QK1(7, pn1); EX2(pc0, 14, w1.w); KR1(11); SB();
;                     QK1(8, pn0); EX2(pc1, 0, w2.x); VR1(0); SB();
;                     QK1(9, pn1); EX2(pc1, 2, w2.y); VR1(1); SB();
;                     QK1(10, pn0); EX2(pc1, 4, w2.z); VR1(2); SB();
;                     QK1(11, pn1); EX2(pc1, 6, w2.w); VR1(3); SB();
;                 } else {
;                     KR1(0); KR1(1); KR1(2); KR1(3); SB();
;                     QK1(0, negm); EX2(pc0, 0, w0.x); EX2(pc0, 2, w0.y); KR1(4); SB();
;                     QK1(1, negm); EX2(pc0, 4, w0.z); EX2(pc0, 6, w0.w); KR1(5); SB();
;                     QK1(2, pn0); EX2(pc0, 8, w1.x); EX2(pc0, 10, w1.y); KR1(6); SB();
;                     QK1(3, pn1); EX2(pc0, 12, w1.z); EX2(pc0, 14, w1.w); KR1(7); SB();
;                     QK1(4, pn0); EX2(pc1, 0, w2.x); VR1(0); SB();
;                     QK1(5, pn1); EX2(pc1, 2, w2.y); VR1(1); SB();
;                     QK1(6, pn0); EX2(pc1, 4, w2.z); VR1(2); SB();
;                     QK1(7, pn1); EX2(pc1, 6, w2.w); VR1(3); SB();
;                 }
;                 PV1(0, w0); EX2(pc1, 8, w3.x); VR1(4); SB();
;                 PV1(1, w0); EX2(pc1, 10, w3.y); VR1(5); SB();
;                 PV1(2, w1); EX2(pc1, 12, w3.z); VR1(6); SB();
;                 PV1(3, w1); EX2(pc1, 14, w3.w); VR1(7); SB();
;                 lrun += sacc;
;                 PV1(4, w2); MASK_TILE(pn0, pn1, t + 1); SB();
;                 PV1(5, w2); SB();
;                 PV1(6, w3); SB();
;                 PV1(7, w3); rmn = rowmax32(pn0, pn1); if (!USE_NEGM) rmn -= mref; SB();
;     ...
;             if (hn) { STOREK(t & 1); STOREV((t + 1) & 1); }
;             __syncthreads();
.Lmla_p12_go:
	v_exp_f32_e32 v222, v34
	v_exp_f32_e32 v223, v35
	v_add_f32_e32 v164, 0, v222
	v_cvt_pk_bf16_f32 v206, v222, v223
	v_add_f32_e32 v164, v223, v164
	v_exp_f32_e32 v224, v36
	v_exp_f32_e32 v225, v37
	v_add_f32_e32 v164, v224, v164
	v_cvt_pk_bf16_f32 v207, v224, v225
	v_add_f32_e32 v164, v225, v164
	s_waitcnt lgkmcnt(3)
	v_mfma_f32_32x32x16_bf16 v[82:97], v[182:185], v[114:117], v[66:81]
	ds_read_b128 v[198:201], v229 offset:13376
	v_exp_f32_e32 v222, v38
	v_exp_f32_e32 v223, v39
	v_add_f32_e32 v164, v222, v164
	v_cvt_pk_bf16_f32 v208, v222, v223
	v_add_f32_e32 v164, v223, v164
	s_waitcnt lgkmcnt(3)
	v_mfma_f32_32x32x16_bf16 v[98:113], v[186:189], v[114:117], v[66:81]
	ds_read_b128 v[182:185], v229 offset:20032
	v_exp_f32_e32 v224, v40
	v_exp_f32_e32 v225, v41
	v_add_f32_e32 v164, v224, v164
	v_cvt_pk_bf16_f32 v209, v224, v225
	v_add_f32_e32 v164, v225, v164
	s_waitcnt lgkmcnt(3)
	v_mfma_f32_32x32x16_bf16 v[82:97], v[190:193], v[118:121], v[82:97]
	ds_read_b128 v[186:189], v229 offset:13408
	v_exp_f32_e32 v222, v42
	v_exp_f32_e32 v223, v43
	v_add_f32_e32 v164, v222, v164
	v_cvt_pk_bf16_f32 v210, v222, v223
	v_add_f32_e32 v164, v223, v164
	s_waitcnt lgkmcnt(3)
	v_mfma_f32_32x32x16_bf16 v[98:113], v[194:197], v[118:121], v[98:113]
	ds_read_b128 v[190:193], v229 offset:20064
	v_exp_f32_e32 v224, v44
	v_exp_f32_e32 v225, v45
	v_add_f32_e32 v164, v224, v164
	v_cvt_pk_bf16_f32 v211, v224, v225
	v_add_f32_e32 v164, v225, v164
	s_waitcnt lgkmcnt(3)
	v_mfma_f32_32x32x16_bf16 v[82:97], v[198:201], v[122:125], v[82:97]
	ds_read_b128 v[194:197], v229 offset:13440
	v_exp_f32_e32 v222, v46
	v_exp_f32_e32 v223, v47
	v_add_f32_e32 v164, v222, v164
	v_cvt_pk_bf16_f32 v212, v222, v223
	v_add_f32_e32 v164, v223, v164
	s_waitcnt lgkmcnt(3)
	v_mfma_f32_32x32x16_bf16 v[98:113], v[182:185], v[122:125], v[98:113]
	ds_read_b128 v[198:201], v229 offset:20096
	v_exp_f32_e32 v224, v48
	v_exp_f32_e32 v225, v49
	v_add_f32_e32 v164, v224, v164
	v_cvt_pk_bf16_f32 v213, v224, v225
	v_add_f32_e32 v164, v225, v164
	s_waitcnt lgkmcnt(3)
	v_mfma_f32_32x32x16_bf16 v[82:97], v[186:189], v[126:129], v[82:97]
	ds_read_b128 v[182:185], v229 offset:13472
	v_exp_f32_e32 v222, v50
	v_exp_f32_e32 v223, v51
	v_add_f32_e32 v164, v222, v164
	v_cvt_pk_bf16_f32 v214, v222, v223
	v_add_f32_e32 v164, v223, v164
	s_waitcnt lgkmcnt(3)
	v_mfma_f32_32x32x16_bf16 v[98:113], v[190:193], v[126:129], v[98:113]
	ds_read_b128 v[186:189], v229 offset:20128
	v_exp_f32_e32 v224, v52
	v_exp_f32_e32 v225, v53
	v_add_f32_e32 v164, v224, v164
	v_cvt_pk_bf16_f32 v215, v224, v225
	v_add_f32_e32 v164, v225, v164
	s_waitcnt lgkmcnt(3)
	v_mfma_f32_32x32x16_bf16 v[82:97], v[194:197], v[130:133], v[82:97]
	ds_read_b128 v[190:193], v228 offset:13312
	v_exp_f32_e32 v222, v54
	v_exp_f32_e32 v223, v55
	v_add_f32_e32 v164, v222, v164
	v_cvt_pk_bf16_f32 v216, v222, v223
	v_add_f32_e32 v164, v223, v164
	s_waitcnt lgkmcnt(3)
	v_mfma_f32_32x32x16_bf16 v[98:113], v[198:201], v[130:133], v[98:113]
	ds_read_b128 v[194:197], v228 offset:17920
	v_exp_f32_e32 v224, v56
	v_exp_f32_e32 v225, v57
	v_add_f32_e32 v164, v224, v164
	v_cvt_pk_bf16_f32 v217, v224, v225
	v_add_f32_e32 v164, v225, v164
	s_waitcnt lgkmcnt(3)
	v_mfma_f32_32x32x16_bf16 v[82:97], v[182:185], v[134:137], v[82:97]
	ds_read_b128 v[198:201], v228 offset:13344
	v_exp_f32_e32 v222, v58
	v_exp_f32_e32 v223, v59
	v_add_f32_e32 v164, v222, v164
	v_cvt_pk_bf16_f32 v218, v222, v223
	v_add_f32_e32 v164, v223, v164
	s_waitcnt lgkmcnt(3)
	v_mfma_f32_32x32x16_bf16 v[98:113], v[186:189], v[134:137], v[98:113]
	ds_read_b128 v[182:185], v228 offset:17952
	v_exp_f32_e32 v224, v60
	v_exp_f32_e32 v225, v61
	v_add_f32_e32 v164, v224, v164
	v_cvt_pk_bf16_f32 v219, v224, v225
	v_add_f32_e32 v164, v225, v164
	s_waitcnt lgkmcnt(3)
	v_mfma_f32_32x32x16_bf16 v[2:17], v[190:193], v[206:209], v[2:17]
	ds_read_b128 v[186:189], v228 offset:13376
	v_exp_f32_e32 v222, v62
	v_exp_f32_e32 v223, v63
	v_add_f32_e32 v164, v222, v164
	v_cvt_pk_bf16_f32 v220, v222, v223
	v_add_f32_e32 v164, v223, v164
	s_waitcnt lgkmcnt(3)
	v_mfma_f32_32x32x16_bf16 v[18:33], v[194:197], v[206:209], v[18:33]
	ds_read_b128 v[190:193], v228 offset:17984
	v_exp_f32_e32 v224, v64
	v_exp_f32_e32 v225, v65
	v_add_f32_e32 v164, v224, v164
	v_cvt_pk_bf16_f32 v221, v224, v225
	v_add_f32_e32 v164, v225, v164
	s_mov_b32 s13, s20
	s_mov_b32 s20, s19
	s_add_i32 s19, s19, 1
	s_cmp_eq_u32 s19, s9
	s_cselect_b32 s19, 0, s19
	s_waitcnt lgkmcnt(3)
	v_mfma_f32_32x32x16_bf16 v[2:17], v[198:201], v[210:213], v[2:17]
	ds_read_b128 v[194:197], v228 offset:13408
	v_max3_f32 v224, v82, v83, v84
	v_max3_f32 v225, v98, v99, v100
	v_max3_f32 v224, v224, v85, v86
	v_max3_f32 v225, v225, v101, v102
	s_waitcnt vmcnt(2)
	ds_write_b128 v172, v[146:149] offset:22528
	v_lshl_add_u32 v222, s19, 17, v178
	global_load_dwordx4 v[146:149], v222, s[52:53]
	s_waitcnt lgkmcnt(4)
	v_mfma_f32_32x32x16_bf16 v[18:33], v[182:185], v[210:213], v[18:33]
	ds_read_b128 v[198:201], v228 offset:18016
	v_max3_f32 v224, v224, v87, v88
	v_max3_f32 v225, v225, v103, v104
	v_max3_f32 v224, v224, v89, v90
	v_max3_f32 v225, v225, v105, v106
	s_and_b64 vcc, exec, s[2:3]
	s_cbranch_vccz .Lmla_p12_nope
	ds_write_b128 v176, v[138:141] offset:22656
	v_lshl_add_u32 v222, s19, 12, v179
	global_load_dwordx4 v[138:141], v222, s[62:63]
.Lmla_p12_nope:
	s_waitcnt lgkmcnt(4)
	v_mfma_f32_32x32x16_bf16 v[2:17], v[186:189], v[214:217], v[2:17]
	ds_read_b128 v[182:185], v229 offset:26624
	v_max3_f32 v224, v224, v91, v92
	v_max3_f32 v225, v225, v107, v108
	v_max3_f32 v224, v224, v93, v94
	v_max3_f32 v225, v225, v109, v110
	v_add_u32_e32 v222, 0xb000, v173
	ds_write_b128 v222, v[142:145] offset:39936
	v_lshl_add_u32 v222, s13, 7, v168
	global_load_dwordx4 v[142:145], v222, s[56:57]
	s_waitcnt lgkmcnt(5)
	v_mfma_f32_32x32x16_bf16 v[18:33], v[190:193], v[214:217], v[18:33]
	ds_read_b128 v[186:189], v229 offset:33280
	v_max3_f32 v224, v224, v95, v96
	v_max3_f32 v225, v225, v111, v112
	v_max3_f32 v224, v224, v97, v113
	v_max_f32_e32 v224, v224, v225
	s_waitcnt lgkmcnt(5)
	v_mfma_f32_32x32x16_bf16 v[2:17], v[194:197], v[218:221], v[2:17]
	ds_read_b128 v[190:193], v229 offset:26656
	v_mov_b32_e32 v225, v224
	v_add_f32_e32 v1, v1, v164
	s_add_i32 s11, s11, 1
	v_permlane32_swap_b32_e32 v224, v225
	s_cmp_eq_u32 s9, s11
	v_max_f32_e32 v167, v224, v225
	s_waitcnt lgkmcnt(4)
	v_mfma_f32_32x32x16_bf16 v[18:33], v[198:201], v[218:221], v[18:33]
	ds_read_b128 v[194:197], v229 offset:33312
	v_cmp_lt_f32_e32 vcc, s66, v167
	s_cbranch_scc1 .Lmla_exit_p12

; template <int VAR>
; __device__ __forceinline__ void attn_phase(LAS unsigned char* lds, const AttnP P, int vcu, int G, int wave_s) {
;     ...
;                 if (ND0 == 6) {
;                     KR1(0); KR1(1); KR1(2); KR1(3); SB();
;                     QK1(0, negm); EX2(pc0, 0, w0.x); KR1(4); SB();
;                     QK1(1, negm); EX2(pc0, 2, w0.y); KR1(5); SB();
;                     QK1(2, pn0); EX2(pc0, 4, w0.z); KR1(6); SB();
;                     QK1(3, pn1); EX2(pc0, 6, w0.w); KR1(7); SB();
;                     QK1(4, pn0); EX2(pc0, 8, w1.x); KR1(8); SB();
;                     QK1(5, pn1); EX2(pc0, 10, w1.y); KR1(9); SB();
;                     QK1(6, pn0); EX2(pc0, 12, w1.z); KR1(10); SB();
;                     QK1(7, pn1); EX2(pc0, 14, w1.w); KR1(11); SB();
;                     QK1(8, pn0); EX2(pc1, 0, w2.x); VR1(0); SB();
;                     QK1(9, pn1); EX2(pc1, 2, w2.y); VR1(1); SB();
;                     QK1(10, pn0); EX2(pc1, 4, w2.z); VR1(2); SB();
;                     QK1(11, pn1); EX2(pc1, 6, w2.w); VR1(3); SB();
;                 } else {
;                     KR1(0); KR1(1); KR1(2); KR1(3); SB();
;                     QK1(0, negm); EX2(pc0, 0, w0.x); EX2(pc0, 2, w0.y); KR1(4); SB();
;                     QK1(1, negm); EX2(pc0, 4, w0.z); EX2(pc0, 6, w0.w); KR1(5); SB();
;                     QK1(2, pn0); EX2(pc0, 8, w1.x); EX2(pc0, 10, w1.y); KR1(6); SB();
;                     QK1(3, pn1); EX2(pc0, 12, w1.z); EX2(pc0, 14, w1.w); KR1(7); SB();
;                     QK1(4, pn0); EX2(pc1, 0, w2.x); VR1(0); SB();
;                     QK1(5, pn1); EX2(pc1, 2, w2.y); VR1(1); SB();
;                     QK1(6, pn0); EX2(pc1, 4, w2.z); VR1(2); SB();
;                     QK1(7, pn1); EX2(pc1, 6, w2.w); VR1(3); SB();
;                 }
;                 PV1(0, w0); EX2(pc1, 8, w3.x); VR1(4); SB();
;                 PV1(1, w0); EX2(pc1, 10, w3.y); VR1(5); SB();
;                 PV1(2, w1); EX2(pc1, 12, w3.z); VR1(6); SB();
;                 PV1(3, w1); EX2(pc1, 14, w3.w); VR1(7); SB();
;                 lrun += sacc;
;                 PV1(4, w2); MASK_TILE(pn0, pn1, t + 1); SB();
;                 PV1(5, w2); SB();
;                 PV1(6, w3); SB();
;                 PV1(7, w3); rmn = rowmax32(pn0, pn1); if (!USE_NEGM) rmn -= mref; SB();
;     ...
;             if (hn) { STOREK(t & 1); STOREV((t + 1) & 1); }
;             __syncthreads();
.Lmla_p13_go:
	v_exp_f32_e32 v222, v82
	v_exp_f32_e32 v223, v83
	v_add_f32_e32 v164, 0, v222
	v_cvt_pk_bf16_f32 v206, v222, v223
	v_add_f32_e32 v164, v223, v164
	v_exp_f32_e32 v224, v84
	v_exp_f32_e32 v225, v85
	v_add_f32_e32 v164, v224, v164
	v_cvt_pk_bf16_f32 v207, v224, v225
	v_add_f32_e32 v164, v225, v164
	s_waitcnt lgkmcnt(4)
	v_mfma_f32_32x32x16_bf16 v[34:49], v[182:185], v[114:117], v[66:81]
	ds_read_b128 v[198:201], v229 offset:26688
	v_exp_f32_e32 v222, v86
	v_exp_f32_e32 v223, v87
	v_add_f32_e32 v164, v222, v164
	v_cvt_pk_bf16_f32 v208, v222, v223
	v_add_f32_e32 v164, v223, v164
	s_waitcnt lgkmcnt(3)
	v_mfma_f32_32x32x16_bf16 v[50:65], v[186:189], v[114:117], v[66:81]
	ds_read_b128 v[182:185], v229 offset:33344
	v_exp_f32_e32 v224, v88
	v_exp_f32_e32 v225, v89
	v_add_f32_e32 v164, v224, v164
	v_cvt_pk_bf16_f32 v209, v224, v225
	v_add_f32_e32 v164, v225, v164
	s_waitcnt lgkmcnt(3)
	v_mfma_f32_32x32x16_bf16 v[34:49], v[190:193], v[118:121], v[34:49]
	ds_read_b128 v[186:189], v229 offset:26720
	v_exp_f32_e32 v222, v90
	v_exp_f32_e32 v223, v91
	v_add_f32_e32 v164, v222, v164
	v_cvt_pk_bf16_f32 v210, v222, v223
	v_add_f32_e32 v164, v223, v164
	s_waitcnt lgkmcnt(3)
	v_mfma_f32_32x32x16_bf16 v[50:65], v[194:197], v[118:121], v[50:65]
	ds_read_b128 v[190:193], v229 offset:33376
	v_exp_f32_e32 v224, v92
	v_exp_f32_e32 v225, v93
	v_add_f32_e32 v164, v224, v164
	v_cvt_pk_bf16_f32 v211, v224, v225
	v_add_f32_e32 v164, v225, v164
	s_waitcnt lgkmcnt(3)
	v_mfma_f32_32x32x16_bf16 v[34:49], v[198:201], v[122:125], v[34:49]
	ds_read_b128 v[194:197], v229 offset:26752
	v_exp_f32_e32 v222, v94
	v_exp_f32_e32 v223, v95
	v_add_f32_e32 v164, v222, v164
	v_cvt_pk_bf16_f32 v212, v222, v223
	v_add_f32_e32 v164, v223, v164
	s_waitcnt lgkmcnt(3)
	v_mfma_f32_32x32x16_bf16 v[50:65], v[182:185], v[122:125], v[50:65]
	ds_read_b128 v[198:201], v229 offset:33408
	v_exp_f32_e32 v224, v96
	v_exp_f32_e32 v225, v97
	v_add_f32_e32 v164, v224, v164
	v_cvt_pk_bf16_f32 v213, v224, v225
	v_add_f32_e32 v164, v225, v164
	s_waitcnt lgkmcnt(3)
	v_mfma_f32_32x32x16_bf16 v[34:49], v[186:189], v[126:129], v[34:49]
	ds_read_b128 v[182:185], v229 offset:26784
	v_exp_f32_e32 v222, v98
	v_exp_f32_e32 v223, v99
	v_add_f32_e32 v164, v222, v164
	v_cvt_pk_bf16_f32 v214, v222, v223
	v_add_f32_e32 v164, v223, v164
	s_waitcnt lgkmcnt(3)
	v_mfma_f32_32x32x16_bf16 v[50:65], v[190:193], v[126:129], v[50:65]
	ds_read_b128 v[186:189], v229 offset:33440
	v_exp_f32_e32 v224, v100
	v_exp_f32_e32 v225, v101
	v_add_f32_e32 v164, v224, v164
	v_cvt_pk_bf16_f32 v215, v224, v225
	v_add_f32_e32 v164, v225, v164
	s_waitcnt lgkmcnt(3)
	v_mfma_f32_32x32x16_bf16 v[34:49], v[194:197], v[130:133], v[34:49]
	ds_read_b128 v[190:193], v228 offset:35840
	v_exp_f32_e32 v222, v102
	v_exp_f32_e32 v223, v103
	v_add_f32_e32 v164, v222, v164
	v_cvt_pk_bf16_f32 v216, v222, v223
	v_add_f32_e32 v164, v223, v164
	s_waitcnt lgkmcnt(3)
	v_mfma_f32_32x32x16_bf16 v[50:65], v[198:201], v[130:133], v[50:65]
	ds_read_b128 v[194:197], v228 offset:40448
	v_exp_f32_e32 v224, v104
	v_exp_f32_e32 v225, v105
	v_add_f32_e32 v164, v224, v164
	v_cvt_pk_bf16_f32 v217, v224, v225
	v_add_f32_e32 v164, v225, v164
	s_waitcnt lgkmcnt(3)
	v_mfma_f32_32x32x16_bf16 v[34:49], v[182:185], v[134:137], v[34:49]
	ds_read_b128 v[198:201], v228 offset:35872
	v_exp_f32_e32 v222, v106
	v_exp_f32_e32 v223, v107
	v_add_f32_e32 v164, v222, v164
	v_cvt_pk_bf16_f32 v218, v222, v223
	v_add_f32_e32 v164, v223, v164
	s_waitcnt lgkmcnt(3)
	v_mfma_f32_32x32x16_bf16 v[50:65], v[186:189], v[134:137], v[50:65]
	ds_read_b128 v[182:185], v228 offset:40480
	v_exp_f32_e32 v224, v108
	v_exp_f32_e32 v225, v109
	v_add_f32_e32 v164, v224, v164
	v_cvt_pk_bf16_f32 v219, v224, v225
	v_add_f32_e32 v164, v225, v164
	s_waitcnt lgkmcnt(3)
	v_mfma_f32_32x32x16_bf16 v[2:17], v[190:193], v[206:209], v[2:17]
	ds_read_b128 v[186:189], v228 offset:35904
	v_exp_f32_e32 v222, v110
	v_exp_f32_e32 v223, v111
	v_add_f32_e32 v164, v222, v164
	v_cvt_pk_bf16_f32 v220, v222, v223
	v_add_f32_e32 v164, v223, v164
	s_waitcnt lgkmcnt(3)
	v_mfma_f32_32x32x16_bf16 v[18:33], v[194:197], v[206:209], v[18:33]
	ds_read_b128 v[190:193], v228 offset:40512
	v_exp_f32_e32 v224, v112
	v_exp_f32_e32 v225, v113
	v_add_f32_e32 v164, v224, v164
	v_cvt_pk_bf16_f32 v221, v224, v225
	v_add_f32_e32 v164, v225, v164
	s_mov_b32 s13, s20
	s_mov_b32 s20, s19
	s_add_i32 s19, s19, 1
	s_cmp_eq_u32 s19, s9
	s_cselect_b32 s19, 0, s19
	s_waitcnt lgkmcnt(3)
	v_mfma_f32_32x32x16_bf16 v[2:17], v[198:201], v[210:213], v[2:17]
	ds_read_b128 v[194:197], v228 offset:35936
	v_max3_f32 v224, v34, v35, v36
	v_max3_f32 v225, v50, v51, v52
	v_max3_f32 v224, v224, v37, v38
	v_max3_f32 v225, v225, v53, v54
	s_waitcnt vmcnt(2)
	ds_write_b128 v172, v[150:153] offset:45056
	v_lshl_add_u32 v222, s19, 17, v178
	global_load_dwordx4 v[150:153], v222, s[52:53]
	s_waitcnt lgkmcnt(4)
	v_mfma_f32_32x32x16_bf16 v[18:33], v[182:185], v[210:213], v[18:33]
	ds_read_b128 v[198:201], v228 offset:40544
	v_max3_f32 v224, v224, v39, v40
	v_max3_f32 v225, v225, v55, v56
	v_max3_f32 v224, v224, v41, v42
	v_max3_f32 v225, v225, v57, v58
	s_and_b64 vcc, exec, s[2:3]
	s_cbranch_vccz .Lmla_p13_nope
	ds_write_b128 v176, v[160:163] offset:45184
	v_lshl_add_u32 v222, s19, 12, v179
	global_load_dwordx4 v[160:163], v222, s[62:63]
.Lmla_p13_nope:
	s_waitcnt lgkmcnt(4)
	v_mfma_f32_32x32x16_bf16 v[2:17], v[186:189], v[214:217], v[2:17]
	ds_read_b128 v[182:185], v174
	v_max3_f32 v224, v224, v43, v44
	v_max3_f32 v225, v225, v59, v60
	v_max3_f32 v224, v224, v45, v46
	v_max3_f32 v225, v225, v61, v62
	v_add_u32_e32 v222, 0xb000, v173
	ds_write_b128 v222, v[202:205] offset:49152
	v_lshl_add_u32 v222, s13, 7, v168
	global_load_dwordx4 v[202:205], v222, s[56:57]
	s_waitcnt lgkmcnt(5)
	v_mfma_f32_32x32x16_bf16 v[18:33], v[190:193], v[214:217], v[18:33]
	ds_read_b128 v[186:189], v174 offset:6656
	v_max3_f32 v224, v224, v47, v48
	v_max3_f32 v225, v225, v63, v64
	v_max3_f32 v224, v224, v49, v65
	v_max_f32_e32 v224, v224, v225
	s_waitcnt lgkmcnt(5)
	v_mfma_f32_32x32x16_bf16 v[2:17], v[194:197], v[218:221], v[2:17]
	ds_read_b128 v[190:193], v174 offset:32
	v_mov_b32_e32 v225, v224
	v_add_f32_e32 v1, v1, v164
	s_add_i32 s11, s11, 1
	v_permlane32_swap_b32_e32 v224, v225
	s_cmp_eq_u32 s9, s11
	v_max_f32_e32 v167, v224, v225
	s_waitcnt lgkmcnt(4)
	v_mfma_f32_32x32x16_bf16 v[18:33], v[198:201], v[218:221], v[18:33]
	ds_read_b128 v[194:197], v174 offset:6688
	v_cmp_lt_f32_e32 vcc, s66, v167
	s_waitcnt lgkmcnt(3)
	s_barrier
	s_cbranch_scc1 .Lmla_exit_p13

; template <int VAR>
; __device__ __forceinline__ void attn_phase(LAS unsigned char* lds, const AttnP P, int vcu, int G, int wave_s) {
;     ...
;                 if (ND0 == 6) {
;                     KR1(0); KR1(1); KR1(2); KR1(3); SB();
;                     QK1(0, negm); EX2(pc0, 0, w0.x); KR1(4); SB();
;                     QK1(1, negm); EX2(pc0, 2, w0.y); KR1(5); SB();
;                     QK1(2, pn0); EX2(pc0, 4, w0.z); KR1(6); SB();
;                     QK1(3, pn1); EX2(pc0, 6, w0.w); KR1(7); SB();
;                     QK1(4, pn0); EX2(pc0, 8, w1.x); KR1(8); SB();
;                     QK1(5, pn1); EX2(pc0, 10, w1.y); KR1(9); SB();
;                     QK1(6, pn0); EX2(pc0, 12, w1.z); KR1(10); SB();
;                     QK1(7, pn1); EX2(pc0, 14, w1.w); KR1(11); SB();
;                     QK1(8, pn0); EX2(pc1, 0, w2.x); VR1(0); SB();
;                     QK1(9, pn1); EX2(pc1, 2, w2.y); VR1(1); SB();
;                     QK1(10, pn0); EX2(pc1, 4, w2.z); VR1(2); SB();
;                     QK1(11, pn1); EX2(pc1, 6, w2.w); VR1(3); SB();
;                 } else {
;                     KR1(0); KR1(1); KR1(2); KR1(3); SB();
;                     QK1(0, negm); EX2(pc0, 0, w0.x); EX2(pc0, 2, w0.y); KR1(4); SB();
;                     QK1(1, negm); EX2(pc0, 4, w0.z); EX2(pc0, 6, w0.w); KR1(5); SB();
;                     QK1(2, pn0); EX2(pc0, 8, w1.x); EX2(pc0, 10, w1.y); KR1(6); SB();
;                     QK1(3, pn1); EX2(pc0, 12, w1.z); EX2(pc0, 14, w1.w); KR1(7); SB();
;                     QK1(4, pn0); EX2(pc1, 0, w2.x); VR1(0); SB();
;                     QK1(5, pn1); EX2(pc1, 2, w2.y); VR1(1); SB();
;                     QK1(6, pn0); EX2(pc1, 4, w2.z); VR1(2); SB();
;                     QK1(7, pn1); EX2(pc1, 6, w2.w); VR1(3); SB();
;                 }
;                 PV1(0, w0); EX2(pc1, 8, w3.x); VR1(4); SB();
;                 PV1(1, w0); EX2(pc1, 10, w3.y); VR1(5); SB();
;                 PV1(2, w1); EX2(pc1, 12, w3.z); VR1(6); SB();
;                 PV1(3, w1); EX2(pc1, 14, w3.w); VR1(7); SB();
;                 lrun += sacc;
;                 PV1(4, w2); MASK_TILE(pn0, pn1, t + 1); SB();
;                 PV1(5, w2); SB();
;                 PV1(6, w3); SB();
;                 PV1(7, w3); rmn = rowmax32(pn0, pn1); if (!USE_NEGM) rmn -= mref; SB();
;     ...
;             if (hn) { STOREK(t & 1); STOREV((t + 1) & 1); }
;             __syncthreads();
.Lmla_p14_go:
	v_exp_f32_e32 v222, v34
	v_exp_f32_e32 v223, v35
	v_add_f32_e32 v164, 0, v222
	v_cvt_pk_bf16_f32 v206, v222, v223
	v_add_f32_e32 v164, v223, v164
	v_exp_f32_e32 v224, v36
	v_exp_f32_e32 v225, v37
	v_add_f32_e32 v164, v224, v164
	v_cvt_pk_bf16_f32 v207, v224, v225
	v_add_f32_e32 v164, v225, v164
	s_waitcnt lgkmcnt(3)
	v_mfma_f32_32x32x16_bf16 v[82:97], v[182:185], v[114:117], v[66:81]
	ds_read_b128 v[198:201], v174 offset:64
	v_exp_f32_e32 v222, v38
	v_exp_f32_e32 v223, v39
	v_add_f32_e32 v164, v222, v164
	v_cvt_pk_bf16_f32 v208, v222, v223
	v_add_f32_e32 v164, v223, v164
	s_waitcnt lgkmcnt(3)
	v_mfma_f32_32x32x16_bf16 v[98:113], v[186:189], v[114:117], v[66:81]
	ds_read_b128 v[182:185], v174 offset:6720
	v_exp_f32_e32 v224, v40
	v_exp_f32_e32 v225, v41
	v_add_f32_e32 v164, v224, v164
	v_cvt_pk_bf16_f32 v209, v224, v225
	v_add_f32_e32 v164, v225, v164
	s_waitcnt lgkmcnt(3)
	v_mfma_f32_32x32x16_bf16 v[82:97], v[190:193], v[118:121], v[82:97]
	ds_read_b128 v[186:189], v174 offset:96
	v_exp_f32_e32 v222, v42
	v_exp_f32_e32 v223, v43
	v_add_f32_e32 v164, v222, v164
	v_cvt_pk_bf16_f32 v210, v222, v223
	v_add_f32_e32 v164, v223, v164
	s_waitcnt lgkmcnt(3)
	v_mfma_f32_32x32x16_bf16 v[98:113], v[194:197], v[118:121], v[98:113]
	ds_read_b128 v[190:193], v174 offset:6752
	v_exp_f32_e32 v224, v44
	v_exp_f32_e32 v225, v45
	v_add_f32_e32 v164, v224, v164
	v_cvt_pk_bf16_f32 v211, v224, v225
	v_add_f32_e32 v164, v225, v164
	s_waitcnt lgkmcnt(3)
	v_mfma_f32_32x32x16_bf16 v[82:97], v[198:201], v[122:125], v[82:97]
	ds_read_b128 v[194:197], v174 offset:128
	v_exp_f32_e32 v222, v46
	v_exp_f32_e32 v223, v47
	v_add_f32_e32 v164, v222, v164
	v_cvt_pk_bf16_f32 v212, v222, v223
	v_add_f32_e32 v164, v223, v164
	s_waitcnt lgkmcnt(3)
	v_mfma_f32_32x32x16_bf16 v[98:113], v[182:185], v[122:125], v[98:113]
	ds_read_b128 v[198:201], v174 offset:6784
	v_exp_f32_e32 v224, v48
	v_exp_f32_e32 v225, v49
	v_add_f32_e32 v164, v224, v164
	v_cvt_pk_bf16_f32 v213, v224, v225
	v_add_f32_e32 v164, v225, v164
	s_waitcnt lgkmcnt(3)
	v_mfma_f32_32x32x16_bf16 v[82:97], v[186:189], v[126:129], v[82:97]
	ds_read_b128 v[182:185], v174 offset:160
	v_exp_f32_e32 v222, v50
	v_exp_f32_e32 v223, v51
	v_add_f32_e32 v164, v222, v164
	v_cvt_pk_bf16_f32 v214, v222, v223
	v_add_f32_e32 v164, v223, v164
	s_waitcnt lgkmcnt(3)
	v_mfma_f32_32x32x16_bf16 v[98:113], v[190:193], v[126:129], v[98:113]
	ds_read_b128 v[186:189], v174 offset:6816
	v_exp_f32_e32 v224, v52
	v_exp_f32_e32 v225, v53
	v_add_f32_e32 v164, v224, v164
	v_cvt_pk_bf16_f32 v215, v224, v225
	v_add_f32_e32 v164, v225, v164
	s_waitcnt lgkmcnt(3)
	v_mfma_f32_32x32x16_bf16 v[82:97], v[194:197], v[130:133], v[82:97]
	ds_read_b128 v[190:193], v181 offset:39936
	v_exp_f32_e32 v222, v54
	v_exp_f32_e32 v223, v55
	v_add_f32_e32 v164, v222, v164
	v_cvt_pk_bf16_f32 v216, v222, v223
	v_add_f32_e32 v164, v223, v164
	s_waitcnt lgkmcnt(3)
	v_mfma_f32_32x32x16_bf16 v[98:113], v[198:201], v[130:133], v[98:113]
	ds_read_b128 v[194:197], v181 offset:44544
	v_exp_f32_e32 v224, v56
	v_exp_f32_e32 v225, v57
	v_add_f32_e32 v164, v224, v164
	v_cvt_pk_bf16_f32 v217, v224, v225
	v_add_f32_e32 v164, v225, v164
	s_waitcnt lgkmcnt(3)
	v_mfma_f32_32x32x16_bf16 v[82:97], v[182:185], v[134:137], v[82:97]
	ds_read_b128 v[198:201], v181 offset:39968
	v_exp_f32_e32 v222, v58
	v_exp_f32_e32 v223, v59
	v_add_f32_e32 v164, v222, v164
	v_cvt_pk_bf16_f32 v218, v222, v223
	v_add_f32_e32 v164, v223, v164
	s_waitcnt lgkmcnt(3)
	v_mfma_f32_32x32x16_bf16 v[98:113], v[186:189], v[134:137], v[98:113]
	ds_read_b128 v[182:185], v181 offset:44576
	v_exp_f32_e32 v224, v60
	v_exp_f32_e32 v225, v61
	v_add_f32_e32 v164, v224, v164
	v_cvt_pk_bf16_f32 v219, v224, v225
	v_add_f32_e32 v164, v225, v164
	s_waitcnt lgkmcnt(3)
	v_mfma_f32_32x32x16_bf16 v[2:17], v[190:193], v[206:209], v[2:17]
	ds_read_b128 v[186:189], v181 offset:40000
	v_exp_f32_e32 v222, v62
	v_exp_f32_e32 v223, v63
	v_add_f32_e32 v164, v222, v164
	v_cvt_pk_bf16_f32 v220, v222, v223
	v_add_f32_e32 v164, v223, v164
	s_waitcnt lgkmcnt(3)
	v_mfma_f32_32x32x16_bf16 v[18:33], v[194:197], v[206:209], v[18:33]
	ds_read_b128 v[190:193], v181 offset:44608
	v_exp_f32_e32 v224, v64
	v_exp_f32_e32 v225, v65
	v_add_f32_e32 v164, v224, v164
	v_cvt_pk_bf16_f32 v221, v224, v225
	v_add_f32_e32 v164, v225, v164
	s_mov_b32 s13, s20
	s_mov_b32 s20, s19
	s_add_i32 s19, s19, 1
	s_cmp_eq_u32 s19, s9
	s_cselect_b32 s19, 0, s19
	s_waitcnt lgkmcnt(3)
	v_mfma_f32_32x32x16_bf16 v[2:17], v[198:201], v[210:213], v[2:17]
	ds_read_b128 v[194:197], v181 offset:40032
	v_max3_f32 v224, v82, v83, v84
	v_max3_f32 v225, v98, v99, v100
	v_max3_f32 v224, v224, v85, v86
	v_max3_f32 v225, v225, v101, v102
	s_waitcnt vmcnt(2)
	ds_write_b128 v172, v[146:149] offset:58368
	v_lshl_add_u32 v222, s19, 17, v178
	global_load_dwordx4 v[146:149], v222, s[52:53]
	s_waitcnt lgkmcnt(4)
	v_mfma_f32_32x32x16_bf16 v[18:33], v[182:185], v[210:213], v[18:33]
	ds_read_b128 v[198:201], v181 offset:44640
	v_max3_f32 v224, v224, v87, v88
	v_max3_f32 v225, v225, v103, v104
	v_max3_f32 v224, v224, v89, v90
	v_max3_f32 v225, v225, v105, v106
	s_and_b64 vcc, exec, s[2:3]
	s_cbranch_vccz .Lmla_p14_nope
	ds_write_b128 v176, v[138:141] offset:58496
	v_lshl_add_u32 v222, s19, 12, v179
	global_load_dwordx4 v[138:141], v222, s[62:63]
.Lmla_p14_nope:
	s_waitcnt lgkmcnt(4)
	v_mfma_f32_32x32x16_bf16 v[2:17], v[186:189], v[214:217], v[2:17]
	ds_read_b128 v[182:185], v174 offset:22528
	v_max3_f32 v224, v224, v91, v92
	v_max3_f32 v225, v225, v107, v108
	v_max3_f32 v224, v224, v93, v94
	v_max3_f32 v225, v225, v109, v110
	ds_write_b128 v173, v[142:145] offset:13312
	v_lshl_add_u32 v222, s13, 7, v168
	global_load_dwordx4 v[142:145], v222, s[56:57]
	s_waitcnt lgkmcnt(5)
	v_mfma_f32_32x32x16_bf16 v[18:33], v[190:193], v[214:217], v[18:33]
	ds_read_b128 v[186:189], v174 offset:29184
	v_max3_f32 v224, v224, v95, v96
	v_max3_f32 v225, v225, v111, v112
	v_max3_f32 v224, v224, v97, v113
	v_max_f32_e32 v224, v224, v225
	s_waitcnt lgkmcnt(5)
	v_mfma_f32_32x32x16_bf16 v[2:17], v[194:197], v[218:221], v[2:17]
	ds_read_b128 v[190:193], v174 offset:22560
	v_mov_b32_e32 v225, v224
	v_add_f32_e32 v1, v1, v164
	s_add_i32 s11, s11, 1
	v_permlane32_swap_b32_e32 v224, v225
	s_cmp_eq_u32 s9, s11
	v_max_f32_e32 v167, v224, v225
	s_waitcnt lgkmcnt(4)
	v_mfma_f32_32x32x16_bf16 v[18:33], v[198:201], v[218:221], v[18:33]
	ds_read_b128 v[194:197], v174 offset:29216
	v_cmp_lt_f32_e32 vcc, s66, v167
	s_cbranch_scc1 .Lmla_exit_p14

; template <int VAR>
; __device__ __forceinline__ void attn_phase(LAS unsigned char* lds, const AttnP P, int vcu, int G, int wave_s) {
;     ...
;                 if (ND0 == 6) {
;                     KR1(0); KR1(1); KR1(2); KR1(3); SB();
;                     QK1(0, negm); EX2(pc0, 0, w0.x); KR1(4); SB();
;                     QK1(1, negm); EX2(pc0, 2, w0.y); KR1(5); SB();
;                     QK1(2, pn0); EX2(pc0, 4, w0.z); KR1(6); SB();
;                     QK1(3, pn1); EX2(pc0, 6, w0.w); KR1(7); SB();
;                     QK1(4, pn0); EX2(pc0, 8, w1.x); KR1(8); SB();
;                     QK1(5, pn1); EX2(pc0, 10, w1.y); KR1(9); SB();
;                     QK1(6, pn0); EX2(pc0, 12, w1.z); KR1(10); SB();
;                     QK1(7, pn1); EX2(pc0, 14, w1.w); KR1(11); SB();
;                     QK1(8, pn0); EX2(pc1, 0, w2.x); VR1(0); SB();
;                     QK1(9, pn1); EX2(pc1, 2, w2.y); VR1(1); SB();
;                     QK1(10, pn0); EX2(pc1, 4, w2.z); VR1(2); SB();
;                     QK1(11, pn1); EX2(pc1, 6, w2.w); VR1(3); SB();
;                 } else {
;                     KR1(0); KR1(1); KR1(2); KR1(3); SB();
;                     QK1(0, negm); EX2(pc0, 0, w0.x); EX2(pc0, 2, w0.y); KR1(4); SB();
;                     QK1(1, negm); EX2(pc0, 4, w0.z); EX2(pc0, 6, w0.w); KR1(5); SB();
;                     QK1(2, pn0); EX2(pc0, 8, w1.x); EX2(pc0, 10, w1.y); KR1(6); SB();
;                     QK1(3, pn1); EX2(pc0, 12, w1.z); EX2(pc0, 14, w1.w); KR1(7); SB();
;                     QK1(4, pn0); EX2(pc1, 0, w2.x); VR1(0); SB();
;                     QK1(5, pn1); EX2(pc1, 2, w2.y); VR1(1); SB();
;                     QK1(6, pn0); EX2(pc1, 4, w2.z); VR1(2); SB();
;                     QK1(7, pn1); EX2(pc1, 6, w2.w); VR1(3); SB();
;                 }
;                 PV1(0, w0); EX2(pc1, 8, w3.x); VR1(4); SB();
;                 PV1(1, w0); EX2(pc1, 10, w3.y); VR1(5); SB();
;                 PV1(2, w1); EX2(pc1, 12, w3.z); VR1(6); SB();
;                 PV1(3, w1); EX2(pc1, 14, w3.w); VR1(7); SB();
;                 lrun += sacc;
;                 PV1(4, w2); MASK_TILE(pn0, pn1, t + 1); SB();
;                 PV1(5, w2); SB();
;                 PV1(6, w3); SB();
;                 PV1(7, w3); rmn = rowmax32(pn0, pn1); if (!USE_NEGM) rmn -= mref; SB();
;     ...
;             if (hn) { STOREK(t & 1); STOREV((t + 1) & 1); }
;             __syncthreads();
.Lmla_p15_go:
	v_exp_f32_e32 v222, v82
	v_exp_f32_e32 v223, v83
	v_add_f32_e32 v164, 0, v222
	v_cvt_pk_bf16_f32 v206, v222, v223
	v_add_f32_e32 v164, v223, v164
	v_exp_f32_e32 v224, v84
	v_exp_f32_e32 v225, v85
	v_add_f32_e32 v164, v224, v164
	v_cvt_pk_bf16_f32 v207, v224, v225
	v_add_f32_e32 v164, v225, v164
	s_waitcnt lgkmcnt(4)
	v_mfma_f32_32x32x16_bf16 v[34:49], v[182:185], v[114:117], v[66:81]
	ds_read_b128 v[198:201], v174 offset:22592
	v_exp_f32_e32 v222, v86
	v_exp_f32_e32 v223, v87
	v_add_f32_e32 v164, v222, v164
	v_cvt_pk_bf16_f32 v208, v222, v223
	v_add_f32_e32 v164, v223, v164
	s_waitcnt lgkmcnt(3)
	v_mfma_f32_32x32x16_bf16 v[50:65], v[186:189], v[114:117], v[66:81]
	ds_read_b128 v[182:185], v174 offset:29248
	v_exp_f32_e32 v224, v88
	v_exp_f32_e32 v225, v89
	v_add_f32_e32 v164, v224, v164
	v_cvt_pk_bf16_f32 v209, v224, v225
	v_add_f32_e32 v164, v225, v164
	s_waitcnt lgkmcnt(3)
	v_mfma_f32_32x32x16_bf16 v[34:49], v[190:193], v[118:121], v[34:49]
	ds_read_b128 v[186:189], v174 offset:22624
	v_exp_f32_e32 v222, v90
	v_exp_f32_e32 v223, v91
	v_add_f32_e32 v164, v222, v164
	v_cvt_pk_bf16_f32 v210, v222, v223
	v_add_f32_e32 v164, v223, v164
	s_waitcnt lgkmcnt(3)
	v_mfma_f32_32x32x16_bf16 v[50:65], v[194:197], v[118:121], v[50:65]
	ds_read_b128 v[190:193], v174 offset:29280
	v_exp_f32_e32 v224, v92
	v_exp_f32_e32 v225, v93
	v_add_f32_e32 v164, v224, v164
	v_cvt_pk_bf16_f32 v211, v224, v225
	v_add_f32_e32 v164, v225, v164
	s_waitcnt lgkmcnt(3)
	v_mfma_f32_32x32x16_bf16 v[34:49], v[198:201], v[122:125], v[34:49]
	ds_read_b128 v[194:197], v174 offset:22656
	v_exp_f32_e32 v222, v94
	v_exp_f32_e32 v223, v95
	v_add_f32_e32 v164, v222, v164
	v_cvt_pk_bf16_f32 v212, v222, v223
	v_add_f32_e32 v164, v223, v164
	s_waitcnt lgkmcnt(3)
	v_mfma_f32_32x32x16_bf16 v[50:65], v[182:185], v[122:125], v[50:65]
	ds_read_b128 v[198:201], v174 offset:29312
	v_exp_f32_e32 v224, v96
	v_exp_f32_e32 v225, v97
	v_add_f32_e32 v164, v224, v164
	v_cvt_pk_bf16_f32 v213, v224, v225
	v_add_f32_e32 v164, v225, v164
	s_waitcnt lgkmcnt(3)
	v_mfma_f32_32x32x16_bf16 v[34:49], v[186:189], v[126:129], v[34:49]
	ds_read_b128 v[182:185], v174 offset:22688
	v_exp_f32_e32 v222, v98
	v_exp_f32_e32 v223, v99
	v_add_f32_e32 v164, v222, v164
	v_cvt_pk_bf16_f32 v214, v222, v223
	v_add_f32_e32 v164, v223, v164
	s_waitcnt lgkmcnt(3)
	v_mfma_f32_32x32x16_bf16 v[50:65], v[190:193], v[126:129], v[50:65]
	ds_read_b128 v[186:189], v174 offset:29344
	v_exp_f32_e32 v224, v100
	v_exp_f32_e32 v225, v101
	v_add_f32_e32 v164, v224, v164
	v_cvt_pk_bf16_f32 v215, v224, v225
	v_add_f32_e32 v164, v225, v164
	s_waitcnt lgkmcnt(3)
	v_mfma_f32_32x32x16_bf16 v[34:49], v[194:197], v[130:133], v[34:49]
	ds_read_b128 v[190:193], v181 offset:49152
	v_exp_f32_e32 v222, v102
	v_exp_f32_e32 v223, v103
	v_add_f32_e32 v164, v222, v164
	v_cvt_pk_bf16_f32 v216, v222, v223
	v_add_f32_e32 v164, v223, v164
	s_waitcnt lgkmcnt(3)
	v_mfma_f32_32x32x16_bf16 v[50:65], v[198:201], v[130:133], v[50:65]
	ds_read_b128 v[194:197], v181 offset:53760
	v_exp_f32_e32 v224, v104
	v_exp_f32_e32 v225, v105
	v_add_f32_e32 v164, v224, v164
	v_cvt_pk_bf16_f32 v217, v224, v225
	v_add_f32_e32 v164, v225, v164
	s_waitcnt lgkmcnt(3)
	v_mfma_f32_32x32x16_bf16 v[34:49], v[182:185], v[134:137], v[34:49]
	ds_read_b128 v[198:201], v181 offset:49184
	v_exp_f32_e32 v222, v106
	v_exp_f32_e32 v223, v107
	v_add_f32_e32 v164, v222, v164
	v_cvt_pk_bf16_f32 v218, v222, v223
	v_add_f32_e32 v164, v223, v164
	s_waitcnt lgkmcnt(3)
	v_mfma_f32_32x32x16_bf16 v[50:65], v[186:189], v[134:137], v[50:65]
	ds_read_b128 v[182:185], v181 offset:53792
	v_exp_f32_e32 v224, v108
	v_exp_f32_e32 v225, v109
	v_add_f32_e32 v164, v224, v164
	v_cvt_pk_bf16_f32 v219, v224, v225
	v_add_f32_e32 v164, v225, v164
	s_waitcnt lgkmcnt(3)
	v_mfma_f32_32x32x16_bf16 v[2:17], v[190:193], v[206:209], v[2:17]
	ds_read_b128 v[186:189], v181 offset:49216
	v_exp_f32_e32 v222, v110
	v_exp_f32_e32 v223, v111
	v_add_f32_e32 v164, v222, v164
	v_cvt_pk_bf16_f32 v220, v222, v223
	v_add_f32_e32 v164, v223, v164
	s_waitcnt lgkmcnt(3)
	v_mfma_f32_32x32x16_bf16 v[18:33], v[194:197], v[206:209], v[18:33]
	ds_read_b128 v[190:193], v181 offset:53824
	v_exp_f32_e32 v224, v112
	v_exp_f32_e32 v225, v113
	v_add_f32_e32 v164, v224, v164
	v_cvt_pk_bf16_f32 v221, v224, v225
	v_add_f32_e32 v164, v225, v164
	s_mov_b32 s13, s20
	s_mov_b32 s20, s19
	s_add_i32 s19, s19, 1
	s_cmp_eq_u32 s19, s9
	s_cselect_b32 s19, 0, s19
	s_waitcnt lgkmcnt(3)
	v_mfma_f32_32x32x16_bf16 v[2:17], v[198:201], v[210:213], v[2:17]
	ds_read_b128 v[194:197], v181 offset:49248
	v_max3_f32 v224, v34, v35, v36
	v_max3_f32 v225, v50, v51, v52
	v_max3_f32 v224, v224, v37, v38
	v_max3_f32 v225, v225, v53, v54
	s_waitcnt vmcnt(2)
	v_add_u32_e32 v222, 0xb000, v172
	ds_write_b128 v222, v[150:153] offset:26624
	v_lshl_add_u32 v222, s19, 17, v178
	global_load_dwordx4 v[150:153], v222, s[52:53]
	s_waitcnt lgkmcnt(4)
	v_mfma_f32_32x32x16_bf16 v[18:33], v[182:185], v[210:213], v[18:33]
	ds_read_b128 v[198:201], v181 offset:53856
	v_max3_f32 v224, v224, v39, v40
	v_max3_f32 v225, v225, v55, v56
	v_max3_f32 v224, v224, v41, v42
	v_max3_f32 v225, v225, v57, v58
	s_and_b64 vcc, exec, s[2:3]
	s_cbranch_vccz .Lmla_p15_nope
	v_add_u32_e32 v222, 0xb000, v176
	ds_write_b128 v222, v[160:163] offset:26752
	v_lshl_add_u32 v222, s19, 12, v179
	global_load_dwordx4 v[160:163], v222, s[62:63]
.Lmla_p15_nope:
	s_waitcnt lgkmcnt(4)
	v_mfma_f32_32x32x16_bf16 v[2:17], v[186:189], v[214:217], v[2:17]
	ds_read_b128 v[182:185], v174 offset:45056
	v_max3_f32 v224, v224, v43, v44
	v_max3_f32 v225, v225, v59, v60
	v_max3_f32 v224, v224, v45, v46
	v_max3_f32 v225, v225, v61, v62
	ds_write_b128 v173, v[202:205] offset:35840
	v_lshl_add_u32 v222, s13, 7, v168
	global_load_dwordx4 v[202:205], v222, s[56:57]
	s_waitcnt lgkmcnt(5)
	v_mfma_f32_32x32x16_bf16 v[18:33], v[190:193], v[214:217], v[18:33]
	ds_read_b128 v[186:189], v174 offset:51712
	v_max3_f32 v224, v224, v47, v48
	v_max3_f32 v225, v225, v63, v64
	v_max3_f32 v224, v224, v49, v65
	v_max_f32_e32 v224, v224, v225
	s_waitcnt lgkmcnt(5)
	v_mfma_f32_32x32x16_bf16 v[2:17], v[194:197], v[218:221], v[2:17]
	ds_read_b128 v[190:193], v174 offset:45088
	v_mov_b32_e32 v225, v224
	v_add_f32_e32 v1, v1, v164
	s_add_i32 s11, s11, 1
	v_permlane32_swap_b32_e32 v224, v225
	s_cmp_eq_u32 s9, s11
	v_max_f32_e32 v167, v224, v225
	s_waitcnt lgkmcnt(4)
	v_mfma_f32_32x32x16_bf16 v[18:33], v[198:201], v[218:221], v[18:33]
	ds_read_b128 v[194:197], v174 offset:51744
	v_cmp_lt_f32_e32 vcc, s66, v167
	s_waitcnt lgkmcnt(3)
	s_barrier
	s_cbranch_scc1 .Lmla_exit_p15

; template <int VAR>
; __device__ __forceinline__ void attn_phase(LAS unsigned char* lds, const AttnP P, int vcu, int G, int wave_s) {
;     ...
;                 if (ND0 == 6) {
;                     KR1(0); KR1(1); KR1(2); KR1(3); SB();
;                     QK1(0, negm); EX2(pc0, 0, w0.x); KR1(4); SB();
;                     QK1(1, negm); EX2(pc0, 2, w0.y); KR1(5); SB();
;                     QK1(2, pn0); EX2(pc0, 4, w0.z); KR1(6); SB();
;                     QK1(3, pn1); EX2(pc0, 6, w0.w); KR1(7); SB();
;                     QK1(4, pn0); EX2(pc0, 8, w1.x); KR1(8); SB();
;                     QK1(5, pn1); EX2(pc0, 10, w1.y); KR1(9); SB();
;                     QK1(6, pn0); EX2(pc0, 12, w1.z); KR1(10); SB();
;                     QK1(7, pn1); EX2(pc0, 14, w1.w); KR1(11); SB();
;                     QK1(8, pn0); EX2(pc1, 0, w2.x); VR1(0); SB();
;                     QK1(9, pn1); EX2(pc1, 2, w2.y); VR1(1); SB();
;                     QK1(10, pn0); EX2(pc1, 4, w2.z); VR1(2); SB();
;                     QK1(11, pn1); EX2(pc1, 6, w2.w); VR1(3); SB();
;                 } else {
;                     KR1(0); KR1(1); KR1(2); KR1(3); SB();
;                     QK1(0, negm); EX2(pc0, 0, w0.x); EX2(pc0, 2, w0.y); KR1(4); SB();
;                     QK1(1, negm); EX2(pc0, 4, w0.z); EX2(pc0, 6, w0.w); KR1(5); SB();
;                     QK1(2, pn0); EX2(pc0, 8, w1.x); EX2(pc0, 10, w1.y); KR1(6); SB();
;                     QK1(3, pn1); EX2(pc0, 12, w1.z); EX2(pc0, 14, w1.w); KR1(7); SB();
;                     QK1(4, pn0); EX2(pc1, 0, w2.x); VR1(0); SB();
;                     QK1(5, pn1); EX2(pc1, 2, w2.y); VR1(1); SB();
;                     QK1(6, pn0); EX2(pc1, 4, w2.z); VR1(2); SB();
;                     QK1(7, pn1); EX2(pc1, 6, w2.w); VR1(3); SB();
;                 }
;                 PV1(0, w0); EX2(pc1, 8, w3.x); VR1(4); SB();
;                 PV1(1, w0); EX2(pc1, 10, w3.y); VR1(5); SB();
;                 PV1(2, w1); EX2(pc1, 12, w3.z); VR1(6); SB();
;                 PV1(3, w1); EX2(pc1, 14, w3.w); VR1(7); SB();
;                 lrun += sacc;
;                 PV1(4, w2); MASK_TILE(pn0, pn1, t + 1); SB();
;                 PV1(5, w2); SB();
;                 PV1(6, w3); SB();
;                 PV1(7, w3); rmn = rowmax32(pn0, pn1); if (!USE_NEGM) rmn -= mref; SB();
;     ...
;             if (hn) { STOREK(t & 1); STOREV((t + 1) & 1); }
;             __syncthreads();
.Lmla_p16_go:
	v_exp_f32_e32 v222, v34
	v_exp_f32_e32 v223, v35
	v_add_f32_e32 v164, 0, v222
	v_cvt_pk_bf16_f32 v206, v222, v223
	v_add_f32_e32 v164, v223, v164
	v_exp_f32_e32 v224, v36
	v_exp_f32_e32 v225, v37
	v_add_f32_e32 v164, v224, v164
	v_cvt_pk_bf16_f32 v207, v224, v225
	v_add_f32_e32 v164, v225, v164
	s_waitcnt lgkmcnt(3)
	v_mfma_f32_32x32x16_bf16 v[82:97], v[182:185], v[114:117], v[66:81]
	ds_read_b128 v[198:201], v174 offset:45120
	v_exp_f32_e32 v222, v38
	v_exp_f32_e32 v223, v39
	v_add_f32_e32 v164, v222, v164
	v_cvt_pk_bf16_f32 v208, v222, v223
	v_add_f32_e32 v164, v223, v164
	s_waitcnt lgkmcnt(3)
	v_mfma_f32_32x32x16_bf16 v[98:113], v[186:189], v[114:117], v[66:81]
	ds_read_b128 v[182:185], v174 offset:51776
	v_exp_f32_e32 v224, v40
	v_exp_f32_e32 v225, v41
	v_add_f32_e32 v164, v224, v164
	v_cvt_pk_bf16_f32 v209, v224, v225
	v_add_f32_e32 v164, v225, v164
	s_waitcnt lgkmcnt(3)
	v_mfma_f32_32x32x16_bf16 v[82:97], v[190:193], v[118:121], v[82:97]
	ds_read_b128 v[186:189], v174 offset:45152
	v_exp_f32_e32 v222, v42
	v_exp_f32_e32 v223, v43
	v_add_f32_e32 v164, v222, v164
	v_cvt_pk_bf16_f32 v210, v222, v223
	v_add_f32_e32 v164, v223, v164
	s_waitcnt lgkmcnt(3)
	v_mfma_f32_32x32x16_bf16 v[98:113], v[194:197], v[118:121], v[98:113]
	ds_read_b128 v[190:193], v174 offset:51808
	v_exp_f32_e32 v224, v44
	v_exp_f32_e32 v225, v45
	v_add_f32_e32 v164, v224, v164
	v_cvt_pk_bf16_f32 v211, v224, v225
	v_add_f32_e32 v164, v225, v164
	s_waitcnt lgkmcnt(3)
	v_mfma_f32_32x32x16_bf16 v[82:97], v[198:201], v[122:125], v[82:97]
	ds_read_b128 v[194:197], v174 offset:45184
	v_exp_f32_e32 v222, v46
	v_exp_f32_e32 v223, v47
	v_add_f32_e32 v164, v222, v164
	v_cvt_pk_bf16_f32 v212, v222, v223
	v_add_f32_e32 v164, v223, v164
	s_waitcnt lgkmcnt(3)
	v_mfma_f32_32x32x16_bf16 v[98:113], v[182:185], v[122:125], v[98:113]
	ds_read_b128 v[198:201], v174 offset:51840
	v_exp_f32_e32 v224, v48
	v_exp_f32_e32 v225, v49
	v_add_f32_e32 v164, v224, v164
	v_cvt_pk_bf16_f32 v213, v224, v225
	v_add_f32_e32 v164, v225, v164
	s_waitcnt lgkmcnt(3)
	v_mfma_f32_32x32x16_bf16 v[82:97], v[186:189], v[126:129], v[82:97]
	ds_read_b128 v[182:185], v174 offset:45216
	v_exp_f32_e32 v222, v50
	v_exp_f32_e32 v223, v51
	v_add_f32_e32 v164, v222, v164
	v_cvt_pk_bf16_f32 v214, v222, v223
	v_add_f32_e32 v164, v223, v164
	s_waitcnt lgkmcnt(3)
	v_mfma_f32_32x32x16_bf16 v[98:113], v[190:193], v[126:129], v[98:113]
	ds_read_b128 v[186:189], v174 offset:51872
	v_exp_f32_e32 v224, v52
	v_exp_f32_e32 v225, v53
	v_add_f32_e32 v164, v224, v164
	v_cvt_pk_bf16_f32 v215, v224, v225
	v_add_f32_e32 v164, v225, v164
	s_waitcnt lgkmcnt(3)
	v_mfma_f32_32x32x16_bf16 v[82:97], v[194:197], v[130:133], v[82:97]
	ds_read_b128 v[190:193], v228 offset:13312
	v_exp_f32_e32 v222, v54
	v_exp_f32_e32 v223, v55
	v_add_f32_e32 v164, v222, v164
	v_cvt_pk_bf16_f32 v216, v222, v223
	v_add_f32_e32 v164, v223, v164
	s_waitcnt lgkmcnt(3)
	v_mfma_f32_32x32x16_bf16 v[98:113], v[198:201], v[130:133], v[98:113]
	ds_read_b128 v[194:197], v228 offset:17920
	v_exp_f32_e32 v224, v56
	v_exp_f32_e32 v225, v57
	v_add_f32_e32 v164, v224, v164
	v_cvt_pk_bf16_f32 v217, v224, v225
	v_add_f32_e32 v164, v225, v164
	s_waitcnt lgkmcnt(3)
	v_mfma_f32_32x32x16_bf16 v[82:97], v[182:185], v[134:137], v[82:97]
	ds_read_b128 v[198:201], v228 offset:13344
	v_exp_f32_e32 v222, v58
	v_exp_f32_e32 v223, v59
	v_add_f32_e32 v164, v222, v164
	v_cvt_pk_bf16_f32 v218, v222, v223
	v_add_f32_e32 v164, v223, v164
	s_waitcnt lgkmcnt(3)
	v_mfma_f32_32x32x16_bf16 v[98:113], v[186:189], v[134:137], v[98:113]
	ds_read_b128 v[182:185], v228 offset:17952
	v_exp_f32_e32 v224, v60
	v_exp_f32_e32 v225, v61
	v_add_f32_e32 v164, v224, v164
	v_cvt_pk_bf16_f32 v219, v224, v225
	v_add_f32_e32 v164, v225, v164
	s_waitcnt lgkmcnt(3)
	v_mfma_f32_32x32x16_bf16 v[2:17], v[190:193], v[206:209], v[2:17]
	ds_read_b128 v[186:189], v228 offset:13376
	v_exp_f32_e32 v222, v62
	v_exp_f32_e32 v223, v63
	v_add_f32_e32 v164, v222, v164
	v_cvt_pk_bf16_f32 v220, v222, v223
	v_add_f32_e32 v164, v223, v164
	s_waitcnt lgkmcnt(3)
	v_mfma_f32_32x32x16_bf16 v[18:33], v[194:197], v[206:209], v[18:33]
	ds_read_b128 v[190:193], v228 offset:17984
	v_exp_f32_e32 v224, v64
	v_exp_f32_e32 v225, v65
	v_add_f32_e32 v164, v224, v164
	v_cvt_pk_bf16_f32 v221, v224, v225
	v_add_f32_e32 v164, v225, v164
	s_mov_b32 s13, s20
	s_mov_b32 s20, s19
	s_add_i32 s19, s19, 1
	s_cmp_eq_u32 s19, s9
	s_cselect_b32 s19, 0, s19
	s_waitcnt lgkmcnt(3)
	v_mfma_f32_32x32x16_bf16 v[2:17], v[198:201], v[210:213], v[2:17]
	ds_read_b128 v[194:197], v228 offset:13408
	v_max3_f32 v224, v82, v83, v84
	v_max3_f32 v225, v98, v99, v100
	v_max3_f32 v224, v224, v85, v86
	v_max3_f32 v225, v225, v101, v102
	s_waitcnt vmcnt(2)
	ds_write_b128 v172, v[146:149]
	v_lshl_add_u32 v222, s19, 17, v178
	global_load_dwordx4 v[146:149], v222, s[52:53]
	s_waitcnt lgkmcnt(4)
	v_mfma_f32_32x32x16_bf16 v[18:33], v[182:185], v[210:213], v[18:33]
	ds_read_b128 v[198:201], v228 offset:18016
	v_max3_f32 v224, v224, v87, v88
	v_max3_f32 v225, v225, v103, v104
	v_max3_f32 v224, v224, v89, v90
	v_max3_f32 v225, v225, v105, v106
	s_and_b64 vcc, exec, s[2:3]
	s_cbranch_vccz .Lmla_p16_nope
	ds_write_b128 v176, v[138:141] offset:128
	v_lshl_add_u32 v222, s19, 12, v179
	global_load_dwordx4 v[138:141], v222, s[62:63]
.Lmla_p16_nope:
	s_waitcnt lgkmcnt(4)
	v_mfma_f32_32x32x16_bf16 v[2:17], v[186:189], v[214:217], v[2:17]
	ds_read_b128 v[182:185], v229 offset:13312
	v_max3_f32 v224, v224, v91, v92
	v_max3_f32 v225, v225, v107, v108
	v_max3_f32 v224, v224, v93, v94
	v_max3_f32 v225, v225, v109, v110
	v_add_u32_e32 v222, 0xb000, v173
	ds_write_b128 v222, v[142:145] offset:39936
	v_lshl_add_u32 v222, s13, 7, v168
	global_load_dwordx4 v[142:145], v222, s[56:57]
	s_waitcnt lgkmcnt(5)
	v_mfma_f32_32x32x16_bf16 v[18:33], v[190:193], v[214:217], v[18:33]
	ds_read_b128 v[186:189], v229 offset:19968
	v_max3_f32 v224, v224, v95, v96
	v_max3_f32 v225, v225, v111, v112
	v_max3_f32 v224, v224, v97, v113
	v_max_f32_e32 v224, v224, v225
	s_waitcnt lgkmcnt(5)
	v_mfma_f32_32x32x16_bf16 v[2:17], v[194:197], v[218:221], v[2:17]
	ds_read_b128 v[190:193], v229 offset:13344
	v_mov_b32_e32 v225, v224
	v_add_f32_e32 v1, v1, v164
	s_add_i32 s11, s11, 1
	v_permlane32_swap_b32_e32 v224, v225
	s_cmp_eq_u32 s9, s11
	v_max_f32_e32 v167, v224, v225
	s_waitcnt lgkmcnt(4)
	v_mfma_f32_32x32x16_bf16 v[18:33], v[198:201], v[218:221], v[18:33]
	ds_read_b128 v[194:197], v229 offset:20000
	v_cmp_lt_f32_e32 vcc, s66, v167
	s_cbranch_scc1 .Lmla_exit_p16

; template <int VAR>
; __device__ __forceinline__ void attn_phase(LAS unsigned char* lds, const AttnP P, int vcu, int G, int wave_s) {
;     ...
;                 if (ND0 == 6) {
;                     KR1(0); KR1(1); KR1(2); KR1(3); SB();
;                     QK1(0, negm); EX2(pc0, 0, w0.x); KR1(4); SB();
;                     QK1(1, negm); EX2(pc0, 2, w0.y); KR1(5); SB();
;                     QK1(2, pn0); EX2(pc0, 4, w0.z); KR1(6); SB();
;                     QK1(3, pn1); EX2(pc0, 6, w0.w); KR1(7); SB();
;                     QK1(4, pn0); EX2(pc0, 8, w1.x); KR1(8); SB();
;                     QK1(5, pn1); EX2(pc0, 10, w1.y); KR1(9); SB();
;                     QK1(6, pn0); EX2(pc0, 12, w1.z); KR1(10); SB();
;                     QK1(7, pn1); EX2(pc0, 14, w1.w); KR1(11); SB();
;                     QK1(8, pn0); EX2(pc1, 0, w2.x); VR1(0); SB();
;                     QK1(9, pn1); EX2(pc1, 2, w2.y); VR1(1); SB();
;                     QK1(10, pn0); EX2(pc1, 4, w2.z); VR1(2); SB();
;                     QK1(11, pn1); EX2(pc1, 6, w2.w); VR1(3); SB();
;                 } else {
;                     KR1(0); KR1(1); KR1(2); KR1(3); SB();
;                     QK1(0, negm); EX2(pc0, 0, w0.x); EX2(pc0, 2, w0.y); KR1(4); SB();
;                     QK1(1, negm); EX2(pc0, 4, w0.z); EX2(pc0, 6, w0.w); KR1(5); SB();
;                     QK1(2, pn0); EX2(pc0, 8, w1.x); EX2(pc0, 10, w1.y); KR1(6); SB();
;                     QK1(3, pn1); EX2(pc0, 12, w1.z); EX2(pc0, 14, w1.w); KR1(7); SB();
;                     QK1(4, pn0); EX2(pc1, 0, w2.x); VR1(0); SB();
;                     QK1(5, pn1); EX2(pc1, 2, w2.y); VR1(1); SB();
;                     QK1(6, pn0); EX2(pc1, 4, w2.z); VR1(2); SB();
;                     QK1(7, pn1); EX2(pc1, 6, w2.w); VR1(3); SB();
;                 }
;                 PV1(0, w0); EX2(pc1, 8, w3.x); VR1(4); SB();
;                 PV1(1, w0); EX2(pc1, 10, w3.y); VR1(5); SB();
;                 PV1(2, w1); EX2(pc1, 12, w3.z); VR1(6); SB();
;                 PV1(3, w1); EX2(pc1, 14, w3.w); VR1(7); SB();
;                 lrun += sacc;
;                 PV1(4, w2); MASK_TILE(pn0, pn1, t + 1); SB();
;                 PV1(5, w2); SB();
;                 PV1(6, w3); SB();
;                 PV1(7, w3); rmn = rowmax32(pn0, pn1); if (!USE_NEGM) rmn -= mref; SB();
;     ...
;             if (hn) { STOREK(t & 1); STOREV((t + 1) & 1); }
;             __syncthreads();
.Lmla_p17_go:
	v_exp_f32_e32 v222, v82
	v_exp_f32_e32 v223, v83
	v_add_f32_e32 v164, 0, v222
	v_cvt_pk_bf16_f32 v206, v222, v223
	v_add_f32_e32 v164, v223, v164
	v_exp_f32_e32 v224, v84
	v_exp_f32_e32 v225, v85
	v_add_f32_e32 v164, v224, v164
	v_cvt_pk_bf16_f32 v207, v224, v225
	v_add_f32_e32 v164, v225, v164
	s_waitcnt lgkmcnt(4)
	v_mfma_f32_32x32x16_bf16 v[34:49], v[182:185], v[114:117], v[66:81]
	ds_read_b128 v[198:201], v229 offset:13376
	v_exp_f32_e32 v222, v86
	v_exp_f32_e32 v223, v87
	v_add_f32_e32 v164, v222, v164
	v_cvt_pk_bf16_f32 v208, v222, v223
	v_add_f32_e32 v164, v223, v164
	s_waitcnt lgkmcnt(3)
	v_mfma_f32_32x32x16_bf16 v[50:65], v[186:189], v[114:117], v[66:81]
	ds_read_b128 v[182:185], v229 offset:20032
	v_exp_f32_e32 v224, v88
	v_exp_f32_e32 v225, v89
	v_add_f32_e32 v164, v224, v164
	v_cvt_pk_bf16_f32 v209, v224, v225
	v_add_f32_e32 v164, v225, v164
	s_waitcnt lgkmcnt(3)
	v_mfma_f32_32x32x16_bf16 v[34:49], v[190:193], v[118:121], v[34:49]
	ds_read_b128 v[186:189], v229 offset:13408
	v_exp_f32_e32 v222, v90
	v_exp_f32_e32 v223, v91
	v_add_f32_e32 v164, v222, v164
	v_cvt_pk_bf16_f32 v210, v222, v223
	v_add_f32_e32 v164, v223, v164
	s_waitcnt lgkmcnt(3)
	v_mfma_f32_32x32x16_bf16 v[50:65], v[194:197], v[118:121], v[50:65]
	ds_read_b128 v[190:193], v229 offset:20064
	v_exp_f32_e32 v224, v92
	v_exp_f32_e32 v225, v93
	v_add_f32_e32 v164, v224, v164
	v_cvt_pk_bf16_f32 v211, v224, v225
	v_add_f32_e32 v164, v225, v164
	s_waitcnt lgkmcnt(3)
	v_mfma_f32_32x32x16_bf16 v[34:49], v[198:201], v[122:125], v[34:49]
	ds_read_b128 v[194:197], v229 offset:13440
	v_exp_f32_e32 v222, v94
	v_exp_f32_e32 v223, v95
	v_add_f32_e32 v164, v222, v164
	v_cvt_pk_bf16_f32 v212, v222, v223
	v_add_f32_e32 v164, v223, v164
	s_waitcnt lgkmcnt(3)
	v_mfma_f32_32x32x16_bf16 v[50:65], v[182:185], v[122:125], v[50:65]
	ds_read_b128 v[198:201], v229 offset:20096
	v_exp_f32_e32 v224, v96
	v_exp_f32_e32 v225, v97
	v_add_f32_e32 v164, v224, v164
	v_cvt_pk_bf16_f32 v213, v224, v225
	v_add_f32_e32 v164, v225, v164
	s_waitcnt lgkmcnt(3)
	v_mfma_f32_32x32x16_bf16 v[34:49], v[186:189], v[126:129], v[34:49]
	ds_read_b128 v[182:185], v229 offset:13472
	v_exp_f32_e32 v222, v98
	v_exp_f32_e32 v223, v99
	v_add_f32_e32 v164, v222, v164
	v_cvt_pk_bf16_f32 v214, v222, v223
	v_add_f32_e32 v164, v223, v164
	s_waitcnt lgkmcnt(3)
	v_mfma_f32_32x32x16_bf16 v[50:65], v[190:193], v[126:129], v[50:65]
	ds_read_b128 v[186:189], v229 offset:20128
	v_exp_f32_e32 v224, v100
	v_exp_f32_e32 v225, v101
	v_add_f32_e32 v164, v224, v164
	v_cvt_pk_bf16_f32 v215, v224, v225
	v_add_f32_e32 v164, v225, v164
	s_waitcnt lgkmcnt(3)
	v_mfma_f32_32x32x16_bf16 v[34:49], v[194:197], v[130:133], v[34:49]
	ds_read_b128 v[190:193], v228 offset:35840
	v_exp_f32_e32 v222, v102
	v_exp_f32_e32 v223, v103
	v_add_f32_e32 v164, v222, v164
	v_cvt_pk_bf16_f32 v216, v222, v223
	v_add_f32_e32 v164, v223, v164
	s_waitcnt lgkmcnt(3)
	v_mfma_f32_32x32x16_bf16 v[50:65], v[198:201], v[130:133], v[50:65]
	ds_read_b128 v[194:197], v228 offset:40448
	v_exp_f32_e32 v224, v104
	v_exp_f32_e32 v225, v105
	v_add_f32_e32 v164, v224, v164
	v_cvt_pk_bf16_f32 v217, v224, v225
	v_add_f32_e32 v164, v225, v164
	s_waitcnt lgkmcnt(3)
	v_mfma_f32_32x32x16_bf16 v[34:49], v[182:185], v[134:137], v[34:49]
	ds_read_b128 v[198:201], v228 offset:35872
	v_exp_f32_e32 v222, v106
	v_exp_f32_e32 v223, v107
	v_add_f32_e32 v164, v222, v164
	v_cvt_pk_bf16_f32 v218, v222, v223
	v_add_f32_e32 v164, v223, v164
	s_waitcnt lgkmcnt(3)
	v_mfma_f32_32x32x16_bf16 v[50:65], v[186:189], v[134:137], v[50:65]
	ds_read_b128 v[182:185], v228 offset:40480
	v_exp_f32_e32 v224, v108
	v_exp_f32_e32 v225, v109
	v_add_f32_e32 v164, v224, v164
	v_cvt_pk_bf16_f32 v219, v224, v225
	v_add_f32_e32 v164, v225, v164
	s_waitcnt lgkmcnt(3)
	v_mfma_f32_32x32x16_bf16 v[2:17], v[190:193], v[206:209], v[2:17]
	ds_read_b128 v[186:189], v228 offset:35904
	v_exp_f32_e32 v222, v110
	v_exp_f32_e32 v223, v111
	v_add_f32_e32 v164, v222, v164
	v_cvt_pk_bf16_f32 v220, v222, v223
	v_add_f32_e32 v164, v223, v164
	s_waitcnt lgkmcnt(3)
	v_mfma_f32_32x32x16_bf16 v[18:33], v[194:197], v[206:209], v[18:33]
	ds_read_b128 v[190:193], v228 offset:40512
	v_exp_f32_e32 v224, v112
	v_exp_f32_e32 v225, v113
	v_add_f32_e32 v164, v224, v164
	v_cvt_pk_bf16_f32 v221, v224, v225
	v_add_f32_e32 v164, v225, v164
	s_mov_b32 s13, s20
	s_mov_b32 s20, s19
	s_add_i32 s19, s19, 1
	s_cmp_eq_u32 s19, s9
	s_cselect_b32 s19, 0, s19
	s_waitcnt lgkmcnt(3)
	v_mfma_f32_32x32x16_bf16 v[2:17], v[198:201], v[210:213], v[2:17]
	ds_read_b128 v[194:197], v228 offset:35936
	v_max3_f32 v224, v34, v35, v36
	v_max3_f32 v225, v50, v51, v52
	v_max3_f32 v224, v224, v37, v38
	v_max3_f32 v225, v225, v53, v54
	s_waitcnt vmcnt(2)
	ds_write_b128 v172, v[150:153] offset:22528
	v_lshl_add_u32 v222, s19, 17, v178
	global_load_dwordx4 v[150:153], v222, s[52:53]
	s_waitcnt lgkmcnt(4)
	v_mfma_f32_32x32x16_bf16 v[18:33], v[182:185], v[210:213], v[18:33]
	ds_read_b128 v[198:201], v228 offset:40544
	v_max3_f32 v224, v224, v39, v40
	v_max3_f32 v225, v225, v55, v56
	v_max3_f32 v224, v224, v41, v42
	v_max3_f32 v225, v225, v57, v58
	s_and_b64 vcc, exec, s[2:3]
	s_cbranch_vccz .Lmla_p17_nope
	ds_write_b128 v176, v[160:163] offset:22656
	v_lshl_add_u32 v222, s19, 12, v179
	global_load_dwordx4 v[160:163], v222, s[62:63]
.Lmla_p17_nope:
	s_waitcnt lgkmcnt(4)
	v_mfma_f32_32x32x16_bf16 v[2:17], v[186:189], v[214:217], v[2:17]
	ds_read_b128 v[182:185], v229 offset:26624
	v_max3_f32 v224, v224, v43, v44
	v_max3_f32 v225, v225, v59, v60
	v_max3_f32 v224, v224, v45, v46
	v_max3_f32 v225, v225, v61, v62
	v_add_u32_e32 v222, 0xb000, v173
	ds_write_b128 v222, v[202:205] offset:49152
	v_lshl_add_u32 v222, s13, 7, v168
	global_load_dwordx4 v[202:205], v222, s[56:57]
	s_waitcnt lgkmcnt(5)
	v_mfma_f32_32x32x16_bf16 v[18:33], v[190:193], v[214:217], v[18:33]
	ds_read_b128 v[186:189], v229 offset:33280
	v_max3_f32 v224, v224, v47, v48
	v_max3_f32 v225, v225, v63, v64
	v_max3_f32 v224, v224, v49, v65
	v_max_f32_e32 v224, v224, v225
	s_waitcnt lgkmcnt(5)
	v_mfma_f32_32x32x16_bf16 v[2:17], v[194:197], v[218:221], v[2:17]
	ds_read_b128 v[190:193], v229 offset:26656
	v_mov_b32_e32 v225, v224
	v_add_f32_e32 v1, v1, v164
	s_add_i32 s11, s11, 1
	v_permlane32_swap_b32_e32 v224, v225
	s_cmp_eq_u32 s9, s11
	v_max_f32_e32 v167, v224, v225
	s_waitcnt lgkmcnt(4)
	v_mfma_f32_32x32x16_bf16 v[18:33], v[198:201], v[218:221], v[18:33]
	ds_read_b128 v[194:197], v229 offset:33312
	v_cmp_lt_f32_e32 vcc, s66, v167
	s_waitcnt lgkmcnt(3)
	s_barrier
	s_cbranch_scc1 .Lmla_exit_p17

; template <int VAR>
; __device__ __forceinline__ void attn_phase(LAS unsigned char* lds, const AttnP P, int vcu, int G, int wave_s) {
;     ...
;                 if (ND0 == 6) {
;                     KR1(0); KR1(1); KR1(2); KR1(3); SB();
;                     QK1(0, negm); EX2(pc0, 0, w0.x); KR1(4); SB();
;                     QK1(1, negm); EX2(pc0, 2, w0.y); KR1(5); SB();
;                     QK1(2, pn0); EX2(pc0, 4, w0.z); KR1(6); SB();
;                     QK1(3, pn1); EX2(pc0, 6, w0.w); KR1(7); SB();
;                     QK1(4, pn0); EX2(pc0, 8, w1.x); KR1(8); SB();
;                     QK1(5, pn1); EX2(pc0, 10, w1.y); KR1(9); SB();
;                     QK1(6, pn0); EX2(pc0, 12, w1.z); KR1(10); SB();
;                     QK1(7, pn1); EX2(pc0, 14, w1.w); KR1(11); SB();
;                     QK1(8, pn0); EX2(pc1, 0, w2.x); VR1(0); SB();
;                     QK1(9, pn1); EX2(pc1, 2, w2.y); VR1(1); SB();
;                     QK1(10, pn0); EX2(pc1, 4, w2.z); VR1(2); SB();
;                     QK1(11, pn1); EX2(pc1, 6, w2.w); VR1(3); SB();
;                 } else {
;                     KR1(0); KR1(1); KR1(2); KR1(3); SB();
;                     QK1(0, negm); EX2(pc0, 0, w0.x); EX2(pc0, 2, w0.y); KR1(4); SB();
;                     QK1(1, negm); EX2(pc0, 4, w0.z); EX2(pc0, 6, w0.w); KR1(5); SB();
;                     QK1(2, pn0); EX2(pc0, 8, w1.x); EX2(pc0, 10, w1.y); KR1(6); SB();
;                     QK1(3, pn1); EX2(pc0, 12, w1.z); EX2(pc0, 14, w1.w); KR1(7); SB();
;                     QK1(4, pn0); EX2(pc1, 0, w2.x); VR1(0); SB();
;                     QK1(5, pn1); EX2(pc1, 2, w2.y); VR1(1); SB();
;                     QK1(6, pn0); EX2(pc1, 4, w2.z); VR1(2); SB();
;                     QK1(7, pn1); EX2(pc1, 6, w2.w); VR1(3); SB();
;                 }
;                 PV1(0, w0); EX2(pc1, 8, w3.x); VR1(4); SB();
;                 PV1(1, w0); EX2(pc1, 10, w3.y); VR1(5); SB();
;                 PV1(2, w1); EX2(pc1, 12, w3.z); VR1(6); SB();
;                 PV1(3, w1); EX2(pc1, 14, w3.w); VR1(7); SB();
;                 lrun += sacc;
;                 PV1(4, w2); MASK_TILE(pn0, pn1, t + 1); SB();
;                 PV1(5, w2); SB();
;                 PV1(6, w3); SB();
;                 PV1(7, w3); rmn = rowmax32(pn0, pn1); if (!USE_NEGM) rmn -= mref; SB();
;     ...
;             if (hn) { STOREK(t & 1); STOREV((t + 1) & 1); }
;             __syncthreads();
.Lmla_p18_go:
	v_exp_f32_e32 v222, v34
	v_exp_f32_e32 v223, v35
	v_add_f32_e32 v164, 0, v222
	v_cvt_pk_bf16_f32 v206, v222, v223
	v_add_f32_e32 v164, v223, v164
	v_exp_f32_e32 v224, v36
	v_exp_f32_e32 v225, v37
	v_add_f32_e32 v164, v224, v164
	v_cvt_pk_bf16_f32 v207, v224, v225
	v_add_f32_e32 v164, v225, v164
	s_waitcnt lgkmcnt(3)
	v_mfma_f32_32x32x16_bf16 v[82:97], v[182:185], v[114:117], v[66:81]
	ds_read_b128 v[198:201], v229 offset:26688
	v_exp_f32_e32 v222, v38
	v_exp_f32_e32 v223, v39
	v_add_f32_e32 v164, v222, v164
	v_cvt_pk_bf16_f32 v208, v222, v223
	v_add_f32_e32 v164, v223, v164
	s_waitcnt lgkmcnt(3)
	v_mfma_f32_32x32x16_bf16 v[98:113], v[186:189], v[114:117], v[66:81]
	ds_read_b128 v[182:185], v229 offset:33344
	v_exp_f32_e32 v224, v40
	v_exp_f32_e32 v225, v41
	v_add_f32_e32 v164, v224, v164
	v_cvt_pk_bf16_f32 v209, v224, v225
	v_add_f32_e32 v164, v225, v164
	s_waitcnt lgkmcnt(3)
	v_mfma_f32_32x32x16_bf16 v[82:97], v[190:193], v[118:121], v[82:97]
	ds_read_b128 v[186:189], v229 offset:26720
	v_exp_f32_e32 v222, v42
	v_exp_f32_e32 v223, v43
	v_add_f32_e32 v164, v222, v164
	v_cvt_pk_bf16_f32 v210, v222, v223
	v_add_f32_e32 v164, v223, v164
	s_waitcnt lgkmcnt(3)
	v_mfma_f32_32x32x16_bf16 v[98:113], v[194:197], v[118:121], v[98:113]
	ds_read_b128 v[190:193], v229 offset:33376
	v_exp_f32_e32 v224, v44
	v_exp_f32_e32 v225, v45
	v_add_f32_e32 v164, v224, v164
	v_cvt_pk_bf16_f32 v211, v224, v225
	v_add_f32_e32 v164, v225, v164
	s_waitcnt lgkmcnt(3)
	v_mfma_f32_32x32x16_bf16 v[82:97], v[198:201], v[122:125], v[82:97]
	ds_read_b128 v[194:197], v229 offset:26752
	v_exp_f32_e32 v222, v46
	v_exp_f32_e32 v223, v47
	v_add_f32_e32 v164, v222, v164
	v_cvt_pk_bf16_f32 v212, v222, v223
	v_add_f32_e32 v164, v223, v164
	s_waitcnt lgkmcnt(3)
	v_mfma_f32_32x32x16_bf16 v[98:113], v[182:185], v[122:125], v[98:113]
	ds_read_b128 v[198:201], v229 offset:33408
	v_exp_f32_e32 v224, v48
	v_exp_f32_e32 v225, v49
	v_add_f32_e32 v164, v224, v164
	v_cvt_pk_bf16_f32 v213, v224, v225
	v_add_f32_e32 v164, v225, v164
	s_waitcnt lgkmcnt(3)
	v_mfma_f32_32x32x16_bf16 v[82:97], v[186:189], v[126:129], v[82:97]
	ds_read_b128 v[182:185], v229 offset:26784
	v_exp_f32_e32 v222, v50
	v_exp_f32_e32 v223, v51
	v_add_f32_e32 v164, v222, v164
	v_cvt_pk_bf16_f32 v214, v222, v223
	v_add_f32_e32 v164, v223, v164
	s_waitcnt lgkmcnt(3)
	v_mfma_f32_32x32x16_bf16 v[98:113], v[190:193], v[126:129], v[98:113]
	ds_read_b128 v[186:189], v229 offset:33440
	v_exp_f32_e32 v224, v52
	v_exp_f32_e32 v225, v53
	v_add_f32_e32 v164, v224, v164
	v_cvt_pk_bf16_f32 v215, v224, v225
	v_add_f32_e32 v164, v225, v164
	s_waitcnt lgkmcnt(3)
	v_mfma_f32_32x32x16_bf16 v[82:97], v[194:197], v[130:133], v[82:97]
	ds_read_b128 v[190:193], v181 offset:39936
	v_exp_f32_e32 v222, v54
	v_exp_f32_e32 v223, v55
	v_add_f32_e32 v164, v222, v164
	v_cvt_pk_bf16_f32 v216, v222, v223
	v_add_f32_e32 v164, v223, v164
	s_waitcnt lgkmcnt(3)
	v_mfma_f32_32x32x16_bf16 v[98:113], v[198:201], v[130:133], v[98:113]
	ds_read_b128 v[194:197], v181 offset:44544
	v_exp_f32_e32 v224, v56
	v_exp_f32_e32 v225, v57
	v_add_f32_e32 v164, v224, v164
	v_cvt_pk_bf16_f32 v217, v224, v225
	v_add_f32_e32 v164, v225, v164
	s_waitcnt lgkmcnt(3)
	v_mfma_f32_32x32x16_bf16 v[82:97], v[182:185], v[134:137], v[82:97]
	ds_read_b128 v[198:201], v181 offset:39968
	v_exp_f32_e32 v222, v58
	v_exp_f32_e32 v223, v59
	v_add_f32_e32 v164, v222, v164
	v_cvt_pk_bf16_f32 v218, v222, v223
	v_add_f32_e32 v164, v223, v164
	s_waitcnt lgkmcnt(3)
	v_mfma_f32_32x32x16_bf16 v[98:113], v[186:189], v[134:137], v[98:113]
	ds_read_b128 v[182:185], v181 offset:44576
	v_exp_f32_e32 v224, v60
	v_exp_f32_e32 v225, v61
	v_add_f32_e32 v164, v224, v164
	v_cvt_pk_bf16_f32 v219, v224, v225
	v_add_f32_e32 v164, v225, v164
	s_waitcnt lgkmcnt(3)
	v_mfma_f32_32x32x16_bf16 v[2:17], v[190:193], v[206:209], v[2:17]
	ds_read_b128 v[186:189], v181 offset:40000
	v_exp_f32_e32 v222, v62
	v_exp_f32_e32 v223, v63
	v_add_f32_e32 v164, v222, v164
	v_cvt_pk_bf16_f32 v220, v222, v223
	v_add_f32_e32 v164, v223, v164
	s_waitcnt lgkmcnt(3)
	v_mfma_f32_32x32x16_bf16 v[18:33], v[194:197], v[206:209], v[18:33]
	ds_read_b128 v[190:193], v181 offset:44608
	v_exp_f32_e32 v224, v64
	v_exp_f32_e32 v225, v65
	v_add_f32_e32 v164, v224, v164
	v_cvt_pk_bf16_f32 v221, v224, v225
	v_add_f32_e32 v164, v225, v164
	s_mov_b32 s13, s20
	s_mov_b32 s20, s19
	s_add_i32 s19, s19, 1
	s_cmp_eq_u32 s19, s9
	s_cselect_b32 s19, 0, s19
	s_waitcnt lgkmcnt(3)
	v_mfma_f32_32x32x16_bf16 v[2:17], v[198:201], v[210:213], v[2:17]
	ds_read_b128 v[194:197], v181 offset:40032
	v_max3_f32 v224, v82, v83, v84
	v_max3_f32 v225, v98, v99, v100
	v_max3_f32 v224, v224, v85, v86
	v_max3_f32 v225, v225, v101, v102
	s_waitcnt vmcnt(2)
	ds_write_b128 v172, v[146:149] offset:45056
	v_lshl_add_u32 v222, s19, 17, v178
	global_load_dwordx4 v[146:149], v222, s[52:53]
	s_waitcnt lgkmcnt(4)
	v_mfma_f32_32x32x16_bf16 v[18:33], v[182:185], v[210:213], v[18:33]
	ds_read_b128 v[198:201], v181 offset:44640
	v_max3_f32 v224, v224, v87, v88
	v_max3_f32 v225, v225, v103, v104
	v_max3_f32 v224, v224, v89, v90
	v_max3_f32 v225, v225, v105, v106
	s_and_b64 vcc, exec, s[2:3]
	s_cbranch_vccz .Lmla_p18_nope
	ds_write_b128 v176, v[138:141] offset:45184
	v_lshl_add_u32 v222, s19, 12, v179
	global_load_dwordx4 v[138:141], v222, s[62:63]
.Lmla_p18_nope:
	s_waitcnt lgkmcnt(4)
	v_mfma_f32_32x32x16_bf16 v[2:17], v[186:189], v[214:217], v[2:17]
	ds_read_b128 v[182:185], v174
	v_max3_f32 v224, v224, v91, v92
	v_max3_f32 v225, v225, v107, v108
	v_max3_f32 v224, v224, v93, v94
	v_max3_f32 v225, v225, v109, v110
	ds_write_b128 v173, v[142:145] offset:13312
	v_lshl_add_u32 v222, s13, 7, v168
	global_load_dwordx4 v[142:145], v222, s[56:57]
	s_waitcnt lgkmcnt(5)
	v_mfma_f32_32x32x16_bf16 v[18:33], v[190:193], v[214:217], v[18:33]
	ds_read_b128 v[186:189], v174 offset:6656
	v_max3_f32 v224, v224, v95, v96
	v_max3_f32 v225, v225, v111, v112
	v_max3_f32 v224, v224, v97, v113
	v_max_f32_e32 v224, v224, v225
	s_waitcnt lgkmcnt(5)
	v_mfma_f32_32x32x16_bf16 v[2:17], v[194:197], v[218:221], v[2:17]
	ds_read_b128 v[190:193], v174 offset:32
	v_mov_b32_e32 v225, v224
	v_add_f32_e32 v1, v1, v164
	s_add_i32 s11, s11, 1
	v_permlane32_swap_b32_e32 v224, v225
	s_cmp_eq_u32 s9, s11
	v_max_f32_e32 v167, v224, v225
	s_waitcnt lgkmcnt(4)
	v_mfma_f32_32x32x16_bf16 v[18:33], v[198:201], v[218:221], v[18:33]
	ds_read_b128 v[194:197], v174 offset:6688
	v_cmp_lt_f32_e32 vcc, s66, v167
	s_cbranch_scc1 .Lmla_exit_p18

; template <int VAR>
; __device__ __forceinline__ void attn_phase(LAS unsigned char* lds, const AttnP P, int vcu, int G, int wave_s) {
;     ...
;                 if (ND0 == 6) {
;                     KR1(0); KR1(1); KR1(2); KR1(3); SB();
;                     QK1(0, negm); EX2(pc0, 0, w0.x); KR1(4); SB();
;                     QK1(1, negm); EX2(pc0, 2, w0.y); KR1(5); SB();
;                     QK1(2, pn0); EX2(pc0, 4, w0.z); KR1(6); SB();
;                     QK1(3, pn1); EX2(pc0, 6, w0.w); KR1(7); SB();
;                     QK1(4, pn0); EX2(pc0, 8, w1.x); KR1(8); SB();
;                     QK1(5, pn1); EX2(pc0, 10, w1.y); KR1(9); SB();
;                     QK1(6, pn0); EX2(pc0, 12, w1.z); KR1(10); SB();
;                     QK1(7, pn1); EX2(pc0, 14, w1.w); KR1(11); SB();
;                     QK1(8, pn0); EX2(pc1, 0, w2.x); VR1(0); SB();
;                     QK1(9, pn1); EX2(pc1, 2, w2.y); VR1(1); SB();
;                     QK1(10, pn0); EX2(pc1, 4, w2.z); VR1(2); SB();
;                     QK1(11, pn1); EX2(pc1, 6, w2.w); VR1(3); SB();
;                 } else {
;                     KR1(0); KR1(1); KR1(2); KR1(3); SB();
;                     QK1(0, negm); EX2(pc0, 0, w0.x); EX2(pc0, 2, w0.y); KR1(4); SB();
;                     QK1(1, negm); EX2(pc0, 4, w0.z); EX2(pc0, 6, w0.w); KR1(5); SB();
;                     QK1(2, pn0); EX2(pc0, 8, w1.x); EX2(pc0, 10, w1.y); KR1(6); SB();
;                     QK1(3, pn1); EX2(pc0, 12, w1.z); EX2(pc0, 14, w1.w); KR1(7); SB();
;                     QK1(4, pn0); EX2(pc1, 0, w2.x); VR1(0); SB();
;                     QK1(5, pn1); EX2(pc1, 2, w2.y); VR1(1); SB();
;                     QK1(6, pn0); EX2(pc1, 4, w2.z); VR1(2); SB();
;                     QK1(7, pn1); EX2(pc1, 6, w2.w); VR1(3); SB();
;                 }
;                 PV1(0, w0); EX2(pc1, 8, w3.x); VR1(4); SB();
;                 PV1(1, w0); EX2(pc1, 10, w3.y); VR1(5); SB();
;                 PV1(2, w1); EX2(pc1, 12, w3.z); VR1(6); SB();
;                 PV1(3, w1); EX2(pc1, 14, w3.w); VR1(7); SB();
;                 lrun += sacc;
;                 PV1(4, w2); MASK_TILE(pn0, pn1, t + 1); SB();
;                 PV1(5, w2); SB();
;                 PV1(6, w3); SB();
;                 PV1(7, w3); rmn = rowmax32(pn0, pn1); if (!USE_NEGM) rmn -= mref; SB();
;     ...
;             if (hn) { STOREK(t & 1); STOREV((t + 1) & 1); }
;             __syncthreads();
.Lmla_p19_go:
	v_exp_f32_e32 v222, v82
	v_exp_f32_e32 v223, v83
	v_add_f32_e32 v164, 0, v222
	v_cvt_pk_bf16_f32 v206, v222, v223
	v_add_f32_e32 v164, v223, v164
	v_exp_f32_e32 v224, v84
	v_exp_f32_e32 v225, v85
	v_add_f32_e32 v164, v224, v164
	v_cvt_pk_bf16_f32 v207, v224, v225
	v_add_f32_e32 v164, v225, v164
	s_waitcnt lgkmcnt(4)
	v_mfma_f32_32x32x16_bf16 v[34:49], v[182:185], v[114:117], v[66:81]
	ds_read_b128 v[198:201], v174 offset:64
	v_exp_f32_e32 v222, v86
	v_exp_f32_e32 v223, v87
	v_add_f32_e32 v164, v222, v164
	v_cvt_pk_bf16_f32 v208, v222, v223
	v_add_f32_e32 v164, v223, v164
	s_waitcnt lgkmcnt(3)
	v_mfma_f32_32x32x16_bf16 v[50:65], v[186:189], v[114:117], v[66:81]
	ds_read_b128 v[182:185], v174 offset:6720
	v_exp_f32_e32 v224, v88
	v_exp_f32_e32 v225, v89
	v_add_f32_e32 v164, v224, v164
	v_cvt_pk_bf16_f32 v209, v224, v225
	v_add_f32_e32 v164, v225, v164
	s_waitcnt lgkmcnt(3)
	v_mfma_f32_32x32x16_bf16 v[34:49], v[190:193], v[118:121], v[34:49]
	ds_read_b128 v[186:189], v174 offset:96
	v_exp_f32_e32 v222, v90
	v_exp_f32_e32 v223, v91
	v_add_f32_e32 v164, v222, v164
	v_cvt_pk_bf16_f32 v210, v222, v223
	v_add_f32_e32 v164, v223, v164
	s_waitcnt lgkmcnt(3)
	v_mfma_f32_32x32x16_bf16 v[50:65], v[194:197], v[118:121], v[50:65]
	ds_read_b128 v[190:193], v174 offset:6752
	v_exp_f32_e32 v224, v92
	v_exp_f32_e32 v225, v93
	v_add_f32_e32 v164, v224, v164
	v_cvt_pk_bf16_f32 v211, v224, v225
	v_add_f32_e32 v164, v225, v164
	s_waitcnt lgkmcnt(3)
	v_mfma_f32_32x32x16_bf16 v[34:49], v[198:201], v[122:125], v[34:49]
	ds_read_b128 v[194:197], v174 offset:128
	v_exp_f32_e32 v222, v94
	v_exp_f32_e32 v223, v95
	v_add_f32_e32 v164, v222, v164
	v_cvt_pk_bf16_f32 v212, v222, v223
	v_add_f32_e32 v164, v223, v164
	s_waitcnt lgkmcnt(3)
	v_mfma_f32_32x32x16_bf16 v[50:65], v[182:185], v[122:125], v[50:65]
	ds_read_b128 v[198:201], v174 offset:6784
	v_exp_f32_e32 v224, v96
	v_exp_f32_e32 v225, v97
	v_add_f32_e32 v164, v224, v164
	v_cvt_pk_bf16_f32 v213, v224, v225
	v_add_f32_e32 v164, v225, v164
	s_waitcnt lgkmcnt(3)
	v_mfma_f32_32x32x16_bf16 v[34:49], v[186:189], v[126:129], v[34:49]
	ds_read_b128 v[182:185], v174 offset:160
	v_exp_f32_e32 v222, v98
	v_exp_f32_e32 v223, v99
	v_add_f32_e32 v164, v222, v164
	v_cvt_pk_bf16_f32 v214, v222, v223
	v_add_f32_e32 v164, v223, v164
	s_waitcnt lgkmcnt(3)
	v_mfma_f32_32x32x16_bf16 v[50:65], v[190:193], v[126:129], v[50:65]
	ds_read_b128 v[186:189], v174 offset:6816
	v_exp_f32_e32 v224, v100
	v_exp_f32_e32 v225, v101
	v_add_f32_e32 v164, v224, v164
	v_cvt_pk_bf16_f32 v215, v224, v225
	v_add_f32_e32 v164, v225, v164
	s_waitcnt lgkmcnt(3)
	v_mfma_f32_32x32x16_bf16 v[34:49], v[194:197], v[130:133], v[34:49]
	ds_read_b128 v[190:193], v181 offset:49152
	v_exp_f32_e32 v222, v102
	v_exp_f32_e32 v223, v103
	v_add_f32_e32 v164, v222, v164
	v_cvt_pk_bf16_f32 v216, v222, v223
	v_add_f32_e32 v164, v223, v164
	s_waitcnt lgkmcnt(3)
	v_mfma_f32_32x32x16_bf16 v[50:65], v[198:201], v[130:133], v[50:65]
	ds_read_b128 v[194:197], v181 offset:53760
	v_exp_f32_e32 v224, v104
	v_exp_f32_e32 v225, v105
	v_add_f32_e32 v164, v224, v164
	v_cvt_pk_bf16_f32 v217, v224, v225
	v_add_f32_e32 v164, v225, v164
	s_waitcnt lgkmcnt(3)
	v_mfma_f32_32x32x16_bf16 v[34:49], v[182:185], v[134:137], v[34:49]
	ds_read_b128 v[198:201], v181 offset:49184
	v_exp_f32_e32 v222, v106
	v_exp_f32_e32 v223, v107
	v_add_f32_e32 v164, v222, v164
	v_cvt_pk_bf16_f32 v218, v222, v223
	v_add_f32_e32 v164, v223, v164
	s_waitcnt lgkmcnt(3)
	v_mfma_f32_32x32x16_bf16 v[50:65], v[186:189], v[134:137], v[50:65]
	ds_read_b128 v[182:185], v181 offset:53792
	v_exp_f32_e32 v224, v108
	v_exp_f32_e32 v225, v109
	v_add_f32_e32 v164, v224, v164
	v_cvt_pk_bf16_f32 v219, v224, v225
	v_add_f32_e32 v164, v225, v164
	s_waitcnt lgkmcnt(3)
	v_mfma_f32_32x32x16_bf16 v[2:17], v[190:193], v[206:209], v[2:17]
	ds_read_b128 v[186:189], v181 offset:49216
	v_exp_f32_e32 v222, v110
	v_exp_f32_e32 v223, v111
	v_add_f32_e32 v164, v222, v164
	v_cvt_pk_bf16_f32 v220, v222, v223
	v_add_f32_e32 v164, v223, v164
	s_waitcnt lgkmcnt(3)
	v_mfma_f32_32x32x16_bf16 v[18:33], v[194:197], v[206:209], v[18:33]
	ds_read_b128 v[190:193], v181 offset:53824
	v_exp_f32_e32 v224, v112
	v_exp_f32_e32 v225, v113
	v_add_f32_e32 v164, v224, v164
	v_cvt_pk_bf16_f32 v221, v224, v225
	v_add_f32_e32 v164, v225, v164
	s_mov_b32 s13, s20
	s_mov_b32 s20, s19
	s_add_i32 s19, s19, 1
	s_cmp_eq_u32 s19, s9
	s_cselect_b32 s19, 0, s19
	s_waitcnt lgkmcnt(3)
	v_mfma_f32_32x32x16_bf16 v[2:17], v[198:201], v[210:213], v[2:17]
	ds_read_b128 v[194:197], v181 offset:49248
	v_max3_f32 v224, v34, v35, v36
	v_max3_f32 v225, v50, v51, v52
	v_max3_f32 v224, v224, v37, v38
	v_max3_f32 v225, v225, v53, v54
	s_waitcnt vmcnt(2)
	ds_write_b128 v172, v[150:153] offset:58368
	v_lshl_add_u32 v222, s19, 17, v178
	global_load_dwordx4 v[150:153], v222, s[52:53]
	s_waitcnt lgkmcnt(4)
	v_mfma_f32_32x32x16_bf16 v[18:33], v[182:185], v[210:213], v[18:33]
	ds_read_b128 v[198:201], v181 offset:53856
	v_max3_f32 v224, v224, v39, v40
	v_max3_f32 v225, v225, v55, v56
	v_max3_f32 v224, v224, v41, v42
	v_max3_f32 v225, v225, v57, v58
	s_and_b64 vcc, exec, s[2:3]
	s_cbranch_vccz .Lmla_p19_nope
	ds_write_b128 v176, v[160:163] offset:58496
	v_lshl_add_u32 v222, s19, 12, v179
	global_load_dwordx4 v[160:163], v222, s[62:63]

; #define STOREK(buf) do { LAS unsigned char* kb_ = lds + (buf) * ABUF; *(LAS u32x4*)(kb_ + (tid >> 3) * KP + (tid & 7) * 16) = kreg; \
;         if (VAR == 0 && tid < 256) *(LAS u32x4*)(kb_ + (tid >> 2) * KP + 128 + (tid & 3) * 16) = pereg; } while (0)
; #define STOREV(buf) do { *(LAS u32x4*)(lds + (buf) * ABUF + KT_BYTES + (tid >> 3) * VP + (tid & 7) * 16) = vreg; } while (0)
; template <int VAR>
; __device__ __forceinline__ void attn_phase(LAS unsigned char* lds, const AttnP P, int vcu, int G, int wave_s) {
;     ...
;             if (hn) { STOREK(t & 1); STOREV((t + 1) & 1); }
;             __syncthreads();
;             pc0 = pn0; pc1 = pn1; rmc = rmn; need_c = need_n;
;         }
.Lmla_exit_p2:
	s_setprio 0
	v_mov_b64_e32 v[34:35], v[82:83]
	v_mov_b64_e32 v[36:37], v[84:85]
	v_mov_b64_e32 v[38:39], v[86:87]
	v_mov_b64_e32 v[40:41], v[88:89]
	v_mov_b64_e32 v[42:43], v[90:91]
	v_mov_b64_e32 v[44:45], v[92:93]
	v_mov_b64_e32 v[46:47], v[94:95]
	v_mov_b64_e32 v[48:49], v[96:97]
	v_mov_b64_e32 v[50:51], v[98:99]
	v_mov_b64_e32 v[52:53], v[100:101]
	v_mov_b64_e32 v[54:55], v[102:103]
	v_mov_b64_e32 v[56:57], v[104:105]
	v_mov_b64_e32 v[58:59], v[106:107]
	v_mov_b64_e32 v[60:61], v[108:109]
	v_mov_b64_e32 v[62:63], v[110:111]
	v_mov_b64_e32 v[64:65], v[112:113]
	v_mov_b32_e32 v82, v167
	s_mov_b32 s11, 0x13c00
	s_waitcnt vmcnt(0) lgkmcnt(0)
	s_branch .LBB0_1185

; #define STOREK(buf) do { LAS unsigned char* kb_ = lds + (buf) * ABUF; *(LAS u32x4*)(kb_ + (tid >> 3) * KP + (tid & 7) * 16) = kreg; \
;         if (VAR == 0 && tid < 256) *(LAS u32x4*)(kb_ + (tid >> 2) * KP + 128 + (tid & 3) * 16) = pereg; } while (0)
; #define STOREV(buf) do { *(LAS u32x4*)(lds + (buf) * ABUF + KT_BYTES + (tid >> 3) * VP + (tid & 7) * 16) = vreg; } while (0)
; template <int VAR>
; __device__ __forceinline__ void attn_phase(LAS unsigned char* lds, const AttnP P, int vcu, int G, int wave_s) {
;     ...
;             if (hn) { STOREK(t & 1); STOREV((t + 1) & 1); }
;             __syncthreads();
;             pc0 = pn0; pc1 = pn1; rmc = rmn; need_c = need_n;
;         }
.Lmla_exit_p1:
	s_setprio 0
	v_mov_b32_e32 v82, v167
	s_mov_b32 s11, 0x11800
	s_waitcnt vmcnt(0) lgkmcnt(0)
	s_branch .LBB0_1185

; template <int VAR>
; __device__ __forceinline__ void attn_phase(LAS unsigned char* lds, const AttnP P, int vcu, int G, int wave_s) {
;     ...
;             if (need_c && __any(rmc > THR)) {
;                 const float dl = __builtin_fmaxf(rmc, 0.f), f = __builtin_amdgcn_exp2f(-dl);
;                 mref += dl; lrun *= f;
; #pragma unroll
;                 for (int r = 0; r < 16; ++r) { if (USE_NEGM) { pc0[r] -= dl; pc1[r] -= dl; negm[r] = -mref; } o0[r] *= f; o1[r] *= f; }
;             }
.Lmla_p0_resc:
	v_max_f32_e32 v224, v167, v167
	v_max_f32_e32 v224, 0, v224
	v_exp_f32_e64 v225, -v224
	v_add_f32_e32 v180, v180, v224
	v_sub_f32_e32 v34, v34, v224
	v_sub_f32_e32 v35, v35, v224
	v_sub_f32_e32 v36, v36, v224
	v_sub_f32_e32 v37, v37, v224
	v_sub_f32_e32 v38, v38, v224
	v_sub_f32_e32 v39, v39, v224
	v_sub_f32_e32 v40, v40, v224
	v_sub_f32_e32 v41, v41, v224
	v_sub_f32_e32 v42, v42, v224
	v_sub_f32_e32 v43, v43, v224
	v_sub_f32_e32 v44, v44, v224
	v_sub_f32_e32 v45, v45, v224
	v_sub_f32_e32 v46, v46, v224
	v_sub_f32_e32 v47, v47, v224
	v_sub_f32_e32 v48, v48, v224
	v_sub_f32_e32 v49, v49, v224
	v_sub_f32_e32 v50, v50, v224
	v_sub_f32_e32 v51, v51, v224
	v_sub_f32_e32 v52, v52, v224
	v_sub_f32_e32 v53, v53, v224
	v_sub_f32_e32 v54, v54, v224
	v_sub_f32_e32 v55, v55, v224
	v_sub_f32_e32 v56, v56, v224
	v_sub_f32_e32 v57, v57, v224
	v_sub_f32_e32 v58, v58, v224
	v_sub_f32_e32 v59, v59, v224
	v_sub_f32_e32 v60, v60, v224
	v_sub_f32_e32 v61, v61, v224
	v_sub_f32_e32 v62, v62, v224
	v_sub_f32_e32 v63, v63, v224
	v_sub_f32_e32 v64, v64, v224
	v_sub_f32_e32 v65, v65, v224
	v_mul_f32_e32 v2, v2, v225
	v_mul_f32_e32 v3, v3, v225
	v_mul_f32_e32 v4, v4, v225
	v_mul_f32_e32 v5, v5, v225
	v_mul_f32_e32 v6, v6, v225
	v_mul_f32_e32 v7, v7, v225
	v_mul_f32_e32 v8, v8, v225
	v_mul_f32_e32 v9, v9, v225
	v_mul_f32_e32 v10, v10, v225
	v_mul_f32_e32 v11, v11, v225
	v_mul_f32_e32 v12, v12, v225
	v_mul_f32_e32 v13, v13, v225
	v_mul_f32_e32 v14, v14, v225
	v_mul_f32_e32 v15, v15, v225
	v_mul_f32_e32 v16, v16, v225
	v_mul_f32_e32 v17, v17, v225
	v_mul_f32_e32 v18, v18, v225
	v_mul_f32_e32 v19, v19, v225
	v_mul_f32_e32 v20, v20, v225
	v_mul_f32_e32 v21, v21, v225
	v_mul_f32_e32 v22, v22, v225
	v_mul_f32_e32 v23, v23, v225
	v_mul_f32_e32 v24, v24, v225
	v_mul_f32_e32 v25, v25, v225
	v_mul_f32_e32 v26, v26, v225
	v_mul_f32_e32 v27, v27, v225
	v_mul_f32_e32 v28, v28, v225
	v_mul_f32_e32 v29, v29, v225
	v_mul_f32_e32 v30, v30, v225
	v_mul_f32_e32 v31, v31, v225
	v_mul_f32_e32 v32, v32, v225
	v_mul_f32_e32 v33, v33, v225
	v_mul_f32_e32 v1, v1, v225
	v_xor_b32_e32 v66, 0x80000000, v180
	v_mov_b32_e32 v67, v66
	v_mov_b32_e32 v68, v66
	v_mov_b32_e32 v69, v66
	v_mov_b32_e32 v70, v66
	v_mov_b32_e32 v71, v66
	v_mov_b32_e32 v72, v66
	v_mov_b32_e32 v73, v66
	v_mov_b32_e32 v74, v66
	v_mov_b32_e32 v75, v66
	v_mov_b32_e32 v76, v66
	v_mov_b32_e32 v77, v66
	v_mov_b32_e32 v78, v66
	v_mov_b32_e32 v79, v66
	v_mov_b32_e32 v80, v66
	v_mov_b32_e32 v81, v66
	s_nop 3
	s_branch .Lmla_p0_go
.Lmla_p1_resc:
	v_max_f32_e32 v224, v167, v167
	v_max_f32_e32 v224, 0, v224
	v_exp_f32_e64 v225, -v224
	v_add_f32_e32 v180, v180, v224
	v_sub_f32_e32 v82, v82, v224
	v_sub_f32_e32 v83, v83, v224
	v_sub_f32_e32 v84, v84, v224
	v_sub_f32_e32 v85, v85, v224
	v_sub_f32_e32 v86, v86, v224
	v_sub_f32_e32 v87, v87, v224
	v_sub_f32_e32 v88, v88, v224
	v_sub_f32_e32 v89, v89, v224
	v_sub_f32_e32 v90, v90, v224
	v_sub_f32_e32 v91, v91, v224
	v_sub_f32_e32 v92, v92, v224
	v_sub_f32_e32 v93, v93, v224
	v_sub_f32_e32 v94, v94, v224
	v_sub_f32_e32 v95, v95, v224
	v_sub_f32_e32 v96, v96, v224
	v_sub_f32_e32 v97, v97, v224
	v_sub_f32_e32 v98, v98, v224
	v_sub_f32_e32 v99, v99, v224
	v_sub_f32_e32 v100, v100, v224
	v_sub_f32_e32 v101, v101, v224
	v_sub_f32_e32 v102, v102, v224
	v_sub_f32_e32 v103, v103, v224
	v_sub_f32_e32 v104, v104, v224
	v_sub_f32_e32 v105, v105, v224
	v_sub_f32_e32 v106, v106, v224
	v_sub_f32_e32 v107, v107, v224
	v_sub_f32_e32 v108, v108, v224
	v_sub_f32_e32 v109, v109, v224
	v_sub_f32_e32 v110, v110, v224
	v_sub_f32_e32 v111, v111, v224
	v_sub_f32_e32 v112, v112, v224
	v_sub_f32_e32 v113, v113, v224
	v_mul_f32_e32 v2, v2, v225
	v_mul_f32_e32 v3, v3, v225
	v_mul_f32_e32 v4, v4, v225
	v_mul_f32_e32 v5, v5, v225
	v_mul_f32_e32 v6, v6, v225
	v_mul_f32_e32 v7, v7, v225
	v_mul_f32_e32 v8, v8, v225
	v_mul_f32_e32 v9, v9, v225
	v_mul_f32_e32 v10, v10, v225
	v_mul_f32_e32 v11, v11, v225
	v_mul_f32_e32 v12, v12, v225
	v_mul_f32_e32 v13, v13, v225
	v_mul_f32_e32 v14, v14, v225
	v_mul_f32_e32 v15, v15, v225
	v_mul_f32_e32 v16, v16, v225
	v_mul_f32_e32 v17, v17, v225
	v_mul_f32_e32 v18, v18, v225
	v_mul_f32_e32 v19, v19, v225
	v_mul_f32_e32 v20, v20, v225
	v_mul_f32_e32 v21, v21, v225
	v_mul_f32_e32 v22, v22, v225
	v_mul_f32_e32 v23, v23, v225
	v_mul_f32_e32 v24, v24, v225
	v_mul_f32_e32 v25, v25, v225
	v_mul_f32_e32 v26, v26, v225
	v_mul_f32_e32 v27, v27, v225
	v_mul_f32_e32 v28, v28, v225
	v_mul_f32_e32 v29, v29, v225
	v_mul_f32_e32 v30, v30, v225
	v_mul_f32_e32 v31, v31, v225
	v_mul_f32_e32 v32, v32, v225
	v_mul_f32_e32 v33, v33, v225
	v_mul_f32_e32 v1, v1, v225
	v_xor_b32_e32 v66, 0x80000000, v180
	v_mov_b32_e32 v67, v66
	v_mov_b32_e32 v68, v66
	v_mov_b32_e32 v69, v66
	v_mov_b32_e32 v70, v66
	v_mov_b32_e32 v71, v66
	v_mov_b32_e32 v72, v66
	v_mov_b32_e32 v73, v66
	v_mov_b32_e32 v74, v66
	v_mov_b32_e32 v75, v66
	v_mov_b32_e32 v76, v66
	v_mov_b32_e32 v77, v66
	v_mov_b32_e32 v78, v66
	v_mov_b32_e32 v79, v66
	v_mov_b32_e32 v80, v66
	v_mov_b32_e32 v81, v66
	s_nop 3
	s_branch .Lmla_p1_go
